# v27 + GEMM K-loops: the 16 LDS-DMA loads per iteration use the saddr form (SGPR base + 32-bit lane offset, M0 compensated where offset:128 is used) instead of a v_lshl_add_u64 each
# speedup vs baseline: 1.0110x; 1.0067x over previous
.LBB0_161:
	s_ashr_i32 s23, s22, 31
	s_lshl_b64 s[8:9], s[22:23], 20
	v_readlane_b32 s20, v254, 38
	v_readlane_b32 s21, v254, 39
	s_add_u32 s8, s20, s8
	s_addc_u32 s9, s21, s9
	s_and_b64 s[20:21], s[40:41], exec
	s_cselect_b32 s13, s9, s43
	s_cselect_b32 s20, s8, s42
	s_ashr_i32 s19, s18, 31
	s_lshl_b64 s[28:29], s[18:19], 20
	v_readlane_b32 s30, v254, 22
	v_readlane_b32 s31, v254, 23
	s_add_u32 s28, s30, s28
	s_addc_u32 s29, s31, s29
	s_and_b64 s[30:31], s[40:41], exec
	s_cselect_b32 s19, s29, s45
	s_cselect_b32 s21, s28, s44
	s_add_u32 s42, s42, 0x80080
	s_addc_u32 s43, s43, 0
	s_add_u32 s23, s44, 0x100
	s_addc_u32 s25, s45, 0
	s_mov_b32 s30, -2
	v_readlane_b32 s52, v255, 20
	v_readlane_b32 s53, v255, 21
	v_readlane_b32 s72, v255, 22
	v_readlane_b32 s73, v255, 23
	s_mov_b64 s[74:75], 0x80
	s_add_u32 s31, s42, 0xfff80080
	s_addc_u32 s44, s43, -1
	s_add_i32 s47, 0, 0x10000
	s_cmp_eq_u32 s30, 28
	s_cselect_b32 s49, s13, s44
	s_cselect_b32 s48, s20, s31
	ds_read_b128 v[144:147], v1
	ds_read_b128 v[148:151], v141
	s_cselect_b32 s45, s19, s25
	s_cselect_b32 s44, s21, s23
	s_add_i32 s31, 0, 0x14000
	ds_read_b128 v[152:155], v1 offset:2048
	ds_read_b128 v[156:159], v141 offset:2048
	ds_read_b128 v[160:163], v1 offset:16384
	ds_read_b128 v[164:167], v141 offset:16384
	ds_read_b128 v[168:171], v1 offset:18432
	ds_read_b128 v[172:175], v141 offset:18432
	s_add_i32 m0, s34, 0xc000
	ds_read_b128 v[176:179], v142
	ds_read_b128 v[184:187], v142 offset:2048
	ds_read_b128 v[188:191], v143
	ds_read_b128 v[192:195], v143 offset:2048
	ds_read_b128 v[196:199], v142 offset:4096
	ds_read_b128 v[200:203], v142 offset:6144
	ds_read_b128 v[204:207], v143 offset:4096
	ds_read_b128 v[208:211], v143 offset:6144
	global_load_lds_dwordx4 v138, s[42:43]
	s_add_i32 m0, s34, 0xe000
	s_nop 0
	global_load_lds_dwordx4 v134, s[42:43]
	s_waitcnt vmcnt(8)
	s_waitcnt lgkmcnt(0)
	s_barrier
	s_setprio 1
	s_waitcnt lgkmcnt(0)
	v_mfma_f32_16x16x32_bf16 v[128:131], v[144:147], v[176:179], 0
	v_mfma_f32_16x16x32_bf16 v[124:127], v[152:155], v[176:179], 0
	v_mfma_f32_16x16x32_bf16 v[112:115], v[144:147], v[184:187], 0
	v_mfma_f32_16x16x32_bf16 v[108:111], v[152:155], v[184:187], 0
	v_mfma_f32_16x16x32_bf16 v[96:99], v[144:147], v[196:199], 0
	v_mfma_f32_16x16x32_bf16 v[92:95], v[152:155], v[196:199], 0
	v_mfma_f32_16x16x32_bf16 v[80:83], v[144:147], v[200:203], 0
	v_mfma_f32_16x16x32_bf16 v[76:79], v[152:155], v[200:203], 0
	v_mfma_f32_16x16x32_bf16 v[128:131], v[148:151], v[188:191], v[128:131]
	v_mfma_f32_16x16x32_bf16 v[124:127], v[156:159], v[188:191], v[124:127]
	v_mfma_f32_16x16x32_bf16 v[112:115], v[148:151], v[192:195], v[112:115]
	v_mfma_f32_16x16x32_bf16 v[108:111], v[156:159], v[192:195], v[108:111]
	v_mfma_f32_16x16x32_bf16 v[96:99], v[148:151], v[204:207], v[96:99]
	v_mfma_f32_16x16x32_bf16 v[92:95], v[156:159], v[204:207], v[92:95]
	v_mfma_f32_16x16x32_bf16 v[80:83], v[148:151], v[208:211], v[80:83]
	v_mfma_f32_16x16x32_bf16 v[76:79], v[156:159], v[208:211], v[76:79]
	s_setprio 0
	s_setprio 1
	v_mfma_f32_16x16x32_bf16 v[120:123], v[160:163], v[176:179], 0
	v_mfma_f32_16x16x32_bf16 v[116:119], v[168:171], v[176:179], 0
	v_mfma_f32_16x16x32_bf16 v[104:107], v[160:163], v[184:187], 0
	v_mfma_f32_16x16x32_bf16 v[100:103], v[168:171], v[184:187], 0
	v_mfma_f32_16x16x32_bf16 v[88:91], v[160:163], v[196:199], 0
	v_mfma_f32_16x16x32_bf16 v[84:87], v[168:171], v[196:199], 0
	v_mfma_f32_16x16x32_bf16 v[72:75], v[160:163], v[200:203], 0
	v_mfma_f32_16x16x32_bf16 v[68:71], v[168:171], v[200:203], 0
	v_mfma_f32_16x16x32_bf16 v[120:123], v[164:167], v[188:191], v[120:123]
	v_mfma_f32_16x16x32_bf16 v[116:119], v[172:175], v[188:191], v[116:119]
	v_mfma_f32_16x16x32_bf16 v[104:107], v[164:167], v[192:195], v[104:107]
	v_mfma_f32_16x16x32_bf16 v[100:103], v[172:175], v[192:195], v[100:103]
	v_mfma_f32_16x16x32_bf16 v[88:91], v[164:167], v[204:207], v[88:91]
	v_mfma_f32_16x16x32_bf16 v[84:87], v[172:175], v[204:207], v[84:87]
	v_mfma_f32_16x16x32_bf16 v[72:75], v[164:167], v[208:211], v[72:75]
	v_mfma_f32_16x16x32_bf16 v[68:71], v[172:175], v[208:211], v[68:71]
	s_setprio 0
	s_barrier
	s_add_i32 s47, s47, s33
	s_mov_b32 m0, s47
	ds_read_b128 v[176:179], v142 offset:16384
	ds_read_b128 v[184:187], v142 offset:18432
	ds_read_b128 v[188:191], v143 offset:16384
	ds_read_b128 v[192:195], v143 offset:18432
	ds_read_b128 v[196:199], v142 offset:20480
	ds_read_b128 v[200:203], v142 offset:22528
	ds_read_b128 v[204:207], v143 offset:20480
	ds_read_b128 v[208:211], v143 offset:22528
	global_load_lds_dwordx4 v136, s[44:45]
	s_add_i32 m0, s47, 0x2000
	s_add_u32 s50, s44, 0x80000
	s_addc_u32 s51, s45, 0
	s_add_i32 s31, s31, s33
	global_load_lds_dwordx4 v132, s[44:45]
	s_mov_b32 m0, s31
	s_nop 0
	global_load_lds_dwordx4 v136, s[50:51]
	s_add_i32 m0, s31, 0x2000
	s_nop 0
	global_load_lds_dwordx4 v132, s[50:51]
	s_mov_b32 m0, s34
	s_nop 0
	global_load_lds_dwordx4 v138, s[48:49]
	s_mov_b32 m0, s35
	s_nop 0
	global_load_lds_dwordx4 v134, s[48:49]
	s_waitcnt vmcnt(8)
	s_waitcnt lgkmcnt(0)
	s_barrier
	s_setprio 1
	s_waitcnt lgkmcnt(0)
	v_mfma_f32_16x16x32_bf16 v[64:67], v[144:147], v[176:179], 0
	v_mfma_f32_16x16x32_bf16 v[60:63], v[152:155], v[176:179], 0
	v_mfma_f32_16x16x32_bf16 v[48:51], v[144:147], v[184:187], 0
	v_mfma_f32_16x16x32_bf16 v[44:47], v[152:155], v[184:187], 0
	v_mfma_f32_16x16x32_bf16 v[30:33], v[144:147], v[196:199], 0
	v_mfma_f32_16x16x32_bf16 v[26:29], v[152:155], v[196:199], 0
	v_mfma_f32_16x16x32_bf16 v[14:17], v[144:147], v[200:203], 0
	v_mfma_f32_16x16x32_bf16 v[10:13], v[152:155], v[200:203], 0
	v_mfma_f32_16x16x32_bf16 v[64:67], v[148:151], v[188:191], v[64:67]
	v_mfma_f32_16x16x32_bf16 v[60:63], v[156:159], v[188:191], v[60:63]
	v_mfma_f32_16x16x32_bf16 v[48:51], v[148:151], v[192:195], v[48:51]
	v_mfma_f32_16x16x32_bf16 v[44:47], v[156:159], v[192:195], v[44:47]
	v_mfma_f32_16x16x32_bf16 v[30:33], v[148:151], v[204:207], v[30:33]
	v_mfma_f32_16x16x32_bf16 v[26:29], v[156:159], v[204:207], v[26:29]
	v_mfma_f32_16x16x32_bf16 v[14:17], v[148:151], v[208:211], v[14:17]
	v_mfma_f32_16x16x32_bf16 v[10:13], v[156:159], v[208:211], v[10:13]
	s_setprio 0
	s_setprio 1
	v_mfma_f32_16x16x32_bf16 v[56:59], v[160:163], v[176:179], 0
	v_mfma_f32_16x16x32_bf16 v[52:55], v[168:171], v[176:179], 0
	v_mfma_f32_16x16x32_bf16 v[40:43], v[160:163], v[184:187], 0
	v_mfma_f32_16x16x32_bf16 v[36:39], v[168:171], v[184:187], 0
	v_mfma_f32_16x16x32_bf16 v[22:25], v[160:163], v[196:199], 0
	v_mfma_f32_16x16x32_bf16 v[18:21], v[168:171], v[196:199], 0
	v_mfma_f32_16x16x32_bf16 v[6:9], v[160:163], v[200:203], 0
	v_mfma_f32_16x16x32_bf16 v[2:5], v[168:171], v[200:203], 0
	v_mfma_f32_16x16x32_bf16 v[56:59], v[164:167], v[188:191], v[56:59]
	v_mfma_f32_16x16x32_bf16 v[52:55], v[172:175], v[188:191], v[52:55]
	v_mfma_f32_16x16x32_bf16 v[40:43], v[164:167], v[192:195], v[40:43]
	v_mfma_f32_16x16x32_bf16 v[36:39], v[172:175], v[192:195], v[36:39]
	v_mfma_f32_16x16x32_bf16 v[22:25], v[164:167], v[204:207], v[22:25]
	v_mfma_f32_16x16x32_bf16 v[18:21], v[172:175], v[204:207], v[18:21]
	v_mfma_f32_16x16x32_bf16 v[6:9], v[164:167], v[208:211], v[6:9]
	v_mfma_f32_16x16x32_bf16 v[2:5], v[172:175], v[208:211], v[2:5]
	s_setprio 0
	s_barrier
	s_add_i32 s31, 0, 0x18000
	ds_read_b128 v[144:147], v1 offset:32768
	ds_read_b128 v[148:151], v141 offset:32768
	s_add_i32 s47, 0, 0x1c000
	ds_read_b128 v[152:155], v1 offset:34816
	ds_read_b128 v[156:159], v141 offset:34816
	ds_read_b128 v[160:163], v1 offset:49152
	ds_read_b128 v[164:167], v141 offset:49152
	ds_read_b128 v[168:171], v1 offset:51200
	ds_read_b128 v[172:175], v141 offset:51200
	s_mov_b64 s[100:101], s[48:49]
	s_add_u32 s48, s48, 0x80000
	s_addc_u32 s49, s49, 0
	s_mov_b32 m0, s54
	ds_read_b128 v[176:179], v142 offset:32768
	ds_read_b128 v[184:187], v142 offset:34816
	ds_read_b128 v[188:191], v143 offset:32768
	ds_read_b128 v[192:195], v143 offset:34816
	ds_read_b128 v[196:199], v142 offset:36864
	ds_read_b128 v[200:203], v142 offset:38912
	ds_read_b128 v[204:207], v143 offset:36864
	ds_read_b128 v[208:211], v143 offset:38912
	global_load_lds_dwordx4 v138, s[48:49]
	s_mov_b32 m0, s55
	s_nop 0
	global_load_lds_dwordx4 v134, s[48:49]
	s_waitcnt vmcnt(8)
	s_waitcnt lgkmcnt(0)
	s_barrier
	s_setprio 1
	s_waitcnt lgkmcnt(0)
	v_mfma_f32_16x16x32_bf16 v[128:131], v[144:147], v[176:179], v[128:131]
	v_mfma_f32_16x16x32_bf16 v[124:127], v[152:155], v[176:179], v[124:127]
	v_mfma_f32_16x16x32_bf16 v[112:115], v[144:147], v[184:187], v[112:115]
	v_mfma_f32_16x16x32_bf16 v[108:111], v[152:155], v[184:187], v[108:111]
	v_mfma_f32_16x16x32_bf16 v[96:99], v[144:147], v[196:199], v[96:99]
	v_mfma_f32_16x16x32_bf16 v[92:95], v[152:155], v[196:199], v[92:95]
	v_mfma_f32_16x16x32_bf16 v[80:83], v[144:147], v[200:203], v[80:83]
	v_mfma_f32_16x16x32_bf16 v[76:79], v[152:155], v[200:203], v[76:79]
	v_mfma_f32_16x16x32_bf16 v[128:131], v[148:151], v[188:191], v[128:131]
	v_mfma_f32_16x16x32_bf16 v[124:127], v[156:159], v[188:191], v[124:127]
	v_mfma_f32_16x16x32_bf16 v[112:115], v[148:151], v[192:195], v[112:115]
	v_mfma_f32_16x16x32_bf16 v[108:111], v[156:159], v[192:195], v[108:111]
	v_mfma_f32_16x16x32_bf16 v[96:99], v[148:151], v[204:207], v[96:99]
	v_mfma_f32_16x16x32_bf16 v[92:95], v[156:159], v[204:207], v[92:95]
	v_mfma_f32_16x16x32_bf16 v[80:83], v[148:151], v[208:211], v[80:83]
	v_mfma_f32_16x16x32_bf16 v[76:79], v[156:159], v[208:211], v[76:79]
	s_setprio 0
	s_setprio 1
	v_mfma_f32_16x16x32_bf16 v[120:123], v[160:163], v[176:179], v[120:123]
	v_mfma_f32_16x16x32_bf16 v[116:119], v[168:171], v[176:179], v[116:119]
	v_mfma_f32_16x16x32_bf16 v[104:107], v[160:163], v[184:187], v[104:107]
	v_mfma_f32_16x16x32_bf16 v[100:103], v[168:171], v[184:187], v[100:103]
	v_mfma_f32_16x16x32_bf16 v[88:91], v[160:163], v[196:199], v[88:91]
	v_mfma_f32_16x16x32_bf16 v[84:87], v[168:171], v[196:199], v[84:87]
	v_mfma_f32_16x16x32_bf16 v[72:75], v[160:163], v[200:203], v[72:75]
	v_mfma_f32_16x16x32_bf16 v[68:71], v[168:171], v[200:203], v[68:71]
	v_mfma_f32_16x16x32_bf16 v[120:123], v[164:167], v[188:191], v[120:123]
	v_mfma_f32_16x16x32_bf16 v[116:119], v[172:175], v[188:191], v[116:119]
	v_mfma_f32_16x16x32_bf16 v[104:107], v[164:167], v[192:195], v[104:107]
	v_mfma_f32_16x16x32_bf16 v[100:103], v[172:175], v[192:195], v[100:103]
	v_mfma_f32_16x16x32_bf16 v[88:91], v[164:167], v[204:207], v[88:91]
	v_mfma_f32_16x16x32_bf16 v[84:87], v[172:175], v[204:207], v[84:87]
	v_mfma_f32_16x16x32_bf16 v[72:75], v[164:167], v[208:211], v[72:75]
	v_mfma_f32_16x16x32_bf16 v[68:71], v[172:175], v[208:211], v[68:71]
	s_setprio 0
	s_barrier
	s_add_i32 s31, s31, s33
	s_add_i32 m0, s31, 0xffffff80
	ds_read_b128 v[176:179], v142 offset:49152
	ds_read_b128 v[184:187], v142 offset:51200
	ds_read_b128 v[188:191], v143 offset:49152
	ds_read_b128 v[192:195], v143 offset:51200
	ds_read_b128 v[196:199], v142 offset:53248
	ds_read_b128 v[200:203], v142 offset:55296
	ds_read_b128 v[204:207], v143 offset:53248
	ds_read_b128 v[208:211], v143 offset:55296
	global_load_lds_dwordx4 v136, s[44:45] offset:128
	s_add_i32 m0, s31, 0x1f80
	s_mov_b64 s[98:99], s[44:45]
	s_add_u32 s44, s44, 0x80080
	s_addc_u32 s45, s45, 0
	s_add_i32 s31, s47, s33
	global_load_lds_dwordx4 v132, s[98:99] offset:128
	s_mov_b32 m0, s31
	s_nop 0
	global_load_lds_dwordx4 v136, s[44:45]
	s_add_i32 m0, s31, 0x2000
	s_nop 0
	global_load_lds_dwordx4 v132, s[44:45]
	s_add_i32 m0, s56, 0xffffff80
	s_nop 0
	global_load_lds_dwordx4 v138, s[100:101] offset:128
	s_add_i32 m0, s57, 0xffffff80
	s_nop 0
	global_load_lds_dwordx4 v134, s[100:101] offset:128
	s_waitcnt vmcnt(8)
	s_waitcnt lgkmcnt(0)
	s_barrier
	s_setprio 1
	s_waitcnt lgkmcnt(0)
	v_mfma_f32_16x16x32_bf16 v[64:67], v[144:147], v[176:179], v[64:67]
	v_mfma_f32_16x16x32_bf16 v[60:63], v[152:155], v[176:179], v[60:63]
	v_mfma_f32_16x16x32_bf16 v[48:51], v[144:147], v[184:187], v[48:51]
	v_mfma_f32_16x16x32_bf16 v[44:47], v[152:155], v[184:187], v[44:47]
	v_mfma_f32_16x16x32_bf16 v[30:33], v[144:147], v[196:199], v[30:33]
	v_mfma_f32_16x16x32_bf16 v[26:29], v[152:155], v[196:199], v[26:29]
	v_mfma_f32_16x16x32_bf16 v[14:17], v[144:147], v[200:203], v[14:17]
	v_mfma_f32_16x16x32_bf16 v[10:13], v[152:155], v[200:203], v[10:13]
	v_mfma_f32_16x16x32_bf16 v[64:67], v[148:151], v[188:191], v[64:67]
	v_mfma_f32_16x16x32_bf16 v[60:63], v[156:159], v[188:191], v[60:63]
	v_mfma_f32_16x16x32_bf16 v[48:51], v[148:151], v[192:195], v[48:51]
	v_mfma_f32_16x16x32_bf16 v[44:47], v[156:159], v[192:195], v[44:47]
	v_mfma_f32_16x16x32_bf16 v[30:33], v[148:151], v[204:207], v[30:33]
	v_mfma_f32_16x16x32_bf16 v[26:29], v[156:159], v[204:207], v[26:29]
	v_mfma_f32_16x16x32_bf16 v[14:17], v[148:151], v[208:211], v[14:17]
	v_mfma_f32_16x16x32_bf16 v[10:13], v[156:159], v[208:211], v[10:13]
	s_setprio 0
	s_setprio 1
	v_mfma_f32_16x16x32_bf16 v[56:59], v[160:163], v[176:179], v[56:59]
	v_mfma_f32_16x16x32_bf16 v[52:55], v[168:171], v[176:179], v[52:55]
	v_mfma_f32_16x16x32_bf16 v[40:43], v[160:163], v[184:187], v[40:43]
	v_mfma_f32_16x16x32_bf16 v[36:39], v[168:171], v[184:187], v[36:39]
	v_mfma_f32_16x16x32_bf16 v[22:25], v[160:163], v[196:199], v[22:25]
	v_mfma_f32_16x16x32_bf16 v[18:21], v[168:171], v[196:199], v[18:21]
	v_mfma_f32_16x16x32_bf16 v[6:9], v[160:163], v[200:203], v[6:9]
	v_mfma_f32_16x16x32_bf16 v[2:5], v[168:171], v[200:203], v[2:5]
	v_mfma_f32_16x16x32_bf16 v[56:59], v[164:167], v[188:191], v[56:59]
	v_mfma_f32_16x16x32_bf16 v[52:55], v[172:175], v[188:191], v[52:55]
	v_mfma_f32_16x16x32_bf16 v[40:43], v[164:167], v[192:195], v[40:43]
	v_mfma_f32_16x16x32_bf16 v[36:39], v[172:175], v[192:195], v[36:39]
	v_mfma_f32_16x16x32_bf16 v[22:25], v[164:167], v[204:207], v[22:25]
	v_mfma_f32_16x16x32_bf16 v[18:21], v[172:175], v[204:207], v[18:21]
	v_mfma_f32_16x16x32_bf16 v[6:9], v[164:167], v[208:211], v[6:9]
	v_mfma_f32_16x16x32_bf16 v[2:5], v[172:175], v[208:211], v[2:5]
	s_setprio 0
	s_barrier
	s_add_i32 s30, s30, 2
	s_add_u32 s42, s42, 0x100
	s_addc_u32 s43, s43, 0
	s_add_u32 s23, s23, 0x100
	s_addc_u32 s25, s25, 0
	s_cmp_gt_u32 s30, 29
	s_cbranch_scc1 .Lpeel_done_P1
.LBB0_162:
	s_add_u32 s31, s42, 0xfff80080
	s_addc_u32 s44, s43, -1
	s_add_i32 s47, 0, 0x10000
	s_cmp_eq_u32 s30, 28
	s_cselect_b32 s49, s13, s44
	s_cselect_b32 s48, s20, s31
	ds_read_b128 v[144:147], v1
	ds_read_b128 v[148:151], v141
	s_cselect_b32 s45, s19, s25
	s_cselect_b32 s44, s21, s23
	s_add_i32 s31, 0, 0x14000
	ds_read_b128 v[152:155], v1 offset:2048
	ds_read_b128 v[156:159], v141 offset:2048
	ds_read_b128 v[160:163], v1 offset:16384
	ds_read_b128 v[164:167], v141 offset:16384
	ds_read_b128 v[168:171], v1 offset:18432
	ds_read_b128 v[172:175], v141 offset:18432
	s_add_i32 m0, s34, 0xc000
	ds_read_b128 v[176:179], v142
	ds_read_b128 v[184:187], v142 offset:2048
	ds_read_b128 v[188:191], v143
	ds_read_b128 v[192:195], v143 offset:2048
	ds_read_b128 v[196:199], v142 offset:4096
	ds_read_b128 v[200:203], v142 offset:6144
	ds_read_b128 v[204:207], v143 offset:4096
	ds_read_b128 v[208:211], v143 offset:6144
	global_load_lds_dwordx4 v138, s[42:43]
	s_add_i32 m0, s34, 0xe000
	s_nop 0
	global_load_lds_dwordx4 v134, s[42:43]
	s_waitcnt vmcnt(8)
	s_waitcnt lgkmcnt(0)
	s_barrier
	s_setprio 1
	s_waitcnt lgkmcnt(0)
	v_mfma_f32_16x16x32_bf16 v[128:131], v[144:147], v[176:179], v[128:131]
	v_mfma_f32_16x16x32_bf16 v[124:127], v[152:155], v[176:179], v[124:127]
	v_mfma_f32_16x16x32_bf16 v[112:115], v[144:147], v[184:187], v[112:115]
	v_mfma_f32_16x16x32_bf16 v[108:111], v[152:155], v[184:187], v[108:111]
	v_mfma_f32_16x16x32_bf16 v[96:99], v[144:147], v[196:199], v[96:99]
	v_mfma_f32_16x16x32_bf16 v[92:95], v[152:155], v[196:199], v[92:95]
	v_mfma_f32_16x16x32_bf16 v[80:83], v[144:147], v[200:203], v[80:83]
	v_mfma_f32_16x16x32_bf16 v[76:79], v[152:155], v[200:203], v[76:79]
	v_mfma_f32_16x16x32_bf16 v[128:131], v[148:151], v[188:191], v[128:131]
	v_mfma_f32_16x16x32_bf16 v[124:127], v[156:159], v[188:191], v[124:127]
	v_mfma_f32_16x16x32_bf16 v[112:115], v[148:151], v[192:195], v[112:115]
	v_mfma_f32_16x16x32_bf16 v[108:111], v[156:159], v[192:195], v[108:111]
	v_mfma_f32_16x16x32_bf16 v[96:99], v[148:151], v[204:207], v[96:99]
	v_mfma_f32_16x16x32_bf16 v[92:95], v[156:159], v[204:207], v[92:95]
	v_mfma_f32_16x16x32_bf16 v[80:83], v[148:151], v[208:211], v[80:83]
	v_mfma_f32_16x16x32_bf16 v[76:79], v[156:159], v[208:211], v[76:79]
	s_setprio 0
	s_setprio 1
	v_mfma_f32_16x16x32_bf16 v[120:123], v[160:163], v[176:179], v[120:123]
	v_mfma_f32_16x16x32_bf16 v[116:119], v[168:171], v[176:179], v[116:119]
	v_mfma_f32_16x16x32_bf16 v[104:107], v[160:163], v[184:187], v[104:107]
	v_mfma_f32_16x16x32_bf16 v[100:103], v[168:171], v[184:187], v[100:103]
	v_mfma_f32_16x16x32_bf16 v[88:91], v[160:163], v[196:199], v[88:91]
	v_mfma_f32_16x16x32_bf16 v[84:87], v[168:171], v[196:199], v[84:87]
	v_mfma_f32_16x16x32_bf16 v[72:75], v[160:163], v[200:203], v[72:75]
	v_mfma_f32_16x16x32_bf16 v[68:71], v[168:171], v[200:203], v[68:71]
	v_mfma_f32_16x16x32_bf16 v[120:123], v[164:167], v[188:191], v[120:123]
	v_mfma_f32_16x16x32_bf16 v[116:119], v[172:175], v[188:191], v[116:119]
	v_mfma_f32_16x16x32_bf16 v[104:107], v[164:167], v[192:195], v[104:107]
	v_mfma_f32_16x16x32_bf16 v[100:103], v[172:175], v[192:195], v[100:103]
	v_mfma_f32_16x16x32_bf16 v[88:91], v[164:167], v[204:207], v[88:91]
	v_mfma_f32_16x16x32_bf16 v[84:87], v[172:175], v[204:207], v[84:87]
	v_mfma_f32_16x16x32_bf16 v[72:75], v[164:167], v[208:211], v[72:75]
	v_mfma_f32_16x16x32_bf16 v[68:71], v[172:175], v[208:211], v[68:71]
	s_setprio 0
	s_barrier
	s_add_i32 s47, s47, s33
	s_mov_b32 m0, s47
	ds_read_b128 v[176:179], v142 offset:16384
	ds_read_b128 v[184:187], v142 offset:18432
	ds_read_b128 v[188:191], v143 offset:16384
	ds_read_b128 v[192:195], v143 offset:18432
	ds_read_b128 v[196:199], v142 offset:20480
	ds_read_b128 v[200:203], v142 offset:22528
	ds_read_b128 v[204:207], v143 offset:20480
	ds_read_b128 v[208:211], v143 offset:22528
	global_load_lds_dwordx4 v136, s[44:45]
	s_add_i32 m0, s47, 0x2000
	s_add_u32 s50, s44, 0x80000
	s_addc_u32 s51, s45, 0
	s_add_i32 s31, s31, s33
	global_load_lds_dwordx4 v132, s[44:45]
	s_mov_b32 m0, s31
	s_nop 0
	global_load_lds_dwordx4 v136, s[50:51]
	s_add_i32 m0, s31, 0x2000
	s_nop 0
	global_load_lds_dwordx4 v132, s[50:51]
	s_mov_b32 m0, s34
	s_nop 0
	global_load_lds_dwordx4 v138, s[48:49]
	s_mov_b32 m0, s35
	s_nop 0
	global_load_lds_dwordx4 v134, s[48:49]
	s_waitcnt vmcnt(8)
	s_waitcnt lgkmcnt(0)
	s_barrier
	s_setprio 1
	s_waitcnt lgkmcnt(0)
	v_mfma_f32_16x16x32_bf16 v[64:67], v[144:147], v[176:179], v[64:67]
	v_mfma_f32_16x16x32_bf16 v[60:63], v[152:155], v[176:179], v[60:63]
	v_mfma_f32_16x16x32_bf16 v[48:51], v[144:147], v[184:187], v[48:51]
	v_mfma_f32_16x16x32_bf16 v[44:47], v[152:155], v[184:187], v[44:47]
	v_mfma_f32_16x16x32_bf16 v[30:33], v[144:147], v[196:199], v[30:33]
	v_mfma_f32_16x16x32_bf16 v[26:29], v[152:155], v[196:199], v[26:29]
	v_mfma_f32_16x16x32_bf16 v[14:17], v[144:147], v[200:203], v[14:17]
	v_mfma_f32_16x16x32_bf16 v[10:13], v[152:155], v[200:203], v[10:13]
	v_mfma_f32_16x16x32_bf16 v[64:67], v[148:151], v[188:191], v[64:67]
	v_mfma_f32_16x16x32_bf16 v[60:63], v[156:159], v[188:191], v[60:63]
	v_mfma_f32_16x16x32_bf16 v[48:51], v[148:151], v[192:195], v[48:51]
	v_mfma_f32_16x16x32_bf16 v[44:47], v[156:159], v[192:195], v[44:47]
	v_mfma_f32_16x16x32_bf16 v[30:33], v[148:151], v[204:207], v[30:33]
	v_mfma_f32_16x16x32_bf16 v[26:29], v[156:159], v[204:207], v[26:29]
	v_mfma_f32_16x16x32_bf16 v[14:17], v[148:151], v[208:211], v[14:17]
	v_mfma_f32_16x16x32_bf16 v[10:13], v[156:159], v[208:211], v[10:13]
	s_setprio 0
	s_setprio 1
	v_mfma_f32_16x16x32_bf16 v[56:59], v[160:163], v[176:179], v[56:59]
	v_mfma_f32_16x16x32_bf16 v[52:55], v[168:171], v[176:179], v[52:55]
	v_mfma_f32_16x16x32_bf16 v[40:43], v[160:163], v[184:187], v[40:43]
	v_mfma_f32_16x16x32_bf16 v[36:39], v[168:171], v[184:187], v[36:39]
	v_mfma_f32_16x16x32_bf16 v[22:25], v[160:163], v[196:199], v[22:25]
	v_mfma_f32_16x16x32_bf16 v[18:21], v[168:171], v[196:199], v[18:21]
	v_mfma_f32_16x16x32_bf16 v[6:9], v[160:163], v[200:203], v[6:9]
	v_mfma_f32_16x16x32_bf16 v[2:5], v[168:171], v[200:203], v[2:5]
	v_mfma_f32_16x16x32_bf16 v[56:59], v[164:167], v[188:191], v[56:59]
	v_mfma_f32_16x16x32_bf16 v[52:55], v[172:175], v[188:191], v[52:55]
	v_mfma_f32_16x16x32_bf16 v[40:43], v[164:167], v[192:195], v[40:43]
	v_mfma_f32_16x16x32_bf16 v[36:39], v[172:175], v[192:195], v[36:39]
	v_mfma_f32_16x16x32_bf16 v[22:25], v[164:167], v[204:207], v[22:25]
	v_mfma_f32_16x16x32_bf16 v[18:21], v[172:175], v[204:207], v[18:21]
	v_mfma_f32_16x16x32_bf16 v[6:9], v[164:167], v[208:211], v[6:9]
	v_mfma_f32_16x16x32_bf16 v[2:5], v[172:175], v[208:211], v[2:5]
	s_setprio 0
	s_barrier
	s_add_i32 s31, 0, 0x18000
	ds_read_b128 v[144:147], v1 offset:32768
	ds_read_b128 v[148:151], v141 offset:32768
	s_add_i32 s47, 0, 0x1c000
	ds_read_b128 v[152:155], v1 offset:34816
	ds_read_b128 v[156:159], v141 offset:34816
	ds_read_b128 v[160:163], v1 offset:49152
	ds_read_b128 v[164:167], v141 offset:49152
	ds_read_b128 v[168:171], v1 offset:51200
	ds_read_b128 v[172:175], v141 offset:51200
	s_mov_b64 s[100:101], s[48:49]
	s_add_u32 s48, s48, 0x80000
	s_addc_u32 s49, s49, 0
	s_mov_b32 m0, s54
	ds_read_b128 v[176:179], v142 offset:32768
	ds_read_b128 v[184:187], v142 offset:34816
	ds_read_b128 v[188:191], v143 offset:32768
	ds_read_b128 v[192:195], v143 offset:34816
	ds_read_b128 v[196:199], v142 offset:36864
	ds_read_b128 v[200:203], v142 offset:38912
	ds_read_b128 v[204:207], v143 offset:36864
	ds_read_b128 v[208:211], v143 offset:38912
	global_load_lds_dwordx4 v138, s[48:49]
	s_mov_b32 m0, s55
	s_nop 0
	global_load_lds_dwordx4 v134, s[48:49]
	s_waitcnt vmcnt(8)
	s_waitcnt lgkmcnt(0)
	s_barrier
	s_setprio 1
	s_waitcnt lgkmcnt(0)
	v_mfma_f32_16x16x32_bf16 v[128:131], v[144:147], v[176:179], v[128:131]
	v_mfma_f32_16x16x32_bf16 v[124:127], v[152:155], v[176:179], v[124:127]
	v_mfma_f32_16x16x32_bf16 v[112:115], v[144:147], v[184:187], v[112:115]
	v_mfma_f32_16x16x32_bf16 v[108:111], v[152:155], v[184:187], v[108:111]
	v_mfma_f32_16x16x32_bf16 v[96:99], v[144:147], v[196:199], v[96:99]
	v_mfma_f32_16x16x32_bf16 v[92:95], v[152:155], v[196:199], v[92:95]
	v_mfma_f32_16x16x32_bf16 v[80:83], v[144:147], v[200:203], v[80:83]
	v_mfma_f32_16x16x32_bf16 v[76:79], v[152:155], v[200:203], v[76:79]
	v_mfma_f32_16x16x32_bf16 v[128:131], v[148:151], v[188:191], v[128:131]
	v_mfma_f32_16x16x32_bf16 v[124:127], v[156:159], v[188:191], v[124:127]
	v_mfma_f32_16x16x32_bf16 v[112:115], v[148:151], v[192:195], v[112:115]
	v_mfma_f32_16x16x32_bf16 v[108:111], v[156:159], v[192:195], v[108:111]
	v_mfma_f32_16x16x32_bf16 v[96:99], v[148:151], v[204:207], v[96:99]
	v_mfma_f32_16x16x32_bf16 v[92:95], v[156:159], v[204:207], v[92:95]
	v_mfma_f32_16x16x32_bf16 v[80:83], v[148:151], v[208:211], v[80:83]
	v_mfma_f32_16x16x32_bf16 v[76:79], v[156:159], v[208:211], v[76:79]
	s_setprio 0
	s_setprio 1
	v_mfma_f32_16x16x32_bf16 v[120:123], v[160:163], v[176:179], v[120:123]
	v_mfma_f32_16x16x32_bf16 v[116:119], v[168:171], v[176:179], v[116:119]
	v_mfma_f32_16x16x32_bf16 v[104:107], v[160:163], v[184:187], v[104:107]
	v_mfma_f32_16x16x32_bf16 v[100:103], v[168:171], v[184:187], v[100:103]
	v_mfma_f32_16x16x32_bf16 v[88:91], v[160:163], v[196:199], v[88:91]
	v_mfma_f32_16x16x32_bf16 v[84:87], v[168:171], v[196:199], v[84:87]
	v_mfma_f32_16x16x32_bf16 v[72:75], v[160:163], v[200:203], v[72:75]
	v_mfma_f32_16x16x32_bf16 v[68:71], v[168:171], v[200:203], v[68:71]
	v_mfma_f32_16x16x32_bf16 v[120:123], v[164:167], v[188:191], v[120:123]
	v_mfma_f32_16x16x32_bf16 v[116:119], v[172:175], v[188:191], v[116:119]
	v_mfma_f32_16x16x32_bf16 v[104:107], v[164:167], v[192:195], v[104:107]
	v_mfma_f32_16x16x32_bf16 v[100:103], v[172:175], v[192:195], v[100:103]
	v_mfma_f32_16x16x32_bf16 v[88:91], v[164:167], v[204:207], v[88:91]
	v_mfma_f32_16x16x32_bf16 v[84:87], v[172:175], v[204:207], v[84:87]
	v_mfma_f32_16x16x32_bf16 v[72:75], v[164:167], v[208:211], v[72:75]
	v_mfma_f32_16x16x32_bf16 v[68:71], v[172:175], v[208:211], v[68:71]
	s_setprio 0
	s_barrier
	s_add_i32 s31, s31, s33
	s_add_i32 m0, s31, 0xffffff80
	ds_read_b128 v[176:179], v142 offset:49152
	ds_read_b128 v[184:187], v142 offset:51200
	ds_read_b128 v[188:191], v143 offset:49152
	ds_read_b128 v[192:195], v143 offset:51200
	ds_read_b128 v[196:199], v142 offset:53248
	ds_read_b128 v[200:203], v142 offset:55296
	ds_read_b128 v[204:207], v143 offset:53248
	ds_read_b128 v[208:211], v143 offset:55296
	global_load_lds_dwordx4 v136, s[44:45] offset:128
	s_add_i32 m0, s31, 0x1f80
	s_mov_b64 s[98:99], s[44:45]
	s_add_u32 s44, s44, 0x80080
	s_addc_u32 s45, s45, 0
	s_add_i32 s31, s47, s33
	global_load_lds_dwordx4 v132, s[98:99] offset:128
	s_mov_b32 m0, s31
	s_nop 0
	global_load_lds_dwordx4 v136, s[44:45]
	s_add_i32 m0, s31, 0x2000
	s_nop 0
	global_load_lds_dwordx4 v132, s[44:45]
	s_add_i32 m0, s56, 0xffffff80
	s_nop 0
	global_load_lds_dwordx4 v138, s[100:101] offset:128
	s_add_i32 m0, s57, 0xffffff80
	s_nop 0
	global_load_lds_dwordx4 v134, s[100:101] offset:128
	s_waitcnt vmcnt(8)
	s_waitcnt lgkmcnt(0)
	s_barrier
	s_setprio 1
	s_waitcnt lgkmcnt(0)
	v_mfma_f32_16x16x32_bf16 v[64:67], v[144:147], v[176:179], v[64:67]
	v_mfma_f32_16x16x32_bf16 v[60:63], v[152:155], v[176:179], v[60:63]
	v_mfma_f32_16x16x32_bf16 v[48:51], v[144:147], v[184:187], v[48:51]
	v_mfma_f32_16x16x32_bf16 v[44:47], v[152:155], v[184:187], v[44:47]
	v_mfma_f32_16x16x32_bf16 v[30:33], v[144:147], v[196:199], v[30:33]
	v_mfma_f32_16x16x32_bf16 v[26:29], v[152:155], v[196:199], v[26:29]
	v_mfma_f32_16x16x32_bf16 v[14:17], v[144:147], v[200:203], v[14:17]
	v_mfma_f32_16x16x32_bf16 v[10:13], v[152:155], v[200:203], v[10:13]
	v_mfma_f32_16x16x32_bf16 v[64:67], v[148:151], v[188:191], v[64:67]
	v_mfma_f32_16x16x32_bf16 v[60:63], v[156:159], v[188:191], v[60:63]
	v_mfma_f32_16x16x32_bf16 v[48:51], v[148:151], v[192:195], v[48:51]
	v_mfma_f32_16x16x32_bf16 v[44:47], v[156:159], v[192:195], v[44:47]
	v_mfma_f32_16x16x32_bf16 v[30:33], v[148:151], v[204:207], v[30:33]
	v_mfma_f32_16x16x32_bf16 v[26:29], v[156:159], v[204:207], v[26:29]
	v_mfma_f32_16x16x32_bf16 v[14:17], v[148:151], v[208:211], v[14:17]
	v_mfma_f32_16x16x32_bf16 v[10:13], v[156:159], v[208:211], v[10:13]
	s_setprio 0
	s_setprio 1
	v_mfma_f32_16x16x32_bf16 v[56:59], v[160:163], v[176:179], v[56:59]
	v_mfma_f32_16x16x32_bf16 v[52:55], v[168:171], v[176:179], v[52:55]
	v_mfma_f32_16x16x32_bf16 v[40:43], v[160:163], v[184:187], v[40:43]
	v_mfma_f32_16x16x32_bf16 v[36:39], v[168:171], v[184:187], v[36:39]
	v_mfma_f32_16x16x32_bf16 v[22:25], v[160:163], v[196:199], v[22:25]
	v_mfma_f32_16x16x32_bf16 v[18:21], v[168:171], v[196:199], v[18:21]
	v_mfma_f32_16x16x32_bf16 v[6:9], v[160:163], v[200:203], v[6:9]
	v_mfma_f32_16x16x32_bf16 v[2:5], v[168:171], v[200:203], v[2:5]
	v_mfma_f32_16x16x32_bf16 v[56:59], v[164:167], v[188:191], v[56:59]
	v_mfma_f32_16x16x32_bf16 v[52:55], v[172:175], v[188:191], v[52:55]
	v_mfma_f32_16x16x32_bf16 v[40:43], v[164:167], v[192:195], v[40:43]
	v_mfma_f32_16x16x32_bf16 v[36:39], v[172:175], v[192:195], v[36:39]
	v_mfma_f32_16x16x32_bf16 v[22:25], v[164:167], v[204:207], v[22:25]
	v_mfma_f32_16x16x32_bf16 v[18:21], v[172:175], v[204:207], v[18:21]
	v_mfma_f32_16x16x32_bf16 v[6:9], v[164:167], v[208:211], v[6:9]
	v_mfma_f32_16x16x32_bf16 v[2:5], v[172:175], v[208:211], v[2:5]
	s_setprio 0
	s_barrier
	s_add_i32 s30, s30, 2
	s_add_u32 s42, s42, 0x100
	s_addc_u32 s43, s43, 0
	s_add_u32 s23, s23, 0x100
	s_addc_u32 s25, s25, 0
	s_cmp_gt_u32 s30, 29
	s_cbranch_scc0 .LBB0_162

.LBB0_907:
	s_and_b32 s9, 1, s12
	s_cmp_gt_i32 s12, 1
	s_cselect_b32 s24, 10, 12
	s_cmp_eq_u32 s9, 1
	s_cselect_b64 s[18:19], -1, 0
	s_and_b64 s[20:21], s[18:19], exec
	s_cselect_b32 s9, s24, 32
	s_add_i32 s20, s9, -2
	s_add_u32 s22, s22, 0x80080
	s_addc_u32 s23, s23, 0
	s_add_u32 s21, s28, 0x100
	s_addc_u32 s24, s29, 0
	s_mov_b32 s25, 0
	s_waitcnt vmcnt(0)
	v_readlane_b32 s43, v255, 20
	v_readlane_b32 s45, v255, 21
	v_readlane_b32 s66, v255, 22
	v_readlane_b32 s67, v255, 23
	s_mov_b64 s[68:69], 0x80
	s_add_i32 s30, s25, 2
	s_add_u32 s28, s22, 0xfff80080
	s_addc_u32 s29, s23, -1
	s_add_i32 s31, 0, 0x10000
	s_cmp_eq_u32 s20, s25
	s_cselect_b32 s41, s47, s29
	s_cselect_b32 s40, s46, s28
	s_cselect_b32 s29, s49, s24
	s_cselect_b32 s28, s48, s21
	s_add_i32 s25, 0, 0x14000
	ds_read_b128 v[132:135], v1
	ds_read_b128 v[136:139], v204
	ds_read_b128 v[140:143], v1 offset:2048
	ds_read_b128 v[144:147], v204 offset:2048
	ds_read_b128 v[148:151], v1 offset:16384
	ds_read_b128 v[152:155], v204 offset:16384
	ds_read_b128 v[156:159], v1 offset:18432
	ds_read_b128 v[160:163], v204 offset:18432
	s_add_i32 m0, s50, 0xc000
	ds_read_b128 v[164:167], v205
	ds_read_b128 v[168:171], v205 offset:2048
	ds_read_b128 v[172:175], v206
	ds_read_b128 v[176:179], v206 offset:2048
	ds_read_b128 v[190:193], v205 offset:4096
	ds_read_b128 v[194:197], v205 offset:6144
	ds_read_b128 v[198:201], v206 offset:4096
	ds_read_b128 v[232:235], v206 offset:6144
	global_load_lds_dwordx4 v188, s[22:23]
	s_add_i32 m0, s50, 0xe000
	s_nop 0
	global_load_lds_dwordx4 v186, s[22:23]
	s_waitcnt vmcnt(8)
	s_waitcnt lgkmcnt(0)
	s_barrier
	s_setprio 1
	s_waitcnt lgkmcnt(0)
	v_mfma_f32_16x16x32_bf16 v[68:71], v[132:135], v[164:167], 0
	v_mfma_f32_16x16x32_bf16 v[72:75], v[140:143], v[164:167], 0
	v_mfma_f32_16x16x32_bf16 v[84:87], v[132:135], v[168:171], 0
	v_mfma_f32_16x16x32_bf16 v[88:91], v[140:143], v[168:171], 0
	v_mfma_f32_16x16x32_bf16 v[100:103], v[132:135], v[190:193], 0
	v_mfma_f32_16x16x32_bf16 v[104:107], v[140:143], v[190:193], 0
	v_mfma_f32_16x16x32_bf16 v[116:119], v[132:135], v[194:197], 0
	v_mfma_f32_16x16x32_bf16 v[120:123], v[140:143], v[194:197], 0
	v_mfma_f32_16x16x32_bf16 v[68:71], v[136:139], v[172:175], v[68:71]
	v_mfma_f32_16x16x32_bf16 v[72:75], v[144:147], v[172:175], v[72:75]
	v_mfma_f32_16x16x32_bf16 v[84:87], v[136:139], v[176:179], v[84:87]
	v_mfma_f32_16x16x32_bf16 v[88:91], v[144:147], v[176:179], v[88:91]
	v_mfma_f32_16x16x32_bf16 v[100:103], v[136:139], v[198:201], v[100:103]
	v_mfma_f32_16x16x32_bf16 v[104:107], v[144:147], v[198:201], v[104:107]
	v_mfma_f32_16x16x32_bf16 v[116:119], v[136:139], v[232:235], v[116:119]
	v_mfma_f32_16x16x32_bf16 v[120:123], v[144:147], v[232:235], v[120:123]
	s_setprio 0
	s_setprio 1
	v_mfma_f32_16x16x32_bf16 v[76:79], v[148:151], v[164:167], 0
	v_mfma_f32_16x16x32_bf16 v[80:83], v[156:159], v[164:167], 0
	v_mfma_f32_16x16x32_bf16 v[92:95], v[148:151], v[168:171], 0
	v_mfma_f32_16x16x32_bf16 v[96:99], v[156:159], v[168:171], 0
	v_mfma_f32_16x16x32_bf16 v[108:111], v[148:151], v[190:193], 0
	v_mfma_f32_16x16x32_bf16 v[112:115], v[156:159], v[190:193], 0
	v_mfma_f32_16x16x32_bf16 v[124:127], v[148:151], v[194:197], 0
	v_mfma_f32_16x16x32_bf16 v[128:131], v[156:159], v[194:197], 0
	v_mfma_f32_16x16x32_bf16 v[76:79], v[152:155], v[172:175], v[76:79]
	v_mfma_f32_16x16x32_bf16 v[80:83], v[160:163], v[172:175], v[80:83]
	v_mfma_f32_16x16x32_bf16 v[92:95], v[152:155], v[176:179], v[92:95]
	v_mfma_f32_16x16x32_bf16 v[96:99], v[160:163], v[176:179], v[96:99]
	v_mfma_f32_16x16x32_bf16 v[108:111], v[152:155], v[198:201], v[108:111]
	v_mfma_f32_16x16x32_bf16 v[112:115], v[160:163], v[198:201], v[112:115]
	v_mfma_f32_16x16x32_bf16 v[124:127], v[152:155], v[232:235], v[124:127]
	v_mfma_f32_16x16x32_bf16 v[128:131], v[160:163], v[232:235], v[128:131]
	s_setprio 0
	s_barrier
	s_add_i32 s31, s31, s33
	s_mov_b32 m0, s31
	ds_read_b128 v[164:167], v205 offset:16384
	ds_read_b128 v[168:171], v205 offset:18432
	ds_read_b128 v[172:175], v206 offset:16384
	ds_read_b128 v[176:179], v206 offset:18432
	ds_read_b128 v[190:193], v205 offset:20480
	ds_read_b128 v[194:197], v205 offset:22528
	ds_read_b128 v[198:201], v206 offset:20480
	ds_read_b128 v[232:235], v206 offset:22528
	global_load_lds_dwordx4 v34, s[28:29]
	s_add_i32 m0, s31, 0x2000
	s_add_u32 s34, s28, 0x80000
	s_addc_u32 s35, s29, 0
	s_add_i32 s25, s25, s33
	global_load_lds_dwordx4 v184, s[28:29]
	s_mov_b32 m0, s25
	s_nop 0
	global_load_lds_dwordx4 v34, s[34:35]
	s_add_i32 m0, s25, 0x2000
	s_nop 0
	global_load_lds_dwordx4 v184, s[34:35]
	s_mov_b32 m0, s50
	s_nop 0
	global_load_lds_dwordx4 v188, s[40:41]
	s_mov_b32 m0, s51
	s_nop 0
	global_load_lds_dwordx4 v186, s[40:41]
	s_waitcnt vmcnt(8)
	s_waitcnt lgkmcnt(0)
	s_barrier
	s_setprio 1
	s_waitcnt lgkmcnt(0)
	v_mfma_f32_16x16x32_bf16 v[2:5], v[132:135], v[164:167], 0
	v_mfma_f32_16x16x32_bf16 v[6:9], v[140:143], v[164:167], 0
	v_mfma_f32_16x16x32_bf16 v[18:21], v[132:135], v[168:171], 0
	v_mfma_f32_16x16x32_bf16 v[22:25], v[140:143], v[168:171], 0
	v_mfma_f32_16x16x32_bf16 v[36:39], v[132:135], v[190:193], 0
	v_mfma_f32_16x16x32_bf16 v[40:43], v[140:143], v[190:193], 0
	v_mfma_f32_16x16x32_bf16 v[52:55], v[132:135], v[194:197], 0
	v_mfma_f32_16x16x32_bf16 v[56:59], v[140:143], v[194:197], 0
	v_mfma_f32_16x16x32_bf16 v[2:5], v[136:139], v[172:175], v[2:5]
	v_mfma_f32_16x16x32_bf16 v[6:9], v[144:147], v[172:175], v[6:9]
	v_mfma_f32_16x16x32_bf16 v[18:21], v[136:139], v[176:179], v[18:21]
	v_mfma_f32_16x16x32_bf16 v[22:25], v[144:147], v[176:179], v[22:25]
	v_mfma_f32_16x16x32_bf16 v[36:39], v[136:139], v[198:201], v[36:39]
	v_mfma_f32_16x16x32_bf16 v[40:43], v[144:147], v[198:201], v[40:43]
	v_mfma_f32_16x16x32_bf16 v[52:55], v[136:139], v[232:235], v[52:55]
	v_mfma_f32_16x16x32_bf16 v[56:59], v[144:147], v[232:235], v[56:59]
	s_setprio 0
	s_setprio 1
	v_mfma_f32_16x16x32_bf16 v[10:13], v[148:151], v[164:167], 0
	v_mfma_f32_16x16x32_bf16 v[14:17], v[156:159], v[164:167], 0
	v_mfma_f32_16x16x32_bf16 v[26:29], v[148:151], v[168:171], 0
	v_mfma_f32_16x16x32_bf16 v[30:33], v[156:159], v[168:171], 0
	v_mfma_f32_16x16x32_bf16 v[44:47], v[148:151], v[190:193], 0
	v_mfma_f32_16x16x32_bf16 v[48:51], v[156:159], v[190:193], 0
	v_mfma_f32_16x16x32_bf16 v[60:63], v[148:151], v[194:197], 0
	v_mfma_f32_16x16x32_bf16 v[64:67], v[156:159], v[194:197], 0
	v_mfma_f32_16x16x32_bf16 v[10:13], v[152:155], v[172:175], v[10:13]
	v_mfma_f32_16x16x32_bf16 v[14:17], v[160:163], v[172:175], v[14:17]
	v_mfma_f32_16x16x32_bf16 v[26:29], v[152:155], v[176:179], v[26:29]
	v_mfma_f32_16x16x32_bf16 v[30:33], v[160:163], v[176:179], v[30:33]
	v_mfma_f32_16x16x32_bf16 v[44:47], v[152:155], v[198:201], v[44:47]
	v_mfma_f32_16x16x32_bf16 v[48:51], v[160:163], v[198:201], v[48:51]
	v_mfma_f32_16x16x32_bf16 v[60:63], v[152:155], v[232:235], v[60:63]
	v_mfma_f32_16x16x32_bf16 v[64:67], v[160:163], v[232:235], v[64:67]
	s_setprio 0
	s_barrier
	s_add_i32 s25, 0, 0x18000
	s_add_i32 s31, 0, 0x1c000
	ds_read_b128 v[132:135], v1 offset:32768
	ds_read_b128 v[136:139], v204 offset:32768
	ds_read_b128 v[140:143], v1 offset:34816
	ds_read_b128 v[144:147], v204 offset:34816
	ds_read_b128 v[148:151], v1 offset:49152
	ds_read_b128 v[152:155], v204 offset:49152
	ds_read_b128 v[156:159], v1 offset:51200
	ds_read_b128 v[160:163], v204 offset:51200
	s_add_u32 s34, s40, 0x80000
	s_addc_u32 s35, s41, 0
	s_mov_b32 m0, s52
	ds_read_b128 v[164:167], v205 offset:32768
	ds_read_b128 v[168:171], v205 offset:34816
	ds_read_b128 v[172:175], v206 offset:32768
	ds_read_b128 v[176:179], v206 offset:34816
	ds_read_b128 v[190:193], v205 offset:36864
	ds_read_b128 v[194:197], v205 offset:38912
	ds_read_b128 v[198:201], v206 offset:36864
	ds_read_b128 v[232:235], v206 offset:38912
	global_load_lds_dwordx4 v188, s[34:35]
	s_mov_b32 m0, s53
	s_nop 0
	global_load_lds_dwordx4 v186, s[34:35]
	s_waitcnt vmcnt(8)
	s_waitcnt lgkmcnt(0)
	s_barrier
	s_setprio 1
	s_waitcnt lgkmcnt(0)
	v_mfma_f32_16x16x32_bf16 v[68:71], v[132:135], v[164:167], v[68:71]
	v_mfma_f32_16x16x32_bf16 v[72:75], v[140:143], v[164:167], v[72:75]
	v_mfma_f32_16x16x32_bf16 v[84:87], v[132:135], v[168:171], v[84:87]
	v_mfma_f32_16x16x32_bf16 v[88:91], v[140:143], v[168:171], v[88:91]
	v_mfma_f32_16x16x32_bf16 v[100:103], v[132:135], v[190:193], v[100:103]
	v_mfma_f32_16x16x32_bf16 v[104:107], v[140:143], v[190:193], v[104:107]
	v_mfma_f32_16x16x32_bf16 v[116:119], v[132:135], v[194:197], v[116:119]
	v_mfma_f32_16x16x32_bf16 v[120:123], v[140:143], v[194:197], v[120:123]
	v_mfma_f32_16x16x32_bf16 v[68:71], v[136:139], v[172:175], v[68:71]
	v_mfma_f32_16x16x32_bf16 v[72:75], v[144:147], v[172:175], v[72:75]
	v_mfma_f32_16x16x32_bf16 v[84:87], v[136:139], v[176:179], v[84:87]
	v_mfma_f32_16x16x32_bf16 v[88:91], v[144:147], v[176:179], v[88:91]
	v_mfma_f32_16x16x32_bf16 v[100:103], v[136:139], v[198:201], v[100:103]
	v_mfma_f32_16x16x32_bf16 v[104:107], v[144:147], v[198:201], v[104:107]
	v_mfma_f32_16x16x32_bf16 v[116:119], v[136:139], v[232:235], v[116:119]
	v_mfma_f32_16x16x32_bf16 v[120:123], v[144:147], v[232:235], v[120:123]
	s_setprio 0
	s_setprio 1
	v_mfma_f32_16x16x32_bf16 v[76:79], v[148:151], v[164:167], v[76:79]
	v_mfma_f32_16x16x32_bf16 v[80:83], v[156:159], v[164:167], v[80:83]
	v_mfma_f32_16x16x32_bf16 v[92:95], v[148:151], v[168:171], v[92:95]
	v_mfma_f32_16x16x32_bf16 v[96:99], v[156:159], v[168:171], v[96:99]
	v_mfma_f32_16x16x32_bf16 v[108:111], v[148:151], v[190:193], v[108:111]
	v_mfma_f32_16x16x32_bf16 v[112:115], v[156:159], v[190:193], v[112:115]
	v_mfma_f32_16x16x32_bf16 v[124:127], v[148:151], v[194:197], v[124:127]
	v_mfma_f32_16x16x32_bf16 v[128:131], v[156:159], v[194:197], v[128:131]
	v_mfma_f32_16x16x32_bf16 v[76:79], v[152:155], v[172:175], v[76:79]
	v_mfma_f32_16x16x32_bf16 v[80:83], v[160:163], v[172:175], v[80:83]
	v_mfma_f32_16x16x32_bf16 v[92:95], v[152:155], v[176:179], v[92:95]
	v_mfma_f32_16x16x32_bf16 v[96:99], v[160:163], v[176:179], v[96:99]
	v_mfma_f32_16x16x32_bf16 v[108:111], v[152:155], v[198:201], v[108:111]
	v_mfma_f32_16x16x32_bf16 v[112:115], v[160:163], v[198:201], v[112:115]
	v_mfma_f32_16x16x32_bf16 v[124:127], v[152:155], v[232:235], v[124:127]
	v_mfma_f32_16x16x32_bf16 v[128:131], v[160:163], v[232:235], v[128:131]
	s_setprio 0
	s_barrier
	s_add_i32 s25, s25, s33
	s_add_i32 m0, s25, 0xffffff80
	ds_read_b128 v[164:167], v205 offset:49152
	ds_read_b128 v[168:171], v205 offset:51200
	ds_read_b128 v[172:175], v206 offset:49152
	ds_read_b128 v[176:179], v206 offset:51200
	ds_read_b128 v[190:193], v205 offset:53248
	ds_read_b128 v[194:197], v205 offset:55296
	ds_read_b128 v[198:201], v206 offset:53248
	ds_read_b128 v[232:235], v206 offset:55296
	global_load_lds_dwordx4 v34, s[28:29] offset:128
	s_add_i32 m0, s25, 0x1f80
	s_mov_b64 s[98:99], s[28:29]
	s_add_u32 s28, s28, 0x80080
	s_addc_u32 s29, s29, 0
	s_add_i32 s25, s31, s33
	global_load_lds_dwordx4 v184, s[98:99] offset:128
	s_mov_b32 m0, s25
	s_nop 0
	global_load_lds_dwordx4 v34, s[28:29]
	s_add_i32 m0, s25, 0x2000
	s_nop 0
	global_load_lds_dwordx4 v184, s[28:29]
	s_add_i32 m0, s54, 0xffffff80
	s_nop 0
	global_load_lds_dwordx4 v188, s[40:41] offset:128
	s_add_i32 m0, s55, 0xffffff80
	s_nop 0
	global_load_lds_dwordx4 v186, s[40:41] offset:128
	s_waitcnt vmcnt(8)
	s_waitcnt lgkmcnt(0)
	s_barrier
	s_setprio 1
	s_waitcnt lgkmcnt(0)
	v_mfma_f32_16x16x32_bf16 v[2:5], v[132:135], v[164:167], v[2:5]
	v_mfma_f32_16x16x32_bf16 v[6:9], v[140:143], v[164:167], v[6:9]
	v_mfma_f32_16x16x32_bf16 v[18:21], v[132:135], v[168:171], v[18:21]
	v_mfma_f32_16x16x32_bf16 v[22:25], v[140:143], v[168:171], v[22:25]
	v_mfma_f32_16x16x32_bf16 v[36:39], v[132:135], v[190:193], v[36:39]
	v_mfma_f32_16x16x32_bf16 v[40:43], v[140:143], v[190:193], v[40:43]
	v_mfma_f32_16x16x32_bf16 v[52:55], v[132:135], v[194:197], v[52:55]
	v_mfma_f32_16x16x32_bf16 v[56:59], v[140:143], v[194:197], v[56:59]
	v_mfma_f32_16x16x32_bf16 v[2:5], v[136:139], v[172:175], v[2:5]
	v_mfma_f32_16x16x32_bf16 v[6:9], v[144:147], v[172:175], v[6:9]
	v_mfma_f32_16x16x32_bf16 v[18:21], v[136:139], v[176:179], v[18:21]
	v_mfma_f32_16x16x32_bf16 v[22:25], v[144:147], v[176:179], v[22:25]
	v_mfma_f32_16x16x32_bf16 v[36:39], v[136:139], v[198:201], v[36:39]
	v_mfma_f32_16x16x32_bf16 v[40:43], v[144:147], v[198:201], v[40:43]
	v_mfma_f32_16x16x32_bf16 v[52:55], v[136:139], v[232:235], v[52:55]
	v_mfma_f32_16x16x32_bf16 v[56:59], v[144:147], v[232:235], v[56:59]
	s_setprio 0
	s_setprio 1
	v_mfma_f32_16x16x32_bf16 v[10:13], v[148:151], v[164:167], v[10:13]
	v_mfma_f32_16x16x32_bf16 v[14:17], v[156:159], v[164:167], v[14:17]
	v_mfma_f32_16x16x32_bf16 v[26:29], v[148:151], v[168:171], v[26:29]
	v_mfma_f32_16x16x32_bf16 v[30:33], v[156:159], v[168:171], v[30:33]
	v_mfma_f32_16x16x32_bf16 v[44:47], v[148:151], v[190:193], v[44:47]
	v_mfma_f32_16x16x32_bf16 v[48:51], v[156:159], v[190:193], v[48:51]
	v_mfma_f32_16x16x32_bf16 v[60:63], v[148:151], v[194:197], v[60:63]
	v_mfma_f32_16x16x32_bf16 v[64:67], v[156:159], v[194:197], v[64:67]
	v_mfma_f32_16x16x32_bf16 v[10:13], v[152:155], v[172:175], v[10:13]
	v_mfma_f32_16x16x32_bf16 v[14:17], v[160:163], v[172:175], v[14:17]
	v_mfma_f32_16x16x32_bf16 v[26:29], v[152:155], v[176:179], v[26:29]
	v_mfma_f32_16x16x32_bf16 v[30:33], v[160:163], v[176:179], v[30:33]
	v_mfma_f32_16x16x32_bf16 v[44:47], v[152:155], v[198:201], v[44:47]
	v_mfma_f32_16x16x32_bf16 v[48:51], v[160:163], v[198:201], v[48:51]
	v_mfma_f32_16x16x32_bf16 v[60:63], v[152:155], v[232:235], v[60:63]
	v_mfma_f32_16x16x32_bf16 v[64:67], v[160:163], v[232:235], v[64:67]
	s_setprio 0
	s_barrier
	s_add_u32 s22, s22, 0x100
	s_addc_u32 s23, s23, 0
	s_add_u32 s21, s21, 0x100
	s_addc_u32 s24, s24, 0
	s_cmp_ge_u32 s30, s9
	s_mov_b32 s25, s30
	s_cbranch_scc1 .Lpeel_done_P3
.LBB0_908:
	s_add_i32 s30, s25, 2
	s_add_u32 s28, s22, 0xfff80080
	s_addc_u32 s29, s23, -1
	s_add_i32 s31, 0, 0x10000
	s_cmp_eq_u32 s20, s25
	s_cselect_b32 s41, s47, s29
	s_cselect_b32 s40, s46, s28
	s_cselect_b32 s29, s49, s24
	s_cselect_b32 s28, s48, s21
	s_add_i32 s25, 0, 0x14000
	ds_read_b128 v[132:135], v1
	ds_read_b128 v[136:139], v204
	ds_read_b128 v[140:143], v1 offset:2048
	ds_read_b128 v[144:147], v204 offset:2048
	ds_read_b128 v[148:151], v1 offset:16384
	ds_read_b128 v[152:155], v204 offset:16384
	ds_read_b128 v[156:159], v1 offset:18432
	ds_read_b128 v[160:163], v204 offset:18432
	s_add_i32 m0, s50, 0xc000
	ds_read_b128 v[164:167], v205
	ds_read_b128 v[168:171], v205 offset:2048
	ds_read_b128 v[172:175], v206
	ds_read_b128 v[176:179], v206 offset:2048
	ds_read_b128 v[190:193], v205 offset:4096
	ds_read_b128 v[194:197], v205 offset:6144
	ds_read_b128 v[198:201], v206 offset:4096
	ds_read_b128 v[232:235], v206 offset:6144
	global_load_lds_dwordx4 v188, s[22:23]
	s_add_i32 m0, s50, 0xe000
	s_nop 0
	global_load_lds_dwordx4 v186, s[22:23]
	s_waitcnt vmcnt(8)
	s_waitcnt lgkmcnt(0)
	s_barrier
	s_setprio 1
	s_waitcnt lgkmcnt(0)
	v_mfma_f32_16x16x32_bf16 v[68:71], v[132:135], v[164:167], v[68:71]
	v_mfma_f32_16x16x32_bf16 v[72:75], v[140:143], v[164:167], v[72:75]
	v_mfma_f32_16x16x32_bf16 v[84:87], v[132:135], v[168:171], v[84:87]
	v_mfma_f32_16x16x32_bf16 v[88:91], v[140:143], v[168:171], v[88:91]
	v_mfma_f32_16x16x32_bf16 v[100:103], v[132:135], v[190:193], v[100:103]
	v_mfma_f32_16x16x32_bf16 v[104:107], v[140:143], v[190:193], v[104:107]
	v_mfma_f32_16x16x32_bf16 v[116:119], v[132:135], v[194:197], v[116:119]
	v_mfma_f32_16x16x32_bf16 v[120:123], v[140:143], v[194:197], v[120:123]
	v_mfma_f32_16x16x32_bf16 v[68:71], v[136:139], v[172:175], v[68:71]
	v_mfma_f32_16x16x32_bf16 v[72:75], v[144:147], v[172:175], v[72:75]
	v_mfma_f32_16x16x32_bf16 v[84:87], v[136:139], v[176:179], v[84:87]
	v_mfma_f32_16x16x32_bf16 v[88:91], v[144:147], v[176:179], v[88:91]
	v_mfma_f32_16x16x32_bf16 v[100:103], v[136:139], v[198:201], v[100:103]
	v_mfma_f32_16x16x32_bf16 v[104:107], v[144:147], v[198:201], v[104:107]
	v_mfma_f32_16x16x32_bf16 v[116:119], v[136:139], v[232:235], v[116:119]
	v_mfma_f32_16x16x32_bf16 v[120:123], v[144:147], v[232:235], v[120:123]
	s_setprio 0
	s_setprio 1
	v_mfma_f32_16x16x32_bf16 v[76:79], v[148:151], v[164:167], v[76:79]
	v_mfma_f32_16x16x32_bf16 v[80:83], v[156:159], v[164:167], v[80:83]
	v_mfma_f32_16x16x32_bf16 v[92:95], v[148:151], v[168:171], v[92:95]
	v_mfma_f32_16x16x32_bf16 v[96:99], v[156:159], v[168:171], v[96:99]
	v_mfma_f32_16x16x32_bf16 v[108:111], v[148:151], v[190:193], v[108:111]
	v_mfma_f32_16x16x32_bf16 v[112:115], v[156:159], v[190:193], v[112:115]
	v_mfma_f32_16x16x32_bf16 v[124:127], v[148:151], v[194:197], v[124:127]
	v_mfma_f32_16x16x32_bf16 v[128:131], v[156:159], v[194:197], v[128:131]
	v_mfma_f32_16x16x32_bf16 v[76:79], v[152:155], v[172:175], v[76:79]
	v_mfma_f32_16x16x32_bf16 v[80:83], v[160:163], v[172:175], v[80:83]
	v_mfma_f32_16x16x32_bf16 v[92:95], v[152:155], v[176:179], v[92:95]
	v_mfma_f32_16x16x32_bf16 v[96:99], v[160:163], v[176:179], v[96:99]
	v_mfma_f32_16x16x32_bf16 v[108:111], v[152:155], v[198:201], v[108:111]
	v_mfma_f32_16x16x32_bf16 v[112:115], v[160:163], v[198:201], v[112:115]
	v_mfma_f32_16x16x32_bf16 v[124:127], v[152:155], v[232:235], v[124:127]
	v_mfma_f32_16x16x32_bf16 v[128:131], v[160:163], v[232:235], v[128:131]
	s_setprio 0
	s_barrier
	s_add_i32 s31, s31, s33
	s_mov_b32 m0, s31
	ds_read_b128 v[164:167], v205 offset:16384
	ds_read_b128 v[168:171], v205 offset:18432
	ds_read_b128 v[172:175], v206 offset:16384
	ds_read_b128 v[176:179], v206 offset:18432
	ds_read_b128 v[190:193], v205 offset:20480
	ds_read_b128 v[194:197], v205 offset:22528
	ds_read_b128 v[198:201], v206 offset:20480
	ds_read_b128 v[232:235], v206 offset:22528
	global_load_lds_dwordx4 v34, s[28:29]
	s_add_i32 m0, s31, 0x2000
	s_add_u32 s34, s28, 0x80000
	s_addc_u32 s35, s29, 0
	s_add_i32 s25, s25, s33
	global_load_lds_dwordx4 v184, s[28:29]
	s_mov_b32 m0, s25
	s_nop 0
	global_load_lds_dwordx4 v34, s[34:35]
	s_add_i32 m0, s25, 0x2000
	s_nop 0
	global_load_lds_dwordx4 v184, s[34:35]
	s_mov_b32 m0, s50
	s_nop 0
	global_load_lds_dwordx4 v188, s[40:41]
	s_mov_b32 m0, s51
	s_nop 0
	global_load_lds_dwordx4 v186, s[40:41]
	s_waitcnt vmcnt(8)
	s_waitcnt lgkmcnt(0)
	s_barrier
	s_setprio 1
	s_waitcnt lgkmcnt(0)
	v_mfma_f32_16x16x32_bf16 v[2:5], v[132:135], v[164:167], v[2:5]
	v_mfma_f32_16x16x32_bf16 v[6:9], v[140:143], v[164:167], v[6:9]
	v_mfma_f32_16x16x32_bf16 v[18:21], v[132:135], v[168:171], v[18:21]
	v_mfma_f32_16x16x32_bf16 v[22:25], v[140:143], v[168:171], v[22:25]
	v_mfma_f32_16x16x32_bf16 v[36:39], v[132:135], v[190:193], v[36:39]
	v_mfma_f32_16x16x32_bf16 v[40:43], v[140:143], v[190:193], v[40:43]
	v_mfma_f32_16x16x32_bf16 v[52:55], v[132:135], v[194:197], v[52:55]
	v_mfma_f32_16x16x32_bf16 v[56:59], v[140:143], v[194:197], v[56:59]
	v_mfma_f32_16x16x32_bf16 v[2:5], v[136:139], v[172:175], v[2:5]
	v_mfma_f32_16x16x32_bf16 v[6:9], v[144:147], v[172:175], v[6:9]
	v_mfma_f32_16x16x32_bf16 v[18:21], v[136:139], v[176:179], v[18:21]
	v_mfma_f32_16x16x32_bf16 v[22:25], v[144:147], v[176:179], v[22:25]
	v_mfma_f32_16x16x32_bf16 v[36:39], v[136:139], v[198:201], v[36:39]
	v_mfma_f32_16x16x32_bf16 v[40:43], v[144:147], v[198:201], v[40:43]
	v_mfma_f32_16x16x32_bf16 v[52:55], v[136:139], v[232:235], v[52:55]
	v_mfma_f32_16x16x32_bf16 v[56:59], v[144:147], v[232:235], v[56:59]
	s_setprio 0
	s_setprio 1
	v_mfma_f32_16x16x32_bf16 v[10:13], v[148:151], v[164:167], v[10:13]
	v_mfma_f32_16x16x32_bf16 v[14:17], v[156:159], v[164:167], v[14:17]
	v_mfma_f32_16x16x32_bf16 v[26:29], v[148:151], v[168:171], v[26:29]
	v_mfma_f32_16x16x32_bf16 v[30:33], v[156:159], v[168:171], v[30:33]
	v_mfma_f32_16x16x32_bf16 v[44:47], v[148:151], v[190:193], v[44:47]
	v_mfma_f32_16x16x32_bf16 v[48:51], v[156:159], v[190:193], v[48:51]
	v_mfma_f32_16x16x32_bf16 v[60:63], v[148:151], v[194:197], v[60:63]
	v_mfma_f32_16x16x32_bf16 v[64:67], v[156:159], v[194:197], v[64:67]
	v_mfma_f32_16x16x32_bf16 v[10:13], v[152:155], v[172:175], v[10:13]
	v_mfma_f32_16x16x32_bf16 v[14:17], v[160:163], v[172:175], v[14:17]
	v_mfma_f32_16x16x32_bf16 v[26:29], v[152:155], v[176:179], v[26:29]
	v_mfma_f32_16x16x32_bf16 v[30:33], v[160:163], v[176:179], v[30:33]
	v_mfma_f32_16x16x32_bf16 v[44:47], v[152:155], v[198:201], v[44:47]
	v_mfma_f32_16x16x32_bf16 v[48:51], v[160:163], v[198:201], v[48:51]
	v_mfma_f32_16x16x32_bf16 v[60:63], v[152:155], v[232:235], v[60:63]
	v_mfma_f32_16x16x32_bf16 v[64:67], v[160:163], v[232:235], v[64:67]
	s_setprio 0
	s_barrier
	s_add_i32 s25, 0, 0x18000
	s_add_i32 s31, 0, 0x1c000
	ds_read_b128 v[132:135], v1 offset:32768
	ds_read_b128 v[136:139], v204 offset:32768
	ds_read_b128 v[140:143], v1 offset:34816
	ds_read_b128 v[144:147], v204 offset:34816
	ds_read_b128 v[148:151], v1 offset:49152
	ds_read_b128 v[152:155], v204 offset:49152
	ds_read_b128 v[156:159], v1 offset:51200
	ds_read_b128 v[160:163], v204 offset:51200
	s_add_u32 s34, s40, 0x80000
	s_addc_u32 s35, s41, 0
	s_mov_b32 m0, s52
	ds_read_b128 v[164:167], v205 offset:32768
	ds_read_b128 v[168:171], v205 offset:34816
	ds_read_b128 v[172:175], v206 offset:32768
	ds_read_b128 v[176:179], v206 offset:34816
	ds_read_b128 v[190:193], v205 offset:36864
	ds_read_b128 v[194:197], v205 offset:38912
	ds_read_b128 v[198:201], v206 offset:36864
	ds_read_b128 v[232:235], v206 offset:38912
	global_load_lds_dwordx4 v188, s[34:35]
	s_mov_b32 m0, s53
	s_nop 0
	global_load_lds_dwordx4 v186, s[34:35]
	s_waitcnt vmcnt(8)
	s_waitcnt lgkmcnt(0)
	s_barrier
	s_setprio 1
	s_waitcnt lgkmcnt(0)
	v_mfma_f32_16x16x32_bf16 v[68:71], v[132:135], v[164:167], v[68:71]
	v_mfma_f32_16x16x32_bf16 v[72:75], v[140:143], v[164:167], v[72:75]
	v_mfma_f32_16x16x32_bf16 v[84:87], v[132:135], v[168:171], v[84:87]
	v_mfma_f32_16x16x32_bf16 v[88:91], v[140:143], v[168:171], v[88:91]
	v_mfma_f32_16x16x32_bf16 v[100:103], v[132:135], v[190:193], v[100:103]
	v_mfma_f32_16x16x32_bf16 v[104:107], v[140:143], v[190:193], v[104:107]
	v_mfma_f32_16x16x32_bf16 v[116:119], v[132:135], v[194:197], v[116:119]
	v_mfma_f32_16x16x32_bf16 v[120:123], v[140:143], v[194:197], v[120:123]
	v_mfma_f32_16x16x32_bf16 v[68:71], v[136:139], v[172:175], v[68:71]
	v_mfma_f32_16x16x32_bf16 v[72:75], v[144:147], v[172:175], v[72:75]
	v_mfma_f32_16x16x32_bf16 v[84:87], v[136:139], v[176:179], v[84:87]
	v_mfma_f32_16x16x32_bf16 v[88:91], v[144:147], v[176:179], v[88:91]
	v_mfma_f32_16x16x32_bf16 v[100:103], v[136:139], v[198:201], v[100:103]
	v_mfma_f32_16x16x32_bf16 v[104:107], v[144:147], v[198:201], v[104:107]
	v_mfma_f32_16x16x32_bf16 v[116:119], v[136:139], v[232:235], v[116:119]
	v_mfma_f32_16x16x32_bf16 v[120:123], v[144:147], v[232:235], v[120:123]
	s_setprio 0
	s_setprio 1
	v_mfma_f32_16x16x32_bf16 v[76:79], v[148:151], v[164:167], v[76:79]
	v_mfma_f32_16x16x32_bf16 v[80:83], v[156:159], v[164:167], v[80:83]
	v_mfma_f32_16x16x32_bf16 v[92:95], v[148:151], v[168:171], v[92:95]
	v_mfma_f32_16x16x32_bf16 v[96:99], v[156:159], v[168:171], v[96:99]
	v_mfma_f32_16x16x32_bf16 v[108:111], v[148:151], v[190:193], v[108:111]
	v_mfma_f32_16x16x32_bf16 v[112:115], v[156:159], v[190:193], v[112:115]
	v_mfma_f32_16x16x32_bf16 v[124:127], v[148:151], v[194:197], v[124:127]
	v_mfma_f32_16x16x32_bf16 v[128:131], v[156:159], v[194:197], v[128:131]
	v_mfma_f32_16x16x32_bf16 v[76:79], v[152:155], v[172:175], v[76:79]
	v_mfma_f32_16x16x32_bf16 v[80:83], v[160:163], v[172:175], v[80:83]
	v_mfma_f32_16x16x32_bf16 v[92:95], v[152:155], v[176:179], v[92:95]
	v_mfma_f32_16x16x32_bf16 v[96:99], v[160:163], v[176:179], v[96:99]
	v_mfma_f32_16x16x32_bf16 v[108:111], v[152:155], v[198:201], v[108:111]
	v_mfma_f32_16x16x32_bf16 v[112:115], v[160:163], v[198:201], v[112:115]
	v_mfma_f32_16x16x32_bf16 v[124:127], v[152:155], v[232:235], v[124:127]
	v_mfma_f32_16x16x32_bf16 v[128:131], v[160:163], v[232:235], v[128:131]
	s_setprio 0
	s_barrier
	s_add_i32 s25, s25, s33
	s_add_i32 m0, s25, 0xffffff80
	ds_read_b128 v[164:167], v205 offset:49152
	ds_read_b128 v[168:171], v205 offset:51200
	ds_read_b128 v[172:175], v206 offset:49152
	ds_read_b128 v[176:179], v206 offset:51200
	ds_read_b128 v[190:193], v205 offset:53248
	ds_read_b128 v[194:197], v205 offset:55296
	ds_read_b128 v[198:201], v206 offset:53248
	ds_read_b128 v[232:235], v206 offset:55296
	global_load_lds_dwordx4 v34, s[28:29] offset:128
	s_add_i32 m0, s25, 0x1f80
	s_mov_b64 s[98:99], s[28:29]
	s_add_u32 s28, s28, 0x80080
	s_addc_u32 s29, s29, 0
	s_add_i32 s25, s31, s33
	global_load_lds_dwordx4 v184, s[98:99] offset:128
	s_mov_b32 m0, s25
	s_nop 0
	global_load_lds_dwordx4 v34, s[28:29]
	s_add_i32 m0, s25, 0x2000
	s_nop 0
	global_load_lds_dwordx4 v184, s[28:29]
	s_add_i32 m0, s54, 0xffffff80
	s_nop 0
	global_load_lds_dwordx4 v188, s[40:41] offset:128
	s_add_i32 m0, s55, 0xffffff80
	s_nop 0
	global_load_lds_dwordx4 v186, s[40:41] offset:128
	s_waitcnt vmcnt(8)
	s_waitcnt lgkmcnt(0)
	s_barrier
	s_setprio 1
	s_waitcnt lgkmcnt(0)
	v_mfma_f32_16x16x32_bf16 v[2:5], v[132:135], v[164:167], v[2:5]
	v_mfma_f32_16x16x32_bf16 v[6:9], v[140:143], v[164:167], v[6:9]
	v_mfma_f32_16x16x32_bf16 v[18:21], v[132:135], v[168:171], v[18:21]
	v_mfma_f32_16x16x32_bf16 v[22:25], v[140:143], v[168:171], v[22:25]
	v_mfma_f32_16x16x32_bf16 v[36:39], v[132:135], v[190:193], v[36:39]
	v_mfma_f32_16x16x32_bf16 v[40:43], v[140:143], v[190:193], v[40:43]
	v_mfma_f32_16x16x32_bf16 v[52:55], v[132:135], v[194:197], v[52:55]
	v_mfma_f32_16x16x32_bf16 v[56:59], v[140:143], v[194:197], v[56:59]
	v_mfma_f32_16x16x32_bf16 v[2:5], v[136:139], v[172:175], v[2:5]
	v_mfma_f32_16x16x32_bf16 v[6:9], v[144:147], v[172:175], v[6:9]
	v_mfma_f32_16x16x32_bf16 v[18:21], v[136:139], v[176:179], v[18:21]
	v_mfma_f32_16x16x32_bf16 v[22:25], v[144:147], v[176:179], v[22:25]
	v_mfma_f32_16x16x32_bf16 v[36:39], v[136:139], v[198:201], v[36:39]
	v_mfma_f32_16x16x32_bf16 v[40:43], v[144:147], v[198:201], v[40:43]
	v_mfma_f32_16x16x32_bf16 v[52:55], v[136:139], v[232:235], v[52:55]
	v_mfma_f32_16x16x32_bf16 v[56:59], v[144:147], v[232:235], v[56:59]
	s_setprio 0
	s_setprio 1
	v_mfma_f32_16x16x32_bf16 v[10:13], v[148:151], v[164:167], v[10:13]
	v_mfma_f32_16x16x32_bf16 v[14:17], v[156:159], v[164:167], v[14:17]
	v_mfma_f32_16x16x32_bf16 v[26:29], v[148:151], v[168:171], v[26:29]
	v_mfma_f32_16x16x32_bf16 v[30:33], v[156:159], v[168:171], v[30:33]
	v_mfma_f32_16x16x32_bf16 v[44:47], v[148:151], v[190:193], v[44:47]
	v_mfma_f32_16x16x32_bf16 v[48:51], v[156:159], v[190:193], v[48:51]
	v_mfma_f32_16x16x32_bf16 v[60:63], v[148:151], v[194:197], v[60:63]
	v_mfma_f32_16x16x32_bf16 v[64:67], v[156:159], v[194:197], v[64:67]
	v_mfma_f32_16x16x32_bf16 v[10:13], v[152:155], v[172:175], v[10:13]
	v_mfma_f32_16x16x32_bf16 v[14:17], v[160:163], v[172:175], v[14:17]
	v_mfma_f32_16x16x32_bf16 v[26:29], v[152:155], v[176:179], v[26:29]
	v_mfma_f32_16x16x32_bf16 v[30:33], v[160:163], v[176:179], v[30:33]
	v_mfma_f32_16x16x32_bf16 v[44:47], v[152:155], v[198:201], v[44:47]
	v_mfma_f32_16x16x32_bf16 v[48:51], v[160:163], v[198:201], v[48:51]
	v_mfma_f32_16x16x32_bf16 v[60:63], v[152:155], v[232:235], v[60:63]
	v_mfma_f32_16x16x32_bf16 v[64:67], v[160:163], v[232:235], v[64:67]
	s_setprio 0
	s_barrier
	s_add_u32 s22, s22, 0x100
	s_addc_u32 s23, s23, 0
	s_add_u32 s21, s21, 0x100
	s_addc_u32 s24, s24, 0
	s_cmp_ge_u32 s30, s9
	s_mov_b32 s25, s30
	s_cbranch_scc0 .LBB0_908

.LBB0_1022:
	s_ashr_i32 s23, s22, 31
	s_lshl_b64 s[12:13], s[22:23], 20
	v_readlane_b32 s20, v254, 52
	v_readlane_b32 s21, v254, 53
	s_add_u32 s40, s20, s12
	s_addc_u32 s41, s21, s13
	s_and_b64 s[12:13], s[38:39], exec
	s_cselect_b32 s12, s41, s9
	s_cselect_b32 s13, s40, s8
	s_ashr_i32 s19, s18, 31
	s_lshl_b64 s[20:21], s[18:19], 20
	v_readlane_b32 s24, v254, 48
	v_readlane_b32 s25, v254, 49
	s_add_u32 s42, s24, s20
	s_addc_u32 s43, s25, s21
	s_and_b64 s[20:21], s[38:39], exec
	s_cselect_b32 s19, s43, s29
	s_cselect_b32 s20, s42, s28
	s_add_u32 s8, s8, 0x80080
	s_addc_u32 s9, s9, 0
	s_add_u32 s21, s28, 0x100
	s_addc_u32 s23, s29, 0
	s_mov_b32 s24, -2
	v_readlane_b32 s35, v255, 20
	v_readlane_b32 s57, v255, 21
	v_readlane_b32 s58, v255, 22
	v_readlane_b32 s59, v255, 23
	s_mov_b64 s[60:61], 0x80
	s_add_u32 s25, s8, 0xfff80080
	s_addc_u32 s28, s9, -1
	s_add_i32 s30, 0, 0x10000
	s_cmp_eq_u32 s24, 28
	s_cselect_b32 s45, s12, s28
	s_cselect_b32 s44, s13, s25
	s_cselect_b32 s29, s19, s23
	s_cselect_b32 s28, s20, s21
	s_add_i32 s25, 0, 0x14000
	ds_read_b128 v[138:141], v1
	ds_read_b128 v[142:145], v150
	ds_read_b128 v[146:149], v1 offset:2048
	ds_read_b128 v[154:157], v150 offset:2048
	ds_read_b128 v[158:161], v1 offset:16384
	ds_read_b128 v[162:165], v150 offset:16384
	ds_read_b128 v[166:169], v1 offset:18432
	ds_read_b128 v[170:173], v150 offset:18432
	s_add_i32 m0, s46, 0xc000
	ds_read_b128 v[174:177], v151
	ds_read_b128 v[184:187], v151 offset:2048
	ds_read_b128 v[188:191], v152
	ds_read_b128 v[192:195], v152 offset:2048
	ds_read_b128 v[196:199], v151 offset:4096
	ds_read_b128 v[200:203], v151 offset:6144
	ds_read_b128 v[204:207], v152 offset:4096
	ds_read_b128 v[208:211], v152 offset:6144
	global_load_lds_dwordx4 v136, s[8:9]
	s_add_i32 m0, s46, 0xe000
	s_nop 0
	global_load_lds_dwordx4 v134, s[8:9]
	s_waitcnt vmcnt(8)
	s_waitcnt lgkmcnt(0)
	s_barrier
	s_setprio 1
	s_waitcnt lgkmcnt(0)
	v_mfma_f32_16x16x32_bf16 v[128:131], v[138:141], v[174:177], 0
	v_mfma_f32_16x16x32_bf16 v[124:127], v[146:149], v[174:177], 0
	v_mfma_f32_16x16x32_bf16 v[112:115], v[138:141], v[184:187], 0
	v_mfma_f32_16x16x32_bf16 v[108:111], v[146:149], v[184:187], 0
	v_mfma_f32_16x16x32_bf16 v[96:99], v[138:141], v[196:199], 0
	v_mfma_f32_16x16x32_bf16 v[92:95], v[146:149], v[196:199], 0
	v_mfma_f32_16x16x32_bf16 v[80:83], v[138:141], v[200:203], 0
	v_mfma_f32_16x16x32_bf16 v[76:79], v[146:149], v[200:203], 0
	v_mfma_f32_16x16x32_bf16 v[128:131], v[142:145], v[188:191], v[128:131]
	v_mfma_f32_16x16x32_bf16 v[124:127], v[154:157], v[188:191], v[124:127]
	v_mfma_f32_16x16x32_bf16 v[112:115], v[142:145], v[192:195], v[112:115]
	v_mfma_f32_16x16x32_bf16 v[108:111], v[154:157], v[192:195], v[108:111]
	v_mfma_f32_16x16x32_bf16 v[96:99], v[142:145], v[204:207], v[96:99]
	v_mfma_f32_16x16x32_bf16 v[92:95], v[154:157], v[204:207], v[92:95]
	v_mfma_f32_16x16x32_bf16 v[80:83], v[142:145], v[208:211], v[80:83]
	v_mfma_f32_16x16x32_bf16 v[76:79], v[154:157], v[208:211], v[76:79]
	s_setprio 0
	s_setprio 1
	v_mfma_f32_16x16x32_bf16 v[120:123], v[158:161], v[174:177], 0
	v_mfma_f32_16x16x32_bf16 v[116:119], v[166:169], v[174:177], 0
	v_mfma_f32_16x16x32_bf16 v[104:107], v[158:161], v[184:187], 0
	v_mfma_f32_16x16x32_bf16 v[100:103], v[166:169], v[184:187], 0
	v_mfma_f32_16x16x32_bf16 v[88:91], v[158:161], v[196:199], 0
	v_mfma_f32_16x16x32_bf16 v[84:87], v[166:169], v[196:199], 0
	v_mfma_f32_16x16x32_bf16 v[72:75], v[158:161], v[200:203], 0
	v_mfma_f32_16x16x32_bf16 v[68:71], v[166:169], v[200:203], 0
	v_mfma_f32_16x16x32_bf16 v[120:123], v[162:165], v[188:191], v[120:123]
	v_mfma_f32_16x16x32_bf16 v[116:119], v[170:173], v[188:191], v[116:119]
	v_mfma_f32_16x16x32_bf16 v[104:107], v[162:165], v[192:195], v[104:107]
	v_mfma_f32_16x16x32_bf16 v[100:103], v[170:173], v[192:195], v[100:103]
	v_mfma_f32_16x16x32_bf16 v[88:91], v[162:165], v[204:207], v[88:91]
	v_mfma_f32_16x16x32_bf16 v[84:87], v[170:173], v[204:207], v[84:87]
	v_mfma_f32_16x16x32_bf16 v[72:75], v[162:165], v[208:211], v[72:75]
	v_mfma_f32_16x16x32_bf16 v[68:71], v[170:173], v[208:211], v[68:71]
	s_setprio 0
	s_barrier
	s_add_i32 s30, s30, s33
	s_mov_b32 m0, s30
	ds_read_b128 v[174:177], v151 offset:16384
	ds_read_b128 v[184:187], v151 offset:18432
	ds_read_b128 v[188:191], v152 offset:16384
	ds_read_b128 v[192:195], v152 offset:18432
	ds_read_b128 v[196:199], v151 offset:20480
	ds_read_b128 v[200:203], v151 offset:22528
	ds_read_b128 v[204:207], v152 offset:20480
	ds_read_b128 v[208:211], v152 offset:22528
	global_load_lds_dwordx4 v34, s[28:29]
	s_add_i32 m0, s30, 0x2000
	s_add_u32 s30, s28, 0x80000
	s_addc_u32 s31, s29, 0
	s_add_i32 s25, s25, s33
	global_load_lds_dwordx4 v132, s[28:29]
	s_mov_b32 m0, s25
	s_nop 0
	global_load_lds_dwordx4 v34, s[30:31]
	s_add_i32 m0, s25, 0x2000
	s_nop 0
	global_load_lds_dwordx4 v132, s[30:31]
	s_mov_b32 m0, s46
	s_nop 0
	global_load_lds_dwordx4 v136, s[44:45]
	s_mov_b32 m0, s47
	s_nop 0
	global_load_lds_dwordx4 v134, s[44:45]
	s_waitcnt vmcnt(8)
	s_waitcnt lgkmcnt(0)
	s_barrier
	s_setprio 1
	s_waitcnt lgkmcnt(0)
	v_mfma_f32_16x16x32_bf16 v[64:67], v[138:141], v[174:177], 0
	v_mfma_f32_16x16x32_bf16 v[60:63], v[146:149], v[174:177], 0
	v_mfma_f32_16x16x32_bf16 v[48:51], v[138:141], v[184:187], 0
	v_mfma_f32_16x16x32_bf16 v[44:47], v[146:149], v[184:187], 0
	v_mfma_f32_16x16x32_bf16 v[30:33], v[138:141], v[196:199], 0
	v_mfma_f32_16x16x32_bf16 v[26:29], v[146:149], v[196:199], 0
	v_mfma_f32_16x16x32_bf16 v[14:17], v[138:141], v[200:203], 0
	v_mfma_f32_16x16x32_bf16 v[10:13], v[146:149], v[200:203], 0
	v_mfma_f32_16x16x32_bf16 v[64:67], v[142:145], v[188:191], v[64:67]
	v_mfma_f32_16x16x32_bf16 v[60:63], v[154:157], v[188:191], v[60:63]
	v_mfma_f32_16x16x32_bf16 v[48:51], v[142:145], v[192:195], v[48:51]
	v_mfma_f32_16x16x32_bf16 v[44:47], v[154:157], v[192:195], v[44:47]
	v_mfma_f32_16x16x32_bf16 v[30:33], v[142:145], v[204:207], v[30:33]
	v_mfma_f32_16x16x32_bf16 v[26:29], v[154:157], v[204:207], v[26:29]
	v_mfma_f32_16x16x32_bf16 v[14:17], v[142:145], v[208:211], v[14:17]
	v_mfma_f32_16x16x32_bf16 v[10:13], v[154:157], v[208:211], v[10:13]
	s_setprio 0
	s_setprio 1
	v_mfma_f32_16x16x32_bf16 v[56:59], v[158:161], v[174:177], 0
	v_mfma_f32_16x16x32_bf16 v[52:55], v[166:169], v[174:177], 0
	v_mfma_f32_16x16x32_bf16 v[40:43], v[158:161], v[184:187], 0
	v_mfma_f32_16x16x32_bf16 v[36:39], v[166:169], v[184:187], 0
	v_mfma_f32_16x16x32_bf16 v[22:25], v[158:161], v[196:199], 0
	v_mfma_f32_16x16x32_bf16 v[18:21], v[166:169], v[196:199], 0
	v_mfma_f32_16x16x32_bf16 v[6:9], v[158:161], v[200:203], 0
	v_mfma_f32_16x16x32_bf16 v[2:5], v[166:169], v[200:203], 0
	v_mfma_f32_16x16x32_bf16 v[56:59], v[162:165], v[188:191], v[56:59]
	v_mfma_f32_16x16x32_bf16 v[52:55], v[170:173], v[188:191], v[52:55]
	v_mfma_f32_16x16x32_bf16 v[40:43], v[162:165], v[192:195], v[40:43]
	v_mfma_f32_16x16x32_bf16 v[36:39], v[170:173], v[192:195], v[36:39]
	v_mfma_f32_16x16x32_bf16 v[22:25], v[162:165], v[204:207], v[22:25]
	v_mfma_f32_16x16x32_bf16 v[18:21], v[170:173], v[204:207], v[18:21]
	v_mfma_f32_16x16x32_bf16 v[6:9], v[162:165], v[208:211], v[6:9]
	v_mfma_f32_16x16x32_bf16 v[2:5], v[170:173], v[208:211], v[2:5]
	s_setprio 0
	s_barrier
	s_add_i32 s25, 0, 0x18000
	s_add_i32 s34, 0, 0x1c000
	ds_read_b128 v[138:141], v1 offset:32768
	ds_read_b128 v[142:145], v150 offset:32768
	ds_read_b128 v[146:149], v1 offset:34816
	ds_read_b128 v[154:157], v150 offset:34816
	ds_read_b128 v[158:161], v1 offset:49152
	ds_read_b128 v[162:165], v150 offset:49152
	ds_read_b128 v[166:169], v1 offset:51200
	ds_read_b128 v[170:173], v150 offset:51200
	s_add_u32 s30, s44, 0x80000
	s_addc_u32 s31, s45, 0
	s_mov_b32 m0, s48
	ds_read_b128 v[174:177], v151 offset:32768
	ds_read_b128 v[184:187], v151 offset:34816
	ds_read_b128 v[188:191], v152 offset:32768
	ds_read_b128 v[192:195], v152 offset:34816
	ds_read_b128 v[196:199], v151 offset:36864
	ds_read_b128 v[200:203], v151 offset:38912
	ds_read_b128 v[204:207], v152 offset:36864
	ds_read_b128 v[208:211], v152 offset:38912
	global_load_lds_dwordx4 v136, s[30:31]
	s_mov_b32 m0, s49
	s_nop 0
	global_load_lds_dwordx4 v134, s[30:31]
	s_waitcnt vmcnt(8)
	s_waitcnt lgkmcnt(0)
	s_barrier
	s_setprio 1
	s_waitcnt lgkmcnt(0)
	v_mfma_f32_16x16x32_bf16 v[128:131], v[138:141], v[174:177], v[128:131]
	v_mfma_f32_16x16x32_bf16 v[124:127], v[146:149], v[174:177], v[124:127]
	v_mfma_f32_16x16x32_bf16 v[112:115], v[138:141], v[184:187], v[112:115]
	v_mfma_f32_16x16x32_bf16 v[108:111], v[146:149], v[184:187], v[108:111]
	v_mfma_f32_16x16x32_bf16 v[96:99], v[138:141], v[196:199], v[96:99]
	v_mfma_f32_16x16x32_bf16 v[92:95], v[146:149], v[196:199], v[92:95]
	v_mfma_f32_16x16x32_bf16 v[80:83], v[138:141], v[200:203], v[80:83]
	v_mfma_f32_16x16x32_bf16 v[76:79], v[146:149], v[200:203], v[76:79]
	v_mfma_f32_16x16x32_bf16 v[128:131], v[142:145], v[188:191], v[128:131]
	v_mfma_f32_16x16x32_bf16 v[124:127], v[154:157], v[188:191], v[124:127]
	v_mfma_f32_16x16x32_bf16 v[112:115], v[142:145], v[192:195], v[112:115]
	v_mfma_f32_16x16x32_bf16 v[108:111], v[154:157], v[192:195], v[108:111]
	v_mfma_f32_16x16x32_bf16 v[96:99], v[142:145], v[204:207], v[96:99]
	v_mfma_f32_16x16x32_bf16 v[92:95], v[154:157], v[204:207], v[92:95]
	v_mfma_f32_16x16x32_bf16 v[80:83], v[142:145], v[208:211], v[80:83]
	v_mfma_f32_16x16x32_bf16 v[76:79], v[154:157], v[208:211], v[76:79]
	s_setprio 0
	s_setprio 1
	v_mfma_f32_16x16x32_bf16 v[120:123], v[158:161], v[174:177], v[120:123]
	v_mfma_f32_16x16x32_bf16 v[116:119], v[166:169], v[174:177], v[116:119]
	v_mfma_f32_16x16x32_bf16 v[104:107], v[158:161], v[184:187], v[104:107]
	v_mfma_f32_16x16x32_bf16 v[100:103], v[166:169], v[184:187], v[100:103]
	v_mfma_f32_16x16x32_bf16 v[88:91], v[158:161], v[196:199], v[88:91]
	v_mfma_f32_16x16x32_bf16 v[84:87], v[166:169], v[196:199], v[84:87]
	v_mfma_f32_16x16x32_bf16 v[72:75], v[158:161], v[200:203], v[72:75]
	v_mfma_f32_16x16x32_bf16 v[68:71], v[166:169], v[200:203], v[68:71]
	v_mfma_f32_16x16x32_bf16 v[120:123], v[162:165], v[188:191], v[120:123]
	v_mfma_f32_16x16x32_bf16 v[116:119], v[170:173], v[188:191], v[116:119]
	v_mfma_f32_16x16x32_bf16 v[104:107], v[162:165], v[192:195], v[104:107]
	v_mfma_f32_16x16x32_bf16 v[100:103], v[170:173], v[192:195], v[100:103]
	v_mfma_f32_16x16x32_bf16 v[88:91], v[162:165], v[204:207], v[88:91]
	v_mfma_f32_16x16x32_bf16 v[84:87], v[170:173], v[204:207], v[84:87]
	v_mfma_f32_16x16x32_bf16 v[72:75], v[162:165], v[208:211], v[72:75]
	v_mfma_f32_16x16x32_bf16 v[68:71], v[170:173], v[208:211], v[68:71]
	s_setprio 0
	s_barrier
	s_add_i32 s25, s25, s33
	s_add_i32 m0, s25, 0xffffff80
	ds_read_b128 v[174:177], v151 offset:49152
	ds_read_b128 v[184:187], v151 offset:51200
	ds_read_b128 v[188:191], v152 offset:49152
	ds_read_b128 v[192:195], v152 offset:51200
	ds_read_b128 v[196:199], v151 offset:53248
	ds_read_b128 v[200:203], v151 offset:55296
	ds_read_b128 v[204:207], v152 offset:53248
	ds_read_b128 v[208:211], v152 offset:55296
	global_load_lds_dwordx4 v34, s[28:29] offset:128
	s_add_i32 m0, s25, 0x1f80
	s_mov_b64 s[98:99], s[28:29]
	s_add_u32 s28, s28, 0x80080
	s_addc_u32 s29, s29, 0
	s_add_i32 s25, s34, s33
	global_load_lds_dwordx4 v132, s[98:99] offset:128
	s_mov_b32 m0, s25
	s_nop 0
	global_load_lds_dwordx4 v34, s[28:29]
	s_add_i32 m0, s25, 0x2000
	s_nop 0
	global_load_lds_dwordx4 v132, s[28:29]
	s_add_i32 m0, s52, 0xffffff80
	s_nop 0
	global_load_lds_dwordx4 v136, s[44:45] offset:128
	s_add_i32 m0, s53, 0xffffff80
	s_nop 0
	global_load_lds_dwordx4 v134, s[44:45] offset:128
	s_waitcnt vmcnt(8)
	s_waitcnt lgkmcnt(0)
	s_barrier
	s_setprio 1
	s_waitcnt lgkmcnt(0)
	v_mfma_f32_16x16x32_bf16 v[64:67], v[138:141], v[174:177], v[64:67]
	v_mfma_f32_16x16x32_bf16 v[60:63], v[146:149], v[174:177], v[60:63]
	v_mfma_f32_16x16x32_bf16 v[48:51], v[138:141], v[184:187], v[48:51]
	v_mfma_f32_16x16x32_bf16 v[44:47], v[146:149], v[184:187], v[44:47]
	v_mfma_f32_16x16x32_bf16 v[30:33], v[138:141], v[196:199], v[30:33]
	v_mfma_f32_16x16x32_bf16 v[26:29], v[146:149], v[196:199], v[26:29]
	v_mfma_f32_16x16x32_bf16 v[14:17], v[138:141], v[200:203], v[14:17]
	v_mfma_f32_16x16x32_bf16 v[10:13], v[146:149], v[200:203], v[10:13]
	v_mfma_f32_16x16x32_bf16 v[64:67], v[142:145], v[188:191], v[64:67]
	v_mfma_f32_16x16x32_bf16 v[60:63], v[154:157], v[188:191], v[60:63]
	v_mfma_f32_16x16x32_bf16 v[48:51], v[142:145], v[192:195], v[48:51]
	v_mfma_f32_16x16x32_bf16 v[44:47], v[154:157], v[192:195], v[44:47]
	v_mfma_f32_16x16x32_bf16 v[30:33], v[142:145], v[204:207], v[30:33]
	v_mfma_f32_16x16x32_bf16 v[26:29], v[154:157], v[204:207], v[26:29]
	v_mfma_f32_16x16x32_bf16 v[14:17], v[142:145], v[208:211], v[14:17]
	v_mfma_f32_16x16x32_bf16 v[10:13], v[154:157], v[208:211], v[10:13]
	s_setprio 0
	s_setprio 1
	v_mfma_f32_16x16x32_bf16 v[56:59], v[158:161], v[174:177], v[56:59]
	v_mfma_f32_16x16x32_bf16 v[52:55], v[166:169], v[174:177], v[52:55]
	v_mfma_f32_16x16x32_bf16 v[40:43], v[158:161], v[184:187], v[40:43]
	v_mfma_f32_16x16x32_bf16 v[36:39], v[166:169], v[184:187], v[36:39]
	v_mfma_f32_16x16x32_bf16 v[22:25], v[158:161], v[196:199], v[22:25]
	v_mfma_f32_16x16x32_bf16 v[18:21], v[166:169], v[196:199], v[18:21]
	v_mfma_f32_16x16x32_bf16 v[6:9], v[158:161], v[200:203], v[6:9]
	v_mfma_f32_16x16x32_bf16 v[2:5], v[166:169], v[200:203], v[2:5]
	v_mfma_f32_16x16x32_bf16 v[56:59], v[162:165], v[188:191], v[56:59]
	v_mfma_f32_16x16x32_bf16 v[52:55], v[170:173], v[188:191], v[52:55]
	v_mfma_f32_16x16x32_bf16 v[40:43], v[162:165], v[192:195], v[40:43]
	v_mfma_f32_16x16x32_bf16 v[36:39], v[170:173], v[192:195], v[36:39]
	v_mfma_f32_16x16x32_bf16 v[22:25], v[162:165], v[204:207], v[22:25]
	v_mfma_f32_16x16x32_bf16 v[18:21], v[170:173], v[204:207], v[18:21]
	v_mfma_f32_16x16x32_bf16 v[6:9], v[162:165], v[208:211], v[6:9]
	v_mfma_f32_16x16x32_bf16 v[2:5], v[170:173], v[208:211], v[2:5]
	s_setprio 0
	s_barrier
	s_add_i32 s24, s24, 2
	s_add_u32 s8, s8, 0x100
	s_addc_u32 s9, s9, 0
	s_add_u32 s21, s21, 0x100
	s_addc_u32 s23, s23, 0
	s_cmp_gt_u32 s24, 29
	s_cbranch_scc1 .Lpeel_done_P4
.LBB0_1023:
	s_add_u32 s25, s8, 0xfff80080
	s_addc_u32 s28, s9, -1
	s_add_i32 s30, 0, 0x10000
	s_cmp_eq_u32 s24, 28
	s_cselect_b32 s45, s12, s28
	s_cselect_b32 s44, s13, s25
	s_cselect_b32 s29, s19, s23
	s_cselect_b32 s28, s20, s21
	s_add_i32 s25, 0, 0x14000
	ds_read_b128 v[138:141], v1
	ds_read_b128 v[142:145], v150
	ds_read_b128 v[146:149], v1 offset:2048
	ds_read_b128 v[154:157], v150 offset:2048
	ds_read_b128 v[158:161], v1 offset:16384
	ds_read_b128 v[162:165], v150 offset:16384
	ds_read_b128 v[166:169], v1 offset:18432
	ds_read_b128 v[170:173], v150 offset:18432
	s_add_i32 m0, s46, 0xc000
	ds_read_b128 v[174:177], v151
	ds_read_b128 v[184:187], v151 offset:2048
	ds_read_b128 v[188:191], v152
	ds_read_b128 v[192:195], v152 offset:2048
	ds_read_b128 v[196:199], v151 offset:4096
	ds_read_b128 v[200:203], v151 offset:6144
	ds_read_b128 v[204:207], v152 offset:4096
	ds_read_b128 v[208:211], v152 offset:6144
	global_load_lds_dwordx4 v136, s[8:9]
	s_add_i32 m0, s46, 0xe000
	s_nop 0
	global_load_lds_dwordx4 v134, s[8:9]
	s_waitcnt vmcnt(8)
	s_waitcnt lgkmcnt(0)
	s_barrier
	s_setprio 1
	s_waitcnt lgkmcnt(0)
	v_mfma_f32_16x16x32_bf16 v[128:131], v[138:141], v[174:177], v[128:131]
	v_mfma_f32_16x16x32_bf16 v[124:127], v[146:149], v[174:177], v[124:127]
	v_mfma_f32_16x16x32_bf16 v[112:115], v[138:141], v[184:187], v[112:115]
	v_mfma_f32_16x16x32_bf16 v[108:111], v[146:149], v[184:187], v[108:111]
	v_mfma_f32_16x16x32_bf16 v[96:99], v[138:141], v[196:199], v[96:99]
	v_mfma_f32_16x16x32_bf16 v[92:95], v[146:149], v[196:199], v[92:95]
	v_mfma_f32_16x16x32_bf16 v[80:83], v[138:141], v[200:203], v[80:83]
	v_mfma_f32_16x16x32_bf16 v[76:79], v[146:149], v[200:203], v[76:79]
	v_mfma_f32_16x16x32_bf16 v[128:131], v[142:145], v[188:191], v[128:131]
	v_mfma_f32_16x16x32_bf16 v[124:127], v[154:157], v[188:191], v[124:127]
	v_mfma_f32_16x16x32_bf16 v[112:115], v[142:145], v[192:195], v[112:115]
	v_mfma_f32_16x16x32_bf16 v[108:111], v[154:157], v[192:195], v[108:111]
	v_mfma_f32_16x16x32_bf16 v[96:99], v[142:145], v[204:207], v[96:99]
	v_mfma_f32_16x16x32_bf16 v[92:95], v[154:157], v[204:207], v[92:95]
	v_mfma_f32_16x16x32_bf16 v[80:83], v[142:145], v[208:211], v[80:83]
	v_mfma_f32_16x16x32_bf16 v[76:79], v[154:157], v[208:211], v[76:79]
	s_setprio 0
	s_setprio 1
	v_mfma_f32_16x16x32_bf16 v[120:123], v[158:161], v[174:177], v[120:123]
	v_mfma_f32_16x16x32_bf16 v[116:119], v[166:169], v[174:177], v[116:119]
	v_mfma_f32_16x16x32_bf16 v[104:107], v[158:161], v[184:187], v[104:107]
	v_mfma_f32_16x16x32_bf16 v[100:103], v[166:169], v[184:187], v[100:103]
	v_mfma_f32_16x16x32_bf16 v[88:91], v[158:161], v[196:199], v[88:91]
	v_mfma_f32_16x16x32_bf16 v[84:87], v[166:169], v[196:199], v[84:87]
	v_mfma_f32_16x16x32_bf16 v[72:75], v[158:161], v[200:203], v[72:75]
	v_mfma_f32_16x16x32_bf16 v[68:71], v[166:169], v[200:203], v[68:71]
	v_mfma_f32_16x16x32_bf16 v[120:123], v[162:165], v[188:191], v[120:123]
	v_mfma_f32_16x16x32_bf16 v[116:119], v[170:173], v[188:191], v[116:119]
	v_mfma_f32_16x16x32_bf16 v[104:107], v[162:165], v[192:195], v[104:107]
	v_mfma_f32_16x16x32_bf16 v[100:103], v[170:173], v[192:195], v[100:103]
	v_mfma_f32_16x16x32_bf16 v[88:91], v[162:165], v[204:207], v[88:91]
	v_mfma_f32_16x16x32_bf16 v[84:87], v[170:173], v[204:207], v[84:87]
	v_mfma_f32_16x16x32_bf16 v[72:75], v[162:165], v[208:211], v[72:75]
	v_mfma_f32_16x16x32_bf16 v[68:71], v[170:173], v[208:211], v[68:71]
	s_setprio 0
	s_barrier
	s_add_i32 s30, s30, s33
	s_mov_b32 m0, s30
	ds_read_b128 v[174:177], v151 offset:16384
	ds_read_b128 v[184:187], v151 offset:18432
	ds_read_b128 v[188:191], v152 offset:16384
	ds_read_b128 v[192:195], v152 offset:18432
	ds_read_b128 v[196:199], v151 offset:20480
	ds_read_b128 v[200:203], v151 offset:22528
	ds_read_b128 v[204:207], v152 offset:20480
	ds_read_b128 v[208:211], v152 offset:22528
	global_load_lds_dwordx4 v34, s[28:29]
	s_add_i32 m0, s30, 0x2000
	s_add_u32 s30, s28, 0x80000
	s_addc_u32 s31, s29, 0
	s_add_i32 s25, s25, s33
	global_load_lds_dwordx4 v132, s[28:29]
	s_mov_b32 m0, s25
	s_nop 0
	global_load_lds_dwordx4 v34, s[30:31]
	s_add_i32 m0, s25, 0x2000
	s_nop 0
	global_load_lds_dwordx4 v132, s[30:31]
	s_mov_b32 m0, s46
	s_nop 0
	global_load_lds_dwordx4 v136, s[44:45]
	s_mov_b32 m0, s47
	s_nop 0
	global_load_lds_dwordx4 v134, s[44:45]
	s_waitcnt vmcnt(8)
	s_waitcnt lgkmcnt(0)
	s_barrier
	s_setprio 1
	s_waitcnt lgkmcnt(0)
	v_mfma_f32_16x16x32_bf16 v[64:67], v[138:141], v[174:177], v[64:67]
	v_mfma_f32_16x16x32_bf16 v[60:63], v[146:149], v[174:177], v[60:63]
	v_mfma_f32_16x16x32_bf16 v[48:51], v[138:141], v[184:187], v[48:51]
	v_mfma_f32_16x16x32_bf16 v[44:47], v[146:149], v[184:187], v[44:47]
	v_mfma_f32_16x16x32_bf16 v[30:33], v[138:141], v[196:199], v[30:33]
	v_mfma_f32_16x16x32_bf16 v[26:29], v[146:149], v[196:199], v[26:29]
	v_mfma_f32_16x16x32_bf16 v[14:17], v[138:141], v[200:203], v[14:17]
	v_mfma_f32_16x16x32_bf16 v[10:13], v[146:149], v[200:203], v[10:13]
	v_mfma_f32_16x16x32_bf16 v[64:67], v[142:145], v[188:191], v[64:67]
	v_mfma_f32_16x16x32_bf16 v[60:63], v[154:157], v[188:191], v[60:63]
	v_mfma_f32_16x16x32_bf16 v[48:51], v[142:145], v[192:195], v[48:51]
	v_mfma_f32_16x16x32_bf16 v[44:47], v[154:157], v[192:195], v[44:47]
	v_mfma_f32_16x16x32_bf16 v[30:33], v[142:145], v[204:207], v[30:33]
	v_mfma_f32_16x16x32_bf16 v[26:29], v[154:157], v[204:207], v[26:29]
	v_mfma_f32_16x16x32_bf16 v[14:17], v[142:145], v[208:211], v[14:17]
	v_mfma_f32_16x16x32_bf16 v[10:13], v[154:157], v[208:211], v[10:13]
	s_setprio 0
	s_setprio 1
	v_mfma_f32_16x16x32_bf16 v[56:59], v[158:161], v[174:177], v[56:59]
	v_mfma_f32_16x16x32_bf16 v[52:55], v[166:169], v[174:177], v[52:55]
	v_mfma_f32_16x16x32_bf16 v[40:43], v[158:161], v[184:187], v[40:43]
	v_mfma_f32_16x16x32_bf16 v[36:39], v[166:169], v[184:187], v[36:39]
	v_mfma_f32_16x16x32_bf16 v[22:25], v[158:161], v[196:199], v[22:25]
	v_mfma_f32_16x16x32_bf16 v[18:21], v[166:169], v[196:199], v[18:21]
	v_mfma_f32_16x16x32_bf16 v[6:9], v[158:161], v[200:203], v[6:9]
	v_mfma_f32_16x16x32_bf16 v[2:5], v[166:169], v[200:203], v[2:5]
	v_mfma_f32_16x16x32_bf16 v[56:59], v[162:165], v[188:191], v[56:59]
	v_mfma_f32_16x16x32_bf16 v[52:55], v[170:173], v[188:191], v[52:55]
	v_mfma_f32_16x16x32_bf16 v[40:43], v[162:165], v[192:195], v[40:43]
	v_mfma_f32_16x16x32_bf16 v[36:39], v[170:173], v[192:195], v[36:39]
	v_mfma_f32_16x16x32_bf16 v[22:25], v[162:165], v[204:207], v[22:25]
	v_mfma_f32_16x16x32_bf16 v[18:21], v[170:173], v[204:207], v[18:21]
	v_mfma_f32_16x16x32_bf16 v[6:9], v[162:165], v[208:211], v[6:9]
	v_mfma_f32_16x16x32_bf16 v[2:5], v[170:173], v[208:211], v[2:5]
	s_setprio 0
	s_barrier
	s_add_i32 s25, 0, 0x18000
	s_add_i32 s34, 0, 0x1c000
	ds_read_b128 v[138:141], v1 offset:32768
	ds_read_b128 v[142:145], v150 offset:32768
	ds_read_b128 v[146:149], v1 offset:34816
	ds_read_b128 v[154:157], v150 offset:34816
	ds_read_b128 v[158:161], v1 offset:49152
	ds_read_b128 v[162:165], v150 offset:49152
	ds_read_b128 v[166:169], v1 offset:51200
	ds_read_b128 v[170:173], v150 offset:51200
	s_add_u32 s30, s44, 0x80000
	s_addc_u32 s31, s45, 0
	s_mov_b32 m0, s48
	ds_read_b128 v[174:177], v151 offset:32768
	ds_read_b128 v[184:187], v151 offset:34816
	ds_read_b128 v[188:191], v152 offset:32768
	ds_read_b128 v[192:195], v152 offset:34816
	ds_read_b128 v[196:199], v151 offset:36864
	ds_read_b128 v[200:203], v151 offset:38912
	ds_read_b128 v[204:207], v152 offset:36864
	ds_read_b128 v[208:211], v152 offset:38912
	global_load_lds_dwordx4 v136, s[30:31]
	s_mov_b32 m0, s49
	s_nop 0
	global_load_lds_dwordx4 v134, s[30:31]
	s_waitcnt vmcnt(8)
	s_waitcnt lgkmcnt(0)
	s_barrier
	s_setprio 1
	s_waitcnt lgkmcnt(0)
	v_mfma_f32_16x16x32_bf16 v[128:131], v[138:141], v[174:177], v[128:131]
	v_mfma_f32_16x16x32_bf16 v[124:127], v[146:149], v[174:177], v[124:127]
	v_mfma_f32_16x16x32_bf16 v[112:115], v[138:141], v[184:187], v[112:115]
	v_mfma_f32_16x16x32_bf16 v[108:111], v[146:149], v[184:187], v[108:111]
	v_mfma_f32_16x16x32_bf16 v[96:99], v[138:141], v[196:199], v[96:99]
	v_mfma_f32_16x16x32_bf16 v[92:95], v[146:149], v[196:199], v[92:95]
	v_mfma_f32_16x16x32_bf16 v[80:83], v[138:141], v[200:203], v[80:83]
	v_mfma_f32_16x16x32_bf16 v[76:79], v[146:149], v[200:203], v[76:79]
	v_mfma_f32_16x16x32_bf16 v[128:131], v[142:145], v[188:191], v[128:131]
	v_mfma_f32_16x16x32_bf16 v[124:127], v[154:157], v[188:191], v[124:127]
	v_mfma_f32_16x16x32_bf16 v[112:115], v[142:145], v[192:195], v[112:115]
	v_mfma_f32_16x16x32_bf16 v[108:111], v[154:157], v[192:195], v[108:111]
	v_mfma_f32_16x16x32_bf16 v[96:99], v[142:145], v[204:207], v[96:99]
	v_mfma_f32_16x16x32_bf16 v[92:95], v[154:157], v[204:207], v[92:95]
	v_mfma_f32_16x16x32_bf16 v[80:83], v[142:145], v[208:211], v[80:83]
	v_mfma_f32_16x16x32_bf16 v[76:79], v[154:157], v[208:211], v[76:79]
	s_setprio 0
	s_setprio 1
	v_mfma_f32_16x16x32_bf16 v[120:123], v[158:161], v[174:177], v[120:123]
	v_mfma_f32_16x16x32_bf16 v[116:119], v[166:169], v[174:177], v[116:119]
	v_mfma_f32_16x16x32_bf16 v[104:107], v[158:161], v[184:187], v[104:107]
	v_mfma_f32_16x16x32_bf16 v[100:103], v[166:169], v[184:187], v[100:103]
	v_mfma_f32_16x16x32_bf16 v[88:91], v[158:161], v[196:199], v[88:91]
	v_mfma_f32_16x16x32_bf16 v[84:87], v[166:169], v[196:199], v[84:87]
	v_mfma_f32_16x16x32_bf16 v[72:75], v[158:161], v[200:203], v[72:75]
	v_mfma_f32_16x16x32_bf16 v[68:71], v[166:169], v[200:203], v[68:71]
	v_mfma_f32_16x16x32_bf16 v[120:123], v[162:165], v[188:191], v[120:123]
	v_mfma_f32_16x16x32_bf16 v[116:119], v[170:173], v[188:191], v[116:119]
	v_mfma_f32_16x16x32_bf16 v[104:107], v[162:165], v[192:195], v[104:107]
	v_mfma_f32_16x16x32_bf16 v[100:103], v[170:173], v[192:195], v[100:103]
	v_mfma_f32_16x16x32_bf16 v[88:91], v[162:165], v[204:207], v[88:91]
	v_mfma_f32_16x16x32_bf16 v[84:87], v[170:173], v[204:207], v[84:87]
	v_mfma_f32_16x16x32_bf16 v[72:75], v[162:165], v[208:211], v[72:75]
	v_mfma_f32_16x16x32_bf16 v[68:71], v[170:173], v[208:211], v[68:71]
	s_setprio 0
	s_barrier
	s_add_i32 s25, s25, s33
	s_add_i32 m0, s25, 0xffffff80
	ds_read_b128 v[174:177], v151 offset:49152
	ds_read_b128 v[184:187], v151 offset:51200
	ds_read_b128 v[188:191], v152 offset:49152
	ds_read_b128 v[192:195], v152 offset:51200
	ds_read_b128 v[196:199], v151 offset:53248
	ds_read_b128 v[200:203], v151 offset:55296
	ds_read_b128 v[204:207], v152 offset:53248
	ds_read_b128 v[208:211], v152 offset:55296
	global_load_lds_dwordx4 v34, s[28:29] offset:128
	s_add_i32 m0, s25, 0x1f80
	s_mov_b64 s[98:99], s[28:29]
	s_add_u32 s28, s28, 0x80080
	s_addc_u32 s29, s29, 0
	s_add_i32 s25, s34, s33
	global_load_lds_dwordx4 v132, s[98:99] offset:128
	s_mov_b32 m0, s25
	s_nop 0
	global_load_lds_dwordx4 v34, s[28:29]
	s_add_i32 m0, s25, 0x2000
	s_nop 0
	global_load_lds_dwordx4 v132, s[28:29]
	s_add_i32 m0, s52, 0xffffff80
	s_nop 0
	global_load_lds_dwordx4 v136, s[44:45] offset:128
	s_add_i32 m0, s53, 0xffffff80
	s_nop 0
	global_load_lds_dwordx4 v134, s[44:45] offset:128
	s_waitcnt vmcnt(8)
	s_waitcnt lgkmcnt(0)
	s_barrier
	s_setprio 1
	s_waitcnt lgkmcnt(0)
	v_mfma_f32_16x16x32_bf16 v[64:67], v[138:141], v[174:177], v[64:67]
	v_mfma_f32_16x16x32_bf16 v[60:63], v[146:149], v[174:177], v[60:63]
	v_mfma_f32_16x16x32_bf16 v[48:51], v[138:141], v[184:187], v[48:51]
	v_mfma_f32_16x16x32_bf16 v[44:47], v[146:149], v[184:187], v[44:47]
	v_mfma_f32_16x16x32_bf16 v[30:33], v[138:141], v[196:199], v[30:33]
	v_mfma_f32_16x16x32_bf16 v[26:29], v[146:149], v[196:199], v[26:29]
	v_mfma_f32_16x16x32_bf16 v[14:17], v[138:141], v[200:203], v[14:17]
	v_mfma_f32_16x16x32_bf16 v[10:13], v[146:149], v[200:203], v[10:13]
	v_mfma_f32_16x16x32_bf16 v[64:67], v[142:145], v[188:191], v[64:67]
	v_mfma_f32_16x16x32_bf16 v[60:63], v[154:157], v[188:191], v[60:63]
	v_mfma_f32_16x16x32_bf16 v[48:51], v[142:145], v[192:195], v[48:51]
	v_mfma_f32_16x16x32_bf16 v[44:47], v[154:157], v[192:195], v[44:47]
	v_mfma_f32_16x16x32_bf16 v[30:33], v[142:145], v[204:207], v[30:33]
	v_mfma_f32_16x16x32_bf16 v[26:29], v[154:157], v[204:207], v[26:29]
	v_mfma_f32_16x16x32_bf16 v[14:17], v[142:145], v[208:211], v[14:17]
	v_mfma_f32_16x16x32_bf16 v[10:13], v[154:157], v[208:211], v[10:13]
	s_setprio 0
	s_setprio 1
	v_mfma_f32_16x16x32_bf16 v[56:59], v[158:161], v[174:177], v[56:59]
	v_mfma_f32_16x16x32_bf16 v[52:55], v[166:169], v[174:177], v[52:55]
	v_mfma_f32_16x16x32_bf16 v[40:43], v[158:161], v[184:187], v[40:43]
	v_mfma_f32_16x16x32_bf16 v[36:39], v[166:169], v[184:187], v[36:39]
	v_mfma_f32_16x16x32_bf16 v[22:25], v[158:161], v[196:199], v[22:25]
	v_mfma_f32_16x16x32_bf16 v[18:21], v[166:169], v[196:199], v[18:21]
	v_mfma_f32_16x16x32_bf16 v[6:9], v[158:161], v[200:203], v[6:9]
	v_mfma_f32_16x16x32_bf16 v[2:5], v[166:169], v[200:203], v[2:5]
	v_mfma_f32_16x16x32_bf16 v[56:59], v[162:165], v[188:191], v[56:59]
	v_mfma_f32_16x16x32_bf16 v[52:55], v[170:173], v[188:191], v[52:55]
	v_mfma_f32_16x16x32_bf16 v[40:43], v[162:165], v[192:195], v[40:43]
	v_mfma_f32_16x16x32_bf16 v[36:39], v[170:173], v[192:195], v[36:39]
	v_mfma_f32_16x16x32_bf16 v[22:25], v[162:165], v[204:207], v[22:25]
	v_mfma_f32_16x16x32_bf16 v[18:21], v[170:173], v[204:207], v[18:21]
	v_mfma_f32_16x16x32_bf16 v[6:9], v[162:165], v[208:211], v[6:9]
	v_mfma_f32_16x16x32_bf16 v[2:5], v[170:173], v[208:211], v[2:5]
	s_setprio 0
	s_barrier
	s_add_i32 s24, s24, 2
	s_add_u32 s8, s8, 0x100
	s_addc_u32 s9, s9, 0
	s_add_u32 s21, s21, 0x100
	s_addc_u32 s23, s23, 0
	s_cmp_gt_u32 s24, 29
	s_cbranch_scc0 .LBB0_1023

.LBB0_1113:
	s_ashr_i32 s19, s18, 31
	s_lshl_b64 s[20:21], s[18:19], 20
	v_readlane_b32 s22, v254, 38
	v_readlane_b32 s23, v254, 39
	s_add_u32 s22, s22, s20
	s_addc_u32 s23, s23, s21
	s_and_b64 s[20:21], s[38:39], exec
	s_cselect_b32 s13, s23, s9
	s_cselect_b32 s19, s22, s8
	s_ashr_i32 s11, s10, 31
	s_lshl_b64 s[20:21], s[10:11], 20
	v_readlane_b32 s30, v254, 8
	v_readlane_b32 s31, v254, 9
	s_add_u32 s40, s30, s20
	s_addc_u32 s41, s31, s21
	v_mov_b32_e32 v2, v0
	s_and_b64 s[20:21], s[38:39], exec
	s_cselect_b32 s20, s41, s29
	s_cselect_b32 s21, s40, s28
	s_lshl_b32 s11, s24, 8
	v_and_or_b32 v2, v2, 63, s50
	v_or_b32_e32 v2, s11, v2
	v_ashrrev_i32_e32 v3, 31, v2
	v_readlane_b32 s24, v252, 61
	v_lshlrev_b64 v[2:3], 5, v[2:3]
	v_readlane_b32 s25, v252, 62
	s_add_u32 s8, s8, 0x80080
	s_addc_u32 s9, s9, 0
	v_lshl_add_u64 v[2:3], s[24:25], 0, v[2:3]
	global_load_dwordx4 v[116:119], v[2:3], off offset:16
	global_load_dwordx4 v[120:123], v[2:3], off
	s_add_u32 s24, s28, 0x100
	s_addc_u32 s25, s29, 0
	s_mov_b32 s30, -2
	v_readlane_b32 s57, v255, 20
	v_readlane_b32 s58, v255, 21
	v_readlane_b32 s59, v255, 22
	v_readlane_b32 s60, v255, 23
	s_mov_b64 s[62:63], 0x80
	s_add_u32 s28, s8, 0xfff80080
	s_addc_u32 s29, s9, -1
	s_add_i32 s31, 0, 0x10000
	s_cmp_eq_u32 s30, 28
	s_cselect_b32 s43, s13, s29
	s_cselect_b32 s42, s19, s28
	ds_read_b128 v[150:153], v1
	ds_read_b128 v[154:157], v146
	s_cselect_b32 s29, s20, s25
	s_cselect_b32 s28, s21, s24
	s_add_i32 s56, 0, 0x14000
	ds_read_b128 v[158:161], v1 offset:2048
	ds_read_b128 v[162:165], v146 offset:2048
	ds_read_b128 v[166:169], v1 offset:16384
	ds_read_b128 v[170:173], v146 offset:16384
	ds_read_b128 v[174:177], v1 offset:18432
	ds_read_b128 v[184:187], v146 offset:18432
	s_add_i32 m0, s34, 0xc000
	ds_read_b128 v[188:191], v147
	ds_read_b128 v[192:195], v147 offset:2048
	ds_read_b128 v[196:199], v148
	ds_read_b128 v[200:203], v148 offset:2048
	ds_read_b128 v[204:207], v147 offset:4096
	ds_read_b128 v[208:211], v147 offset:6144
	ds_read_b128 v[224:227], v148 offset:4096
	ds_read_b128 v[228:231], v148 offset:6144
	global_load_lds_dwordx4 v144, s[8:9]
	s_add_i32 m0, s34, 0xe000
	s_nop 0
	global_load_lds_dwordx4 v142, s[8:9]
	s_waitcnt vmcnt(8)
	s_waitcnt lgkmcnt(0)
	s_barrier
	s_setprio 1
	s_waitcnt lgkmcnt(0)
	v_mfma_f32_16x16x32_bf16 v[132:135], v[150:153], v[188:191], 0
	v_mfma_f32_16x16x32_bf16 v[124:127], v[158:161], v[188:191], 0
	v_mfma_f32_16x16x32_bf16 v[108:111], v[150:153], v[192:195], 0
	v_mfma_f32_16x16x32_bf16 v[100:103], v[158:161], v[192:195], 0
	v_mfma_f32_16x16x32_bf16 v[92:95], v[150:153], v[204:207], 0
	v_mfma_f32_16x16x32_bf16 v[84:87], v[158:161], v[204:207], 0
	v_mfma_f32_16x16x32_bf16 v[76:79], v[150:153], v[208:211], 0
	v_mfma_f32_16x16x32_bf16 v[68:71], v[158:161], v[208:211], 0
	v_mfma_f32_16x16x32_bf16 v[132:135], v[154:157], v[196:199], v[132:135]
	v_mfma_f32_16x16x32_bf16 v[124:127], v[162:165], v[196:199], v[124:127]
	v_mfma_f32_16x16x32_bf16 v[108:111], v[154:157], v[200:203], v[108:111]
	v_mfma_f32_16x16x32_bf16 v[100:103], v[162:165], v[200:203], v[100:103]
	v_mfma_f32_16x16x32_bf16 v[92:95], v[154:157], v[224:227], v[92:95]
	v_mfma_f32_16x16x32_bf16 v[84:87], v[162:165], v[224:227], v[84:87]
	v_mfma_f32_16x16x32_bf16 v[76:79], v[154:157], v[228:231], v[76:79]
	v_mfma_f32_16x16x32_bf16 v[68:71], v[162:165], v[228:231], v[68:71]
	s_setprio 0
	s_setprio 1
	v_mfma_f32_16x16x32_bf16 v[136:139], v[166:169], v[188:191], 0
	v_mfma_f32_16x16x32_bf16 v[128:131], v[174:177], v[188:191], 0
	v_mfma_f32_16x16x32_bf16 v[112:115], v[166:169], v[192:195], 0
	v_mfma_f32_16x16x32_bf16 v[104:107], v[174:177], v[192:195], 0
	v_mfma_f32_16x16x32_bf16 v[96:99], v[166:169], v[204:207], 0
	v_mfma_f32_16x16x32_bf16 v[88:91], v[174:177], v[204:207], 0
	v_mfma_f32_16x16x32_bf16 v[80:83], v[166:169], v[208:211], 0
	v_mfma_f32_16x16x32_bf16 v[72:75], v[174:177], v[208:211], 0
	v_mfma_f32_16x16x32_bf16 v[136:139], v[170:173], v[196:199], v[136:139]
	v_mfma_f32_16x16x32_bf16 v[128:131], v[184:187], v[196:199], v[128:131]
	v_mfma_f32_16x16x32_bf16 v[112:115], v[170:173], v[200:203], v[112:115]
	v_mfma_f32_16x16x32_bf16 v[104:107], v[184:187], v[200:203], v[104:107]
	v_mfma_f32_16x16x32_bf16 v[96:99], v[170:173], v[224:227], v[96:99]
	v_mfma_f32_16x16x32_bf16 v[88:91], v[184:187], v[224:227], v[88:91]
	v_mfma_f32_16x16x32_bf16 v[80:83], v[170:173], v[228:231], v[80:83]
	v_mfma_f32_16x16x32_bf16 v[72:75], v[184:187], v[228:231], v[72:75]
	s_setprio 0
	s_barrier
	s_add_i32 s31, s31, s33
	s_mov_b32 m0, s31
	ds_read_b128 v[188:191], v147 offset:16384
	ds_read_b128 v[192:195], v147 offset:18432
	ds_read_b128 v[196:199], v148 offset:16384
	ds_read_b128 v[200:203], v148 offset:18432
	ds_read_b128 v[204:207], v147 offset:20480
	ds_read_b128 v[208:211], v147 offset:22528
	ds_read_b128 v[224:227], v148 offset:20480
	ds_read_b128 v[228:231], v148 offset:22528
	global_load_lds_dwordx4 v34, s[28:29]
	s_add_i32 m0, s31, 0x2000
	s_add_u32 s54, s28, 0x80000
	s_addc_u32 s55, s29, 0
	s_add_i32 s31, s56, s33
	global_load_lds_dwordx4 v140, s[28:29]
	s_mov_b32 m0, s31
	s_nop 0
	global_load_lds_dwordx4 v34, s[54:55]
	s_add_i32 m0, s31, 0x2000
	s_nop 0
	global_load_lds_dwordx4 v140, s[54:55]
	s_mov_b32 m0, s34
	s_nop 0
	global_load_lds_dwordx4 v144, s[42:43]
	s_mov_b32 m0, s35
	s_nop 0
	global_load_lds_dwordx4 v142, s[42:43]
	s_waitcnt vmcnt(8)
	s_waitcnt lgkmcnt(0)
	s_barrier
	s_setprio 1
	s_waitcnt lgkmcnt(0)
	v_mfma_f32_16x16x32_bf16 v[60:63], v[150:153], v[188:191], 0
	v_mfma_f32_16x16x32_bf16 v[52:55], v[158:161], v[188:191], 0
	v_mfma_f32_16x16x32_bf16 v[44:47], v[150:153], v[192:195], 0
	v_mfma_f32_16x16x32_bf16 v[36:39], v[158:161], v[192:195], 0
	v_mfma_f32_16x16x32_bf16 v[26:29], v[150:153], v[204:207], 0
	v_mfma_f32_16x16x32_bf16 v[18:21], v[158:161], v[204:207], 0
	v_mfma_f32_16x16x32_bf16 v[10:13], v[150:153], v[208:211], 0
	v_mfma_f32_16x16x32_bf16 v[6:9], v[158:161], v[208:211], 0
	v_mfma_f32_16x16x32_bf16 v[60:63], v[154:157], v[196:199], v[60:63]
	v_mfma_f32_16x16x32_bf16 v[52:55], v[162:165], v[196:199], v[52:55]
	v_mfma_f32_16x16x32_bf16 v[44:47], v[154:157], v[200:203], v[44:47]
	v_mfma_f32_16x16x32_bf16 v[36:39], v[162:165], v[200:203], v[36:39]
	v_mfma_f32_16x16x32_bf16 v[26:29], v[154:157], v[224:227], v[26:29]
	v_mfma_f32_16x16x32_bf16 v[18:21], v[162:165], v[224:227], v[18:21]
	v_mfma_f32_16x16x32_bf16 v[10:13], v[154:157], v[228:231], v[10:13]
	v_mfma_f32_16x16x32_bf16 v[6:9], v[162:165], v[228:231], v[6:9]
	s_setprio 0
	s_setprio 1
	v_mfma_f32_16x16x32_bf16 v[64:67], v[166:169], v[188:191], 0
	v_mfma_f32_16x16x32_bf16 v[56:59], v[174:177], v[188:191], 0
	v_mfma_f32_16x16x32_bf16 v[48:51], v[166:169], v[192:195], 0
	v_mfma_f32_16x16x32_bf16 v[40:43], v[174:177], v[192:195], 0
	v_mfma_f32_16x16x32_bf16 v[30:33], v[166:169], v[204:207], 0
	v_mfma_f32_16x16x32_bf16 v[22:25], v[174:177], v[204:207], 0
	v_mfma_f32_16x16x32_bf16 v[14:17], v[166:169], v[208:211], 0
	v_mfma_f32_16x16x32_bf16 v[2:5], v[174:177], v[208:211], 0
	v_mfma_f32_16x16x32_bf16 v[64:67], v[170:173], v[196:199], v[64:67]
	v_mfma_f32_16x16x32_bf16 v[56:59], v[184:187], v[196:199], v[56:59]
	v_mfma_f32_16x16x32_bf16 v[48:51], v[170:173], v[200:203], v[48:51]
	v_mfma_f32_16x16x32_bf16 v[40:43], v[184:187], v[200:203], v[40:43]
	v_mfma_f32_16x16x32_bf16 v[30:33], v[170:173], v[224:227], v[30:33]
	v_mfma_f32_16x16x32_bf16 v[22:25], v[184:187], v[224:227], v[22:25]
	v_mfma_f32_16x16x32_bf16 v[14:17], v[170:173], v[228:231], v[14:17]
	v_mfma_f32_16x16x32_bf16 v[2:5], v[184:187], v[228:231], v[2:5]
	s_setprio 0
	s_barrier
	s_add_i32 s31, 0, 0x18000
	ds_read_b128 v[150:153], v1 offset:32768
	ds_read_b128 v[154:157], v146 offset:32768
	s_add_i32 s54, 0, 0x1c000
	ds_read_b128 v[158:161], v1 offset:34816
	ds_read_b128 v[162:165], v146 offset:34816
	ds_read_b128 v[166:169], v1 offset:49152
	ds_read_b128 v[170:173], v146 offset:49152
	ds_read_b128 v[174:177], v1 offset:51200
	ds_read_b128 v[184:187], v146 offset:51200
	s_mov_b64 s[100:101], s[42:43]
	s_add_u32 s42, s42, 0x80000
	s_addc_u32 s43, s43, 0
	s_mov_b32 m0, s44
	ds_read_b128 v[188:191], v147 offset:32768
	ds_read_b128 v[192:195], v147 offset:34816
	ds_read_b128 v[196:199], v148 offset:32768
	ds_read_b128 v[200:203], v148 offset:34816
	ds_read_b128 v[204:207], v147 offset:36864
	ds_read_b128 v[208:211], v147 offset:38912
	ds_read_b128 v[224:227], v148 offset:36864
	ds_read_b128 v[228:231], v148 offset:38912
	global_load_lds_dwordx4 v144, s[42:43]
	s_mov_b32 m0, s45
	s_nop 0
	global_load_lds_dwordx4 v142, s[42:43]
	s_waitcnt vmcnt(8)
	s_waitcnt lgkmcnt(0)
	s_barrier
	s_setprio 1
	s_waitcnt lgkmcnt(0)
	v_mfma_f32_16x16x32_bf16 v[132:135], v[150:153], v[188:191], v[132:135]
	v_mfma_f32_16x16x32_bf16 v[124:127], v[158:161], v[188:191], v[124:127]
	v_mfma_f32_16x16x32_bf16 v[108:111], v[150:153], v[192:195], v[108:111]
	v_mfma_f32_16x16x32_bf16 v[100:103], v[158:161], v[192:195], v[100:103]
	v_mfma_f32_16x16x32_bf16 v[92:95], v[150:153], v[204:207], v[92:95]
	v_mfma_f32_16x16x32_bf16 v[84:87], v[158:161], v[204:207], v[84:87]
	v_mfma_f32_16x16x32_bf16 v[76:79], v[150:153], v[208:211], v[76:79]
	v_mfma_f32_16x16x32_bf16 v[68:71], v[158:161], v[208:211], v[68:71]
	v_mfma_f32_16x16x32_bf16 v[132:135], v[154:157], v[196:199], v[132:135]
	v_mfma_f32_16x16x32_bf16 v[124:127], v[162:165], v[196:199], v[124:127]
	v_mfma_f32_16x16x32_bf16 v[108:111], v[154:157], v[200:203], v[108:111]
	v_mfma_f32_16x16x32_bf16 v[100:103], v[162:165], v[200:203], v[100:103]
	v_mfma_f32_16x16x32_bf16 v[92:95], v[154:157], v[224:227], v[92:95]
	v_mfma_f32_16x16x32_bf16 v[84:87], v[162:165], v[224:227], v[84:87]
	v_mfma_f32_16x16x32_bf16 v[76:79], v[154:157], v[228:231], v[76:79]
	v_mfma_f32_16x16x32_bf16 v[68:71], v[162:165], v[228:231], v[68:71]
	s_setprio 0
	s_setprio 1
	v_mfma_f32_16x16x32_bf16 v[136:139], v[166:169], v[188:191], v[136:139]
	v_mfma_f32_16x16x32_bf16 v[128:131], v[174:177], v[188:191], v[128:131]
	v_mfma_f32_16x16x32_bf16 v[112:115], v[166:169], v[192:195], v[112:115]
	v_mfma_f32_16x16x32_bf16 v[104:107], v[174:177], v[192:195], v[104:107]
	v_mfma_f32_16x16x32_bf16 v[96:99], v[166:169], v[204:207], v[96:99]
	v_mfma_f32_16x16x32_bf16 v[88:91], v[174:177], v[204:207], v[88:91]
	v_mfma_f32_16x16x32_bf16 v[80:83], v[166:169], v[208:211], v[80:83]
	v_mfma_f32_16x16x32_bf16 v[72:75], v[174:177], v[208:211], v[72:75]
	v_mfma_f32_16x16x32_bf16 v[136:139], v[170:173], v[196:199], v[136:139]
	v_mfma_f32_16x16x32_bf16 v[128:131], v[184:187], v[196:199], v[128:131]
	v_mfma_f32_16x16x32_bf16 v[112:115], v[170:173], v[200:203], v[112:115]
	v_mfma_f32_16x16x32_bf16 v[104:107], v[184:187], v[200:203], v[104:107]
	v_mfma_f32_16x16x32_bf16 v[96:99], v[170:173], v[224:227], v[96:99]
	v_mfma_f32_16x16x32_bf16 v[88:91], v[184:187], v[224:227], v[88:91]
	v_mfma_f32_16x16x32_bf16 v[80:83], v[170:173], v[228:231], v[80:83]
	v_mfma_f32_16x16x32_bf16 v[72:75], v[184:187], v[228:231], v[72:75]
	s_setprio 0
	s_barrier
	s_add_i32 s31, s31, s33
	s_add_i32 m0, s31, 0xffffff80
	ds_read_b128 v[188:191], v147 offset:49152
	ds_read_b128 v[192:195], v147 offset:51200
	ds_read_b128 v[196:199], v148 offset:49152
	ds_read_b128 v[200:203], v148 offset:51200
	ds_read_b128 v[204:207], v147 offset:53248
	ds_read_b128 v[208:211], v147 offset:55296
	ds_read_b128 v[224:227], v148 offset:53248
	ds_read_b128 v[228:231], v148 offset:55296
	global_load_lds_dwordx4 v34, s[28:29] offset:128
	s_add_i32 m0, s31, 0x1f80
	s_mov_b64 s[98:99], s[28:29]
	s_add_u32 s28, s28, 0x80080
	s_addc_u32 s29, s29, 0
	s_add_i32 s31, s54, s33
	global_load_lds_dwordx4 v140, s[98:99] offset:128
	s_mov_b32 m0, s31
	s_nop 0
	global_load_lds_dwordx4 v34, s[28:29]
	s_add_i32 m0, s31, 0x2000
	s_nop 0
	global_load_lds_dwordx4 v140, s[28:29]
	s_add_i32 m0, s48, 0xffffff80
	s_nop 0
	global_load_lds_dwordx4 v144, s[100:101] offset:128
	s_add_i32 m0, s49, 0xffffff80
	s_nop 0
	global_load_lds_dwordx4 v142, s[100:101] offset:128
	s_waitcnt vmcnt(8)
	s_waitcnt lgkmcnt(0)
	s_barrier
	s_setprio 1
	s_waitcnt lgkmcnt(0)
	v_mfma_f32_16x16x32_bf16 v[60:63], v[150:153], v[188:191], v[60:63]
	v_mfma_f32_16x16x32_bf16 v[52:55], v[158:161], v[188:191], v[52:55]
	v_mfma_f32_16x16x32_bf16 v[44:47], v[150:153], v[192:195], v[44:47]
	v_mfma_f32_16x16x32_bf16 v[36:39], v[158:161], v[192:195], v[36:39]
	v_mfma_f32_16x16x32_bf16 v[26:29], v[150:153], v[204:207], v[26:29]
	v_mfma_f32_16x16x32_bf16 v[18:21], v[158:161], v[204:207], v[18:21]
	v_mfma_f32_16x16x32_bf16 v[10:13], v[150:153], v[208:211], v[10:13]
	v_mfma_f32_16x16x32_bf16 v[6:9], v[158:161], v[208:211], v[6:9]
	v_mfma_f32_16x16x32_bf16 v[60:63], v[154:157], v[196:199], v[60:63]
	v_mfma_f32_16x16x32_bf16 v[52:55], v[162:165], v[196:199], v[52:55]
	v_mfma_f32_16x16x32_bf16 v[44:47], v[154:157], v[200:203], v[44:47]
	v_mfma_f32_16x16x32_bf16 v[36:39], v[162:165], v[200:203], v[36:39]
	v_mfma_f32_16x16x32_bf16 v[26:29], v[154:157], v[224:227], v[26:29]
	v_mfma_f32_16x16x32_bf16 v[18:21], v[162:165], v[224:227], v[18:21]
	v_mfma_f32_16x16x32_bf16 v[10:13], v[154:157], v[228:231], v[10:13]
	v_mfma_f32_16x16x32_bf16 v[6:9], v[162:165], v[228:231], v[6:9]
	s_setprio 0
	s_setprio 1
	v_mfma_f32_16x16x32_bf16 v[64:67], v[166:169], v[188:191], v[64:67]
	v_mfma_f32_16x16x32_bf16 v[56:59], v[174:177], v[188:191], v[56:59]
	v_mfma_f32_16x16x32_bf16 v[48:51], v[166:169], v[192:195], v[48:51]
	v_mfma_f32_16x16x32_bf16 v[40:43], v[174:177], v[192:195], v[40:43]
	v_mfma_f32_16x16x32_bf16 v[30:33], v[166:169], v[204:207], v[30:33]
	v_mfma_f32_16x16x32_bf16 v[22:25], v[174:177], v[204:207], v[22:25]
	v_mfma_f32_16x16x32_bf16 v[14:17], v[166:169], v[208:211], v[14:17]
	v_mfma_f32_16x16x32_bf16 v[2:5], v[174:177], v[208:211], v[2:5]
	v_mfma_f32_16x16x32_bf16 v[64:67], v[170:173], v[196:199], v[64:67]
	v_mfma_f32_16x16x32_bf16 v[56:59], v[184:187], v[196:199], v[56:59]
	v_mfma_f32_16x16x32_bf16 v[48:51], v[170:173], v[200:203], v[48:51]
	v_mfma_f32_16x16x32_bf16 v[40:43], v[184:187], v[200:203], v[40:43]
	v_mfma_f32_16x16x32_bf16 v[30:33], v[170:173], v[224:227], v[30:33]
	v_mfma_f32_16x16x32_bf16 v[22:25], v[184:187], v[224:227], v[22:25]
	v_mfma_f32_16x16x32_bf16 v[14:17], v[170:173], v[228:231], v[14:17]
	v_mfma_f32_16x16x32_bf16 v[2:5], v[184:187], v[228:231], v[2:5]
	s_setprio 0
	s_barrier
	s_add_i32 s30, s30, 2
	s_add_u32 s8, s8, 0x100
	s_addc_u32 s9, s9, 0
	s_add_u32 s24, s24, 0x100
	s_addc_u32 s25, s25, 0
	s_cmp_gt_u32 s30, 29
	s_cbranch_scc1 .Lpeel_done_P6
.LBB0_1114:
	s_add_u32 s28, s8, 0xfff80080
	s_addc_u32 s29, s9, -1
	s_add_i32 s31, 0, 0x10000
	s_cmp_eq_u32 s30, 28
	s_cselect_b32 s43, s13, s29
	s_cselect_b32 s42, s19, s28
	ds_read_b128 v[150:153], v1
	ds_read_b128 v[154:157], v146
	s_cselect_b32 s29, s20, s25
	s_cselect_b32 s28, s21, s24
	s_add_i32 s56, 0, 0x14000
	ds_read_b128 v[158:161], v1 offset:2048
	ds_read_b128 v[162:165], v146 offset:2048
	ds_read_b128 v[166:169], v1 offset:16384
	ds_read_b128 v[170:173], v146 offset:16384
	ds_read_b128 v[174:177], v1 offset:18432
	ds_read_b128 v[184:187], v146 offset:18432
	s_add_i32 m0, s34, 0xc000
	ds_read_b128 v[188:191], v147
	ds_read_b128 v[192:195], v147 offset:2048
	ds_read_b128 v[196:199], v148
	ds_read_b128 v[200:203], v148 offset:2048
	ds_read_b128 v[204:207], v147 offset:4096
	ds_read_b128 v[208:211], v147 offset:6144
	ds_read_b128 v[224:227], v148 offset:4096
	ds_read_b128 v[228:231], v148 offset:6144
	global_load_lds_dwordx4 v144, s[8:9]
	s_add_i32 m0, s34, 0xe000
	s_nop 0
	global_load_lds_dwordx4 v142, s[8:9]
	s_waitcnt vmcnt(8)
	s_waitcnt lgkmcnt(0)
	s_barrier
	s_setprio 1
	s_waitcnt lgkmcnt(0)
	v_mfma_f32_16x16x32_bf16 v[132:135], v[150:153], v[188:191], v[132:135]
	v_mfma_f32_16x16x32_bf16 v[124:127], v[158:161], v[188:191], v[124:127]
	v_mfma_f32_16x16x32_bf16 v[108:111], v[150:153], v[192:195], v[108:111]
	v_mfma_f32_16x16x32_bf16 v[100:103], v[158:161], v[192:195], v[100:103]
	v_mfma_f32_16x16x32_bf16 v[92:95], v[150:153], v[204:207], v[92:95]
	v_mfma_f32_16x16x32_bf16 v[84:87], v[158:161], v[204:207], v[84:87]
	v_mfma_f32_16x16x32_bf16 v[76:79], v[150:153], v[208:211], v[76:79]
	v_mfma_f32_16x16x32_bf16 v[68:71], v[158:161], v[208:211], v[68:71]
	v_mfma_f32_16x16x32_bf16 v[132:135], v[154:157], v[196:199], v[132:135]
	v_mfma_f32_16x16x32_bf16 v[124:127], v[162:165], v[196:199], v[124:127]
	v_mfma_f32_16x16x32_bf16 v[108:111], v[154:157], v[200:203], v[108:111]
	v_mfma_f32_16x16x32_bf16 v[100:103], v[162:165], v[200:203], v[100:103]
	v_mfma_f32_16x16x32_bf16 v[92:95], v[154:157], v[224:227], v[92:95]
	v_mfma_f32_16x16x32_bf16 v[84:87], v[162:165], v[224:227], v[84:87]
	v_mfma_f32_16x16x32_bf16 v[76:79], v[154:157], v[228:231], v[76:79]
	v_mfma_f32_16x16x32_bf16 v[68:71], v[162:165], v[228:231], v[68:71]
	s_setprio 0
	s_setprio 1
	v_mfma_f32_16x16x32_bf16 v[136:139], v[166:169], v[188:191], v[136:139]
	v_mfma_f32_16x16x32_bf16 v[128:131], v[174:177], v[188:191], v[128:131]
	v_mfma_f32_16x16x32_bf16 v[112:115], v[166:169], v[192:195], v[112:115]
	v_mfma_f32_16x16x32_bf16 v[104:107], v[174:177], v[192:195], v[104:107]
	v_mfma_f32_16x16x32_bf16 v[96:99], v[166:169], v[204:207], v[96:99]
	v_mfma_f32_16x16x32_bf16 v[88:91], v[174:177], v[204:207], v[88:91]
	v_mfma_f32_16x16x32_bf16 v[80:83], v[166:169], v[208:211], v[80:83]
	v_mfma_f32_16x16x32_bf16 v[72:75], v[174:177], v[208:211], v[72:75]
	v_mfma_f32_16x16x32_bf16 v[136:139], v[170:173], v[196:199], v[136:139]
	v_mfma_f32_16x16x32_bf16 v[128:131], v[184:187], v[196:199], v[128:131]
	v_mfma_f32_16x16x32_bf16 v[112:115], v[170:173], v[200:203], v[112:115]
	v_mfma_f32_16x16x32_bf16 v[104:107], v[184:187], v[200:203], v[104:107]
	v_mfma_f32_16x16x32_bf16 v[96:99], v[170:173], v[224:227], v[96:99]
	v_mfma_f32_16x16x32_bf16 v[88:91], v[184:187], v[224:227], v[88:91]
	v_mfma_f32_16x16x32_bf16 v[80:83], v[170:173], v[228:231], v[80:83]
	v_mfma_f32_16x16x32_bf16 v[72:75], v[184:187], v[228:231], v[72:75]
	s_setprio 0
	s_barrier
	s_add_i32 s31, s31, s33
	s_mov_b32 m0, s31
	ds_read_b128 v[188:191], v147 offset:16384
	ds_read_b128 v[192:195], v147 offset:18432
	ds_read_b128 v[196:199], v148 offset:16384
	ds_read_b128 v[200:203], v148 offset:18432
	ds_read_b128 v[204:207], v147 offset:20480
	ds_read_b128 v[208:211], v147 offset:22528
	ds_read_b128 v[224:227], v148 offset:20480
	ds_read_b128 v[228:231], v148 offset:22528
	global_load_lds_dwordx4 v34, s[28:29]
	s_add_i32 m0, s31, 0x2000
	s_add_u32 s54, s28, 0x80000
	s_addc_u32 s55, s29, 0
	s_add_i32 s31, s56, s33
	global_load_lds_dwordx4 v140, s[28:29]
	s_mov_b32 m0, s31
	s_nop 0
	global_load_lds_dwordx4 v34, s[54:55]
	s_add_i32 m0, s31, 0x2000
	s_nop 0
	global_load_lds_dwordx4 v140, s[54:55]
	s_mov_b32 m0, s34
	s_nop 0
	global_load_lds_dwordx4 v144, s[42:43]
	s_mov_b32 m0, s35
	s_nop 0
	global_load_lds_dwordx4 v142, s[42:43]
	s_waitcnt vmcnt(8)
	s_waitcnt lgkmcnt(0)
	s_barrier
	s_setprio 1
	s_waitcnt lgkmcnt(0)
	v_mfma_f32_16x16x32_bf16 v[60:63], v[150:153], v[188:191], v[60:63]
	v_mfma_f32_16x16x32_bf16 v[52:55], v[158:161], v[188:191], v[52:55]
	v_mfma_f32_16x16x32_bf16 v[44:47], v[150:153], v[192:195], v[44:47]
	v_mfma_f32_16x16x32_bf16 v[36:39], v[158:161], v[192:195], v[36:39]
	v_mfma_f32_16x16x32_bf16 v[26:29], v[150:153], v[204:207], v[26:29]
	v_mfma_f32_16x16x32_bf16 v[18:21], v[158:161], v[204:207], v[18:21]
	v_mfma_f32_16x16x32_bf16 v[10:13], v[150:153], v[208:211], v[10:13]
	v_mfma_f32_16x16x32_bf16 v[6:9], v[158:161], v[208:211], v[6:9]
	v_mfma_f32_16x16x32_bf16 v[60:63], v[154:157], v[196:199], v[60:63]
	v_mfma_f32_16x16x32_bf16 v[52:55], v[162:165], v[196:199], v[52:55]
	v_mfma_f32_16x16x32_bf16 v[44:47], v[154:157], v[200:203], v[44:47]
	v_mfma_f32_16x16x32_bf16 v[36:39], v[162:165], v[200:203], v[36:39]
	v_mfma_f32_16x16x32_bf16 v[26:29], v[154:157], v[224:227], v[26:29]
	v_mfma_f32_16x16x32_bf16 v[18:21], v[162:165], v[224:227], v[18:21]
	v_mfma_f32_16x16x32_bf16 v[10:13], v[154:157], v[228:231], v[10:13]
	v_mfma_f32_16x16x32_bf16 v[6:9], v[162:165], v[228:231], v[6:9]
	s_setprio 0
	s_setprio 1
	v_mfma_f32_16x16x32_bf16 v[64:67], v[166:169], v[188:191], v[64:67]
	v_mfma_f32_16x16x32_bf16 v[56:59], v[174:177], v[188:191], v[56:59]
	v_mfma_f32_16x16x32_bf16 v[48:51], v[166:169], v[192:195], v[48:51]
	v_mfma_f32_16x16x32_bf16 v[40:43], v[174:177], v[192:195], v[40:43]
	v_mfma_f32_16x16x32_bf16 v[30:33], v[166:169], v[204:207], v[30:33]
	v_mfma_f32_16x16x32_bf16 v[22:25], v[174:177], v[204:207], v[22:25]
	v_mfma_f32_16x16x32_bf16 v[14:17], v[166:169], v[208:211], v[14:17]
	v_mfma_f32_16x16x32_bf16 v[2:5], v[174:177], v[208:211], v[2:5]
	v_mfma_f32_16x16x32_bf16 v[64:67], v[170:173], v[196:199], v[64:67]
	v_mfma_f32_16x16x32_bf16 v[56:59], v[184:187], v[196:199], v[56:59]
	v_mfma_f32_16x16x32_bf16 v[48:51], v[170:173], v[200:203], v[48:51]
	v_mfma_f32_16x16x32_bf16 v[40:43], v[184:187], v[200:203], v[40:43]
	v_mfma_f32_16x16x32_bf16 v[30:33], v[170:173], v[224:227], v[30:33]
	v_mfma_f32_16x16x32_bf16 v[22:25], v[184:187], v[224:227], v[22:25]
	v_mfma_f32_16x16x32_bf16 v[14:17], v[170:173], v[228:231], v[14:17]
	v_mfma_f32_16x16x32_bf16 v[2:5], v[184:187], v[228:231], v[2:5]
	s_setprio 0
	s_barrier
	s_add_i32 s31, 0, 0x18000
	ds_read_b128 v[150:153], v1 offset:32768
	ds_read_b128 v[154:157], v146 offset:32768
	s_add_i32 s54, 0, 0x1c000
	ds_read_b128 v[158:161], v1 offset:34816
	ds_read_b128 v[162:165], v146 offset:34816
	ds_read_b128 v[166:169], v1 offset:49152
	ds_read_b128 v[170:173], v146 offset:49152
	ds_read_b128 v[174:177], v1 offset:51200
	ds_read_b128 v[184:187], v146 offset:51200
	s_mov_b64 s[100:101], s[42:43]
	s_add_u32 s42, s42, 0x80000
	s_addc_u32 s43, s43, 0
	s_mov_b32 m0, s44
	ds_read_b128 v[188:191], v147 offset:32768
	ds_read_b128 v[192:195], v147 offset:34816
	ds_read_b128 v[196:199], v148 offset:32768
	ds_read_b128 v[200:203], v148 offset:34816
	ds_read_b128 v[204:207], v147 offset:36864
	ds_read_b128 v[208:211], v147 offset:38912
	ds_read_b128 v[224:227], v148 offset:36864
	ds_read_b128 v[228:231], v148 offset:38912
	global_load_lds_dwordx4 v144, s[42:43]
	s_mov_b32 m0, s45
	s_nop 0
	global_load_lds_dwordx4 v142, s[42:43]
	s_waitcnt vmcnt(8)
	s_waitcnt lgkmcnt(0)
	s_barrier
	s_setprio 1
	s_waitcnt lgkmcnt(0)
	v_mfma_f32_16x16x32_bf16 v[132:135], v[150:153], v[188:191], v[132:135]
	v_mfma_f32_16x16x32_bf16 v[124:127], v[158:161], v[188:191], v[124:127]
	v_mfma_f32_16x16x32_bf16 v[108:111], v[150:153], v[192:195], v[108:111]
	v_mfma_f32_16x16x32_bf16 v[100:103], v[158:161], v[192:195], v[100:103]
	v_mfma_f32_16x16x32_bf16 v[92:95], v[150:153], v[204:207], v[92:95]
	v_mfma_f32_16x16x32_bf16 v[84:87], v[158:161], v[204:207], v[84:87]
	v_mfma_f32_16x16x32_bf16 v[76:79], v[150:153], v[208:211], v[76:79]
	v_mfma_f32_16x16x32_bf16 v[68:71], v[158:161], v[208:211], v[68:71]
	v_mfma_f32_16x16x32_bf16 v[132:135], v[154:157], v[196:199], v[132:135]
	v_mfma_f32_16x16x32_bf16 v[124:127], v[162:165], v[196:199], v[124:127]
	v_mfma_f32_16x16x32_bf16 v[108:111], v[154:157], v[200:203], v[108:111]
	v_mfma_f32_16x16x32_bf16 v[100:103], v[162:165], v[200:203], v[100:103]
	v_mfma_f32_16x16x32_bf16 v[92:95], v[154:157], v[224:227], v[92:95]
	v_mfma_f32_16x16x32_bf16 v[84:87], v[162:165], v[224:227], v[84:87]
	v_mfma_f32_16x16x32_bf16 v[76:79], v[154:157], v[228:231], v[76:79]
	v_mfma_f32_16x16x32_bf16 v[68:71], v[162:165], v[228:231], v[68:71]
	s_setprio 0
	s_setprio 1
	v_mfma_f32_16x16x32_bf16 v[136:139], v[166:169], v[188:191], v[136:139]
	v_mfma_f32_16x16x32_bf16 v[128:131], v[174:177], v[188:191], v[128:131]
	v_mfma_f32_16x16x32_bf16 v[112:115], v[166:169], v[192:195], v[112:115]
	v_mfma_f32_16x16x32_bf16 v[104:107], v[174:177], v[192:195], v[104:107]
	v_mfma_f32_16x16x32_bf16 v[96:99], v[166:169], v[204:207], v[96:99]
	v_mfma_f32_16x16x32_bf16 v[88:91], v[174:177], v[204:207], v[88:91]
	v_mfma_f32_16x16x32_bf16 v[80:83], v[166:169], v[208:211], v[80:83]
	v_mfma_f32_16x16x32_bf16 v[72:75], v[174:177], v[208:211], v[72:75]
	v_mfma_f32_16x16x32_bf16 v[136:139], v[170:173], v[196:199], v[136:139]
	v_mfma_f32_16x16x32_bf16 v[128:131], v[184:187], v[196:199], v[128:131]
	v_mfma_f32_16x16x32_bf16 v[112:115], v[170:173], v[200:203], v[112:115]
	v_mfma_f32_16x16x32_bf16 v[104:107], v[184:187], v[200:203], v[104:107]
	v_mfma_f32_16x16x32_bf16 v[96:99], v[170:173], v[224:227], v[96:99]
	v_mfma_f32_16x16x32_bf16 v[88:91], v[184:187], v[224:227], v[88:91]
	v_mfma_f32_16x16x32_bf16 v[80:83], v[170:173], v[228:231], v[80:83]
	v_mfma_f32_16x16x32_bf16 v[72:75], v[184:187], v[228:231], v[72:75]
	s_setprio 0
	s_barrier
	s_add_i32 s31, s31, s33
	s_add_i32 m0, s31, 0xffffff80
	ds_read_b128 v[188:191], v147 offset:49152
	ds_read_b128 v[192:195], v147 offset:51200
	ds_read_b128 v[196:199], v148 offset:49152
	ds_read_b128 v[200:203], v148 offset:51200
	ds_read_b128 v[204:207], v147 offset:53248
	ds_read_b128 v[208:211], v147 offset:55296
	ds_read_b128 v[224:227], v148 offset:53248
	ds_read_b128 v[228:231], v148 offset:55296
	global_load_lds_dwordx4 v34, s[28:29] offset:128
	s_add_i32 m0, s31, 0x1f80
	s_mov_b64 s[98:99], s[28:29]
	s_add_u32 s28, s28, 0x80080
	s_addc_u32 s29, s29, 0
	s_add_i32 s31, s54, s33
	global_load_lds_dwordx4 v140, s[98:99] offset:128
	s_mov_b32 m0, s31
	s_nop 0
	global_load_lds_dwordx4 v34, s[28:29]
	s_add_i32 m0, s31, 0x2000
	s_nop 0
	global_load_lds_dwordx4 v140, s[28:29]
	s_add_i32 m0, s48, 0xffffff80
	s_nop 0
	global_load_lds_dwordx4 v144, s[100:101] offset:128
	s_add_i32 m0, s49, 0xffffff80
	s_nop 0
	global_load_lds_dwordx4 v142, s[100:101] offset:128
	s_waitcnt vmcnt(8)
	s_waitcnt lgkmcnt(0)
	s_barrier
	s_setprio 1
	s_waitcnt lgkmcnt(0)
	v_mfma_f32_16x16x32_bf16 v[60:63], v[150:153], v[188:191], v[60:63]
	v_mfma_f32_16x16x32_bf16 v[52:55], v[158:161], v[188:191], v[52:55]
	v_mfma_f32_16x16x32_bf16 v[44:47], v[150:153], v[192:195], v[44:47]
	v_mfma_f32_16x16x32_bf16 v[36:39], v[158:161], v[192:195], v[36:39]
	v_mfma_f32_16x16x32_bf16 v[26:29], v[150:153], v[204:207], v[26:29]
	v_mfma_f32_16x16x32_bf16 v[18:21], v[158:161], v[204:207], v[18:21]
	v_mfma_f32_16x16x32_bf16 v[10:13], v[150:153], v[208:211], v[10:13]
	v_mfma_f32_16x16x32_bf16 v[6:9], v[158:161], v[208:211], v[6:9]
	v_mfma_f32_16x16x32_bf16 v[60:63], v[154:157], v[196:199], v[60:63]
	v_mfma_f32_16x16x32_bf16 v[52:55], v[162:165], v[196:199], v[52:55]
	v_mfma_f32_16x16x32_bf16 v[44:47], v[154:157], v[200:203], v[44:47]
	v_mfma_f32_16x16x32_bf16 v[36:39], v[162:165], v[200:203], v[36:39]
	v_mfma_f32_16x16x32_bf16 v[26:29], v[154:157], v[224:227], v[26:29]
	v_mfma_f32_16x16x32_bf16 v[18:21], v[162:165], v[224:227], v[18:21]
	v_mfma_f32_16x16x32_bf16 v[10:13], v[154:157], v[228:231], v[10:13]
	v_mfma_f32_16x16x32_bf16 v[6:9], v[162:165], v[228:231], v[6:9]
	s_setprio 0
	s_setprio 1
	v_mfma_f32_16x16x32_bf16 v[64:67], v[166:169], v[188:191], v[64:67]
	v_mfma_f32_16x16x32_bf16 v[56:59], v[174:177], v[188:191], v[56:59]
	v_mfma_f32_16x16x32_bf16 v[48:51], v[166:169], v[192:195], v[48:51]
	v_mfma_f32_16x16x32_bf16 v[40:43], v[174:177], v[192:195], v[40:43]
	v_mfma_f32_16x16x32_bf16 v[30:33], v[166:169], v[204:207], v[30:33]
	v_mfma_f32_16x16x32_bf16 v[22:25], v[174:177], v[204:207], v[22:25]
	v_mfma_f32_16x16x32_bf16 v[14:17], v[166:169], v[208:211], v[14:17]
	v_mfma_f32_16x16x32_bf16 v[2:5], v[174:177], v[208:211], v[2:5]
	v_mfma_f32_16x16x32_bf16 v[64:67], v[170:173], v[196:199], v[64:67]
	v_mfma_f32_16x16x32_bf16 v[56:59], v[184:187], v[196:199], v[56:59]
	v_mfma_f32_16x16x32_bf16 v[48:51], v[170:173], v[200:203], v[48:51]
	v_mfma_f32_16x16x32_bf16 v[40:43], v[184:187], v[200:203], v[40:43]
	v_mfma_f32_16x16x32_bf16 v[30:33], v[170:173], v[224:227], v[30:33]
	v_mfma_f32_16x16x32_bf16 v[22:25], v[184:187], v[224:227], v[22:25]
	v_mfma_f32_16x16x32_bf16 v[14:17], v[170:173], v[228:231], v[14:17]
	v_mfma_f32_16x16x32_bf16 v[2:5], v[184:187], v[228:231], v[2:5]
	s_setprio 0
	s_barrier
	s_add_i32 s30, s30, 2
	s_add_u32 s8, s8, 0x100
	s_addc_u32 s9, s9, 0
	s_add_u32 s24, s24, 0x100
	s_addc_u32 s25, s25, 0
	s_cmp_gt_u32 s30, 29
	s_cbranch_scc0 .LBB0_1114

.LBB0_1194:
	s_add_u32 s8, s8, 0x160080
	s_addc_u32 s9, s9, 0
	s_add_u32 s20, s18, 0x100
	s_addc_u32 s21, s19, 0
	s_mov_b32 s24, -2
	v_readlane_b32 s35, v255, 20
	v_readlane_b32 s40, v255, 21
	v_readlane_b32 s41, v255, 22
	v_readlane_b32 s57, v255, 23
	s_mov_b64 s[58:59], 0x80
	s_add_u32 s18, s8, 0xffea0080
	s_addc_u32 s19, s9, -1
	s_add_i32 s25, 0, 0x10000
	s_cmpk_eq_i32 s24, 0x54
	s_cselect_b32 s23, s45, s19
	s_cselect_b32 s22, s44, s18
	s_cselect_b32 s19, s47, s21
	s_cselect_b32 s18, s46, s20
	s_add_i32 s34, 0, 0x14000
	ds_read_b128 v[138:141], v1
	ds_read_b128 v[142:145], v160
	ds_read_b128 v[146:149], v1 offset:2048
	ds_read_b128 v[150:153], v160 offset:2048
	ds_read_b128 v[154:157], v1 offset:16384
	ds_read_b128 v[164:167], v160 offset:16384
	ds_read_b128 v[168:171], v1 offset:18432
	ds_read_b128 v[172:175], v160 offset:18432
	s_add_i32 m0, s29, 0xc000
	ds_read_b128 v[176:179], v161
	ds_read_b128 v[184:187], v161 offset:2048
	ds_read_b128 v[188:191], v162
	ds_read_b128 v[192:195], v162 offset:2048
	ds_read_b128 v[196:199], v161 offset:4096
	ds_read_b128 v[200:203], v161 offset:6144
	ds_read_b128 v[204:207], v162 offset:4096
	ds_read_b128 v[208:211], v162 offset:6144
	global_load_lds_dwordx4 v136, s[8:9]
	s_add_i32 m0, s29, 0xe000
	s_nop 0
	global_load_lds_dwordx4 v134, s[8:9]
	s_waitcnt vmcnt(8)
	s_waitcnt lgkmcnt(0)
	s_barrier
	s_setprio 1
	s_waitcnt lgkmcnt(0)
	v_mfma_f32_16x16x32_bf16 v[128:131], v[138:141], v[176:179], 0
	v_mfma_f32_16x16x32_bf16 v[124:127], v[146:149], v[176:179], 0
	v_mfma_f32_16x16x32_bf16 v[112:115], v[138:141], v[184:187], 0
	v_mfma_f32_16x16x32_bf16 v[108:111], v[146:149], v[184:187], 0
	v_mfma_f32_16x16x32_bf16 v[96:99], v[138:141], v[196:199], 0
	v_mfma_f32_16x16x32_bf16 v[92:95], v[146:149], v[196:199], 0
	v_mfma_f32_16x16x32_bf16 v[80:83], v[138:141], v[200:203], 0
	v_mfma_f32_16x16x32_bf16 v[76:79], v[146:149], v[200:203], 0
	v_mfma_f32_16x16x32_bf16 v[128:131], v[142:145], v[188:191], v[128:131]
	v_mfma_f32_16x16x32_bf16 v[124:127], v[150:153], v[188:191], v[124:127]
	v_mfma_f32_16x16x32_bf16 v[112:115], v[142:145], v[192:195], v[112:115]
	v_mfma_f32_16x16x32_bf16 v[108:111], v[150:153], v[192:195], v[108:111]
	v_mfma_f32_16x16x32_bf16 v[96:99], v[142:145], v[204:207], v[96:99]
	v_mfma_f32_16x16x32_bf16 v[92:95], v[150:153], v[204:207], v[92:95]
	v_mfma_f32_16x16x32_bf16 v[80:83], v[142:145], v[208:211], v[80:83]
	v_mfma_f32_16x16x32_bf16 v[76:79], v[150:153], v[208:211], v[76:79]
	s_setprio 0
	s_setprio 1
	v_mfma_f32_16x16x32_bf16 v[120:123], v[154:157], v[176:179], 0
	v_mfma_f32_16x16x32_bf16 v[116:119], v[168:171], v[176:179], 0
	v_mfma_f32_16x16x32_bf16 v[104:107], v[154:157], v[184:187], 0
	v_mfma_f32_16x16x32_bf16 v[100:103], v[168:171], v[184:187], 0
	v_mfma_f32_16x16x32_bf16 v[88:91], v[154:157], v[196:199], 0
	v_mfma_f32_16x16x32_bf16 v[84:87], v[168:171], v[196:199], 0
	v_mfma_f32_16x16x32_bf16 v[72:75], v[154:157], v[200:203], 0
	v_mfma_f32_16x16x32_bf16 v[68:71], v[168:171], v[200:203], 0
	v_mfma_f32_16x16x32_bf16 v[120:123], v[164:167], v[188:191], v[120:123]
	v_mfma_f32_16x16x32_bf16 v[116:119], v[172:175], v[188:191], v[116:119]
	v_mfma_f32_16x16x32_bf16 v[104:107], v[164:167], v[192:195], v[104:107]
	v_mfma_f32_16x16x32_bf16 v[100:103], v[172:175], v[192:195], v[100:103]
	v_mfma_f32_16x16x32_bf16 v[88:91], v[164:167], v[204:207], v[88:91]
	v_mfma_f32_16x16x32_bf16 v[84:87], v[172:175], v[204:207], v[84:87]
	v_mfma_f32_16x16x32_bf16 v[72:75], v[164:167], v[208:211], v[72:75]
	v_mfma_f32_16x16x32_bf16 v[68:71], v[172:175], v[208:211], v[68:71]
	s_setprio 0
	s_barrier
	s_add_i32 s25, s25, s28
	s_mov_b32 m0, s25
	ds_read_b128 v[176:179], v161 offset:16384
	ds_read_b128 v[184:187], v161 offset:18432
	ds_read_b128 v[188:191], v162 offset:16384
	ds_read_b128 v[192:195], v162 offset:18432
	ds_read_b128 v[196:199], v161 offset:20480
	ds_read_b128 v[200:203], v161 offset:22528
	ds_read_b128 v[204:207], v162 offset:20480
	ds_read_b128 v[208:211], v162 offset:22528
	global_load_lds_dwordx4 v34, s[18:19]
	s_add_i32 m0, s25, 0x2000
	s_add_u32 s30, s18, 0x160000
	s_addc_u32 s31, s19, 0
	s_add_i32 s25, s34, s28
	global_load_lds_dwordx4 v132, s[18:19]
	s_mov_b32 m0, s25
	s_nop 0
	global_load_lds_dwordx4 v34, s[30:31]
	s_add_i32 m0, s25, 0x2000
	s_nop 0
	global_load_lds_dwordx4 v132, s[30:31]
	s_mov_b32 m0, s29
	s_nop 0
	global_load_lds_dwordx4 v136, s[22:23]
	s_mov_b32 m0, s33
	s_nop 0
	global_load_lds_dwordx4 v134, s[22:23]
	s_waitcnt vmcnt(8)
	s_waitcnt lgkmcnt(0)
	s_barrier
	s_setprio 1
	s_waitcnt lgkmcnt(0)
	v_mfma_f32_16x16x32_bf16 v[64:67], v[138:141], v[176:179], 0
	v_mfma_f32_16x16x32_bf16 v[60:63], v[146:149], v[176:179], 0
	v_mfma_f32_16x16x32_bf16 v[48:51], v[138:141], v[184:187], 0
	v_mfma_f32_16x16x32_bf16 v[44:47], v[146:149], v[184:187], 0
	v_mfma_f32_16x16x32_bf16 v[30:33], v[138:141], v[196:199], 0
	v_mfma_f32_16x16x32_bf16 v[26:29], v[146:149], v[196:199], 0
	v_mfma_f32_16x16x32_bf16 v[14:17], v[138:141], v[200:203], 0
	v_mfma_f32_16x16x32_bf16 v[10:13], v[146:149], v[200:203], 0
	v_mfma_f32_16x16x32_bf16 v[64:67], v[142:145], v[188:191], v[64:67]
	v_mfma_f32_16x16x32_bf16 v[60:63], v[150:153], v[188:191], v[60:63]
	v_mfma_f32_16x16x32_bf16 v[48:51], v[142:145], v[192:195], v[48:51]
	v_mfma_f32_16x16x32_bf16 v[44:47], v[150:153], v[192:195], v[44:47]
	v_mfma_f32_16x16x32_bf16 v[30:33], v[142:145], v[204:207], v[30:33]
	v_mfma_f32_16x16x32_bf16 v[26:29], v[150:153], v[204:207], v[26:29]
	v_mfma_f32_16x16x32_bf16 v[14:17], v[142:145], v[208:211], v[14:17]
	v_mfma_f32_16x16x32_bf16 v[10:13], v[150:153], v[208:211], v[10:13]
	s_setprio 0
	s_setprio 1
	v_mfma_f32_16x16x32_bf16 v[56:59], v[154:157], v[176:179], 0
	v_mfma_f32_16x16x32_bf16 v[52:55], v[168:171], v[176:179], 0
	v_mfma_f32_16x16x32_bf16 v[40:43], v[154:157], v[184:187], 0
	v_mfma_f32_16x16x32_bf16 v[36:39], v[168:171], v[184:187], 0
	v_mfma_f32_16x16x32_bf16 v[22:25], v[154:157], v[196:199], 0
	v_mfma_f32_16x16x32_bf16 v[18:21], v[168:171], v[196:199], 0
	v_mfma_f32_16x16x32_bf16 v[6:9], v[154:157], v[200:203], 0
	v_mfma_f32_16x16x32_bf16 v[2:5], v[168:171], v[200:203], 0
	v_mfma_f32_16x16x32_bf16 v[56:59], v[164:167], v[188:191], v[56:59]
	v_mfma_f32_16x16x32_bf16 v[52:55], v[172:175], v[188:191], v[52:55]
	v_mfma_f32_16x16x32_bf16 v[40:43], v[164:167], v[192:195], v[40:43]
	v_mfma_f32_16x16x32_bf16 v[36:39], v[172:175], v[192:195], v[36:39]
	v_mfma_f32_16x16x32_bf16 v[22:25], v[164:167], v[204:207], v[22:25]
	v_mfma_f32_16x16x32_bf16 v[18:21], v[172:175], v[204:207], v[18:21]
	v_mfma_f32_16x16x32_bf16 v[6:9], v[164:167], v[208:211], v[6:9]
	v_mfma_f32_16x16x32_bf16 v[2:5], v[172:175], v[208:211], v[2:5]
	s_setprio 0
	s_barrier
	s_add_i32 s25, 0, 0x18000
	s_add_i32 s30, 0, 0x1c000
	ds_read_b128 v[138:141], v1 offset:32768
	ds_read_b128 v[142:145], v160 offset:32768
	ds_read_b128 v[146:149], v1 offset:34816
	ds_read_b128 v[150:153], v160 offset:34816
	ds_read_b128 v[154:157], v1 offset:49152
	ds_read_b128 v[164:167], v160 offset:49152
	ds_read_b128 v[168:171], v1 offset:51200
	ds_read_b128 v[172:175], v160 offset:51200
	s_mov_b64 s[100:101], s[22:23]
	s_add_u32 s22, s22, 0x160000
	s_addc_u32 s23, s23, 0
	s_mov_b32 m0, s48
	ds_read_b128 v[176:179], v161 offset:32768
	ds_read_b128 v[184:187], v161 offset:34816
	ds_read_b128 v[188:191], v162 offset:32768
	ds_read_b128 v[192:195], v162 offset:34816
	ds_read_b128 v[196:199], v161 offset:36864
	ds_read_b128 v[200:203], v161 offset:38912
	ds_read_b128 v[204:207], v162 offset:36864
	ds_read_b128 v[208:211], v162 offset:38912
	global_load_lds_dwordx4 v136, s[22:23]
	s_mov_b32 m0, s49
	s_nop 0
	global_load_lds_dwordx4 v134, s[22:23]
	s_waitcnt vmcnt(8)
	s_waitcnt lgkmcnt(0)
	s_barrier
	s_setprio 1
	s_waitcnt lgkmcnt(0)
	v_mfma_f32_16x16x32_bf16 v[128:131], v[138:141], v[176:179], v[128:131]
	v_mfma_f32_16x16x32_bf16 v[124:127], v[146:149], v[176:179], v[124:127]
	v_mfma_f32_16x16x32_bf16 v[112:115], v[138:141], v[184:187], v[112:115]
	v_mfma_f32_16x16x32_bf16 v[108:111], v[146:149], v[184:187], v[108:111]
	v_mfma_f32_16x16x32_bf16 v[96:99], v[138:141], v[196:199], v[96:99]
	v_mfma_f32_16x16x32_bf16 v[92:95], v[146:149], v[196:199], v[92:95]
	v_mfma_f32_16x16x32_bf16 v[80:83], v[138:141], v[200:203], v[80:83]
	v_mfma_f32_16x16x32_bf16 v[76:79], v[146:149], v[200:203], v[76:79]
	v_mfma_f32_16x16x32_bf16 v[128:131], v[142:145], v[188:191], v[128:131]
	v_mfma_f32_16x16x32_bf16 v[124:127], v[150:153], v[188:191], v[124:127]
	v_mfma_f32_16x16x32_bf16 v[112:115], v[142:145], v[192:195], v[112:115]
	v_mfma_f32_16x16x32_bf16 v[108:111], v[150:153], v[192:195], v[108:111]
	v_mfma_f32_16x16x32_bf16 v[96:99], v[142:145], v[204:207], v[96:99]
	v_mfma_f32_16x16x32_bf16 v[92:95], v[150:153], v[204:207], v[92:95]
	v_mfma_f32_16x16x32_bf16 v[80:83], v[142:145], v[208:211], v[80:83]
	v_mfma_f32_16x16x32_bf16 v[76:79], v[150:153], v[208:211], v[76:79]
	s_setprio 0
	s_setprio 1
	v_mfma_f32_16x16x32_bf16 v[120:123], v[154:157], v[176:179], v[120:123]
	v_mfma_f32_16x16x32_bf16 v[116:119], v[168:171], v[176:179], v[116:119]
	v_mfma_f32_16x16x32_bf16 v[104:107], v[154:157], v[184:187], v[104:107]
	v_mfma_f32_16x16x32_bf16 v[100:103], v[168:171], v[184:187], v[100:103]
	v_mfma_f32_16x16x32_bf16 v[88:91], v[154:157], v[196:199], v[88:91]
	v_mfma_f32_16x16x32_bf16 v[84:87], v[168:171], v[196:199], v[84:87]
	v_mfma_f32_16x16x32_bf16 v[72:75], v[154:157], v[200:203], v[72:75]
	v_mfma_f32_16x16x32_bf16 v[68:71], v[168:171], v[200:203], v[68:71]
	v_mfma_f32_16x16x32_bf16 v[120:123], v[164:167], v[188:191], v[120:123]
	v_mfma_f32_16x16x32_bf16 v[116:119], v[172:175], v[188:191], v[116:119]
	v_mfma_f32_16x16x32_bf16 v[104:107], v[164:167], v[192:195], v[104:107]
	v_mfma_f32_16x16x32_bf16 v[100:103], v[172:175], v[192:195], v[100:103]
	v_mfma_f32_16x16x32_bf16 v[88:91], v[164:167], v[204:207], v[88:91]
	v_mfma_f32_16x16x32_bf16 v[84:87], v[172:175], v[204:207], v[84:87]
	v_mfma_f32_16x16x32_bf16 v[72:75], v[164:167], v[208:211], v[72:75]
	v_mfma_f32_16x16x32_bf16 v[68:71], v[172:175], v[208:211], v[68:71]
	s_setprio 0
	s_barrier
	s_add_i32 s22, s25, s28
	s_add_i32 m0, s22, 0xffffff80
	ds_read_b128 v[176:179], v161 offset:49152
	ds_read_b128 v[184:187], v161 offset:51200
	ds_read_b128 v[188:191], v162 offset:49152
	ds_read_b128 v[192:195], v162 offset:51200
	ds_read_b128 v[196:199], v161 offset:53248
	ds_read_b128 v[200:203], v161 offset:55296
	ds_read_b128 v[204:207], v162 offset:53248
	ds_read_b128 v[208:211], v162 offset:55296
	global_load_lds_dwordx4 v34, s[18:19] offset:128
	s_add_i32 m0, s22, 0x1f80
	s_mov_b64 s[98:99], s[18:19]
	s_add_u32 s18, s18, 0x160080
	s_addc_u32 s19, s19, 0
	s_add_i32 s22, s30, s28
	global_load_lds_dwordx4 v132, s[98:99] offset:128
	s_mov_b32 m0, s22
	s_nop 0
	global_load_lds_dwordx4 v34, s[18:19]
	s_add_i32 m0, s22, 0x2000
	s_nop 0
	global_load_lds_dwordx4 v132, s[18:19]
	s_add_i32 m0, s53, 0xffffff80
	s_nop 0
	global_load_lds_dwordx4 v136, s[100:101] offset:128
	s_add_i32 m0, s54, 0xffffff80
	s_nop 0
	global_load_lds_dwordx4 v134, s[100:101] offset:128
	s_waitcnt vmcnt(8)
	s_waitcnt lgkmcnt(0)
	s_barrier
	s_setprio 1
	s_waitcnt lgkmcnt(0)
	v_mfma_f32_16x16x32_bf16 v[64:67], v[138:141], v[176:179], v[64:67]
	v_mfma_f32_16x16x32_bf16 v[60:63], v[146:149], v[176:179], v[60:63]
	v_mfma_f32_16x16x32_bf16 v[48:51], v[138:141], v[184:187], v[48:51]
	v_mfma_f32_16x16x32_bf16 v[44:47], v[146:149], v[184:187], v[44:47]
	v_mfma_f32_16x16x32_bf16 v[30:33], v[138:141], v[196:199], v[30:33]
	v_mfma_f32_16x16x32_bf16 v[26:29], v[146:149], v[196:199], v[26:29]
	v_mfma_f32_16x16x32_bf16 v[14:17], v[138:141], v[200:203], v[14:17]
	v_mfma_f32_16x16x32_bf16 v[10:13], v[146:149], v[200:203], v[10:13]
	v_mfma_f32_16x16x32_bf16 v[64:67], v[142:145], v[188:191], v[64:67]
	v_mfma_f32_16x16x32_bf16 v[60:63], v[150:153], v[188:191], v[60:63]
	v_mfma_f32_16x16x32_bf16 v[48:51], v[142:145], v[192:195], v[48:51]
	v_mfma_f32_16x16x32_bf16 v[44:47], v[150:153], v[192:195], v[44:47]
	v_mfma_f32_16x16x32_bf16 v[30:33], v[142:145], v[204:207], v[30:33]
	v_mfma_f32_16x16x32_bf16 v[26:29], v[150:153], v[204:207], v[26:29]
	v_mfma_f32_16x16x32_bf16 v[14:17], v[142:145], v[208:211], v[14:17]
	v_mfma_f32_16x16x32_bf16 v[10:13], v[150:153], v[208:211], v[10:13]
	s_setprio 0
	s_setprio 1
	v_mfma_f32_16x16x32_bf16 v[56:59], v[154:157], v[176:179], v[56:59]
	v_mfma_f32_16x16x32_bf16 v[52:55], v[168:171], v[176:179], v[52:55]
	v_mfma_f32_16x16x32_bf16 v[40:43], v[154:157], v[184:187], v[40:43]
	v_mfma_f32_16x16x32_bf16 v[36:39], v[168:171], v[184:187], v[36:39]
	v_mfma_f32_16x16x32_bf16 v[22:25], v[154:157], v[196:199], v[22:25]
	v_mfma_f32_16x16x32_bf16 v[18:21], v[168:171], v[196:199], v[18:21]
	v_mfma_f32_16x16x32_bf16 v[6:9], v[154:157], v[200:203], v[6:9]
	v_mfma_f32_16x16x32_bf16 v[2:5], v[168:171], v[200:203], v[2:5]
	v_mfma_f32_16x16x32_bf16 v[56:59], v[164:167], v[188:191], v[56:59]
	v_mfma_f32_16x16x32_bf16 v[52:55], v[172:175], v[188:191], v[52:55]
	v_mfma_f32_16x16x32_bf16 v[40:43], v[164:167], v[192:195], v[40:43]
	v_mfma_f32_16x16x32_bf16 v[36:39], v[172:175], v[192:195], v[36:39]
	v_mfma_f32_16x16x32_bf16 v[22:25], v[164:167], v[204:207], v[22:25]
	v_mfma_f32_16x16x32_bf16 v[18:21], v[172:175], v[204:207], v[18:21]
	v_mfma_f32_16x16x32_bf16 v[6:9], v[164:167], v[208:211], v[6:9]
	v_mfma_f32_16x16x32_bf16 v[2:5], v[172:175], v[208:211], v[2:5]
	s_setprio 0
	s_barrier
	s_add_i32 s24, s24, 2
	s_add_u32 s8, s8, 0x100
	s_addc_u32 s9, s9, 0
	s_add_u32 s20, s20, 0x100
	s_addc_u32 s21, s21, 0
	s_cmpk_gt_u32 s24, 0x55
	s_cbranch_scc1 .Lpeel_done_P7
.LBB0_1195:
	s_add_u32 s18, s8, 0xffea0080
	s_addc_u32 s19, s9, -1
	s_add_i32 s25, 0, 0x10000
	s_cmpk_eq_i32 s24, 0x54
	s_cselect_b32 s23, s45, s19
	s_cselect_b32 s22, s44, s18
	s_cselect_b32 s19, s47, s21
	s_cselect_b32 s18, s46, s20
	s_add_i32 s34, 0, 0x14000
	ds_read_b128 v[138:141], v1
	ds_read_b128 v[142:145], v160
	ds_read_b128 v[146:149], v1 offset:2048
	ds_read_b128 v[150:153], v160 offset:2048
	ds_read_b128 v[154:157], v1 offset:16384
	ds_read_b128 v[164:167], v160 offset:16384
	ds_read_b128 v[168:171], v1 offset:18432
	ds_read_b128 v[172:175], v160 offset:18432
	s_add_i32 m0, s29, 0xc000
	ds_read_b128 v[176:179], v161
	ds_read_b128 v[184:187], v161 offset:2048
	ds_read_b128 v[188:191], v162
	ds_read_b128 v[192:195], v162 offset:2048
	ds_read_b128 v[196:199], v161 offset:4096
	ds_read_b128 v[200:203], v161 offset:6144
	ds_read_b128 v[204:207], v162 offset:4096
	ds_read_b128 v[208:211], v162 offset:6144
	global_load_lds_dwordx4 v136, s[8:9]
	s_add_i32 m0, s29, 0xe000
	s_nop 0
	global_load_lds_dwordx4 v134, s[8:9]
	s_waitcnt vmcnt(8)
	s_waitcnt lgkmcnt(0)
	s_barrier
	s_setprio 1
	s_waitcnt lgkmcnt(0)
	v_mfma_f32_16x16x32_bf16 v[128:131], v[138:141], v[176:179], v[128:131]
	v_mfma_f32_16x16x32_bf16 v[124:127], v[146:149], v[176:179], v[124:127]
	v_mfma_f32_16x16x32_bf16 v[112:115], v[138:141], v[184:187], v[112:115]
	v_mfma_f32_16x16x32_bf16 v[108:111], v[146:149], v[184:187], v[108:111]
	v_mfma_f32_16x16x32_bf16 v[96:99], v[138:141], v[196:199], v[96:99]
	v_mfma_f32_16x16x32_bf16 v[92:95], v[146:149], v[196:199], v[92:95]
	v_mfma_f32_16x16x32_bf16 v[80:83], v[138:141], v[200:203], v[80:83]
	v_mfma_f32_16x16x32_bf16 v[76:79], v[146:149], v[200:203], v[76:79]
	v_mfma_f32_16x16x32_bf16 v[128:131], v[142:145], v[188:191], v[128:131]
	v_mfma_f32_16x16x32_bf16 v[124:127], v[150:153], v[188:191], v[124:127]
	v_mfma_f32_16x16x32_bf16 v[112:115], v[142:145], v[192:195], v[112:115]
	v_mfma_f32_16x16x32_bf16 v[108:111], v[150:153], v[192:195], v[108:111]
	v_mfma_f32_16x16x32_bf16 v[96:99], v[142:145], v[204:207], v[96:99]
	v_mfma_f32_16x16x32_bf16 v[92:95], v[150:153], v[204:207], v[92:95]
	v_mfma_f32_16x16x32_bf16 v[80:83], v[142:145], v[208:211], v[80:83]
	v_mfma_f32_16x16x32_bf16 v[76:79], v[150:153], v[208:211], v[76:79]
	s_setprio 0
	s_setprio 1
	v_mfma_f32_16x16x32_bf16 v[120:123], v[154:157], v[176:179], v[120:123]
	v_mfma_f32_16x16x32_bf16 v[116:119], v[168:171], v[176:179], v[116:119]
	v_mfma_f32_16x16x32_bf16 v[104:107], v[154:157], v[184:187], v[104:107]
	v_mfma_f32_16x16x32_bf16 v[100:103], v[168:171], v[184:187], v[100:103]
	v_mfma_f32_16x16x32_bf16 v[88:91], v[154:157], v[196:199], v[88:91]
	v_mfma_f32_16x16x32_bf16 v[84:87], v[168:171], v[196:199], v[84:87]
	v_mfma_f32_16x16x32_bf16 v[72:75], v[154:157], v[200:203], v[72:75]
	v_mfma_f32_16x16x32_bf16 v[68:71], v[168:171], v[200:203], v[68:71]
	v_mfma_f32_16x16x32_bf16 v[120:123], v[164:167], v[188:191], v[120:123]
	v_mfma_f32_16x16x32_bf16 v[116:119], v[172:175], v[188:191], v[116:119]
	v_mfma_f32_16x16x32_bf16 v[104:107], v[164:167], v[192:195], v[104:107]
	v_mfma_f32_16x16x32_bf16 v[100:103], v[172:175], v[192:195], v[100:103]
	v_mfma_f32_16x16x32_bf16 v[88:91], v[164:167], v[204:207], v[88:91]
	v_mfma_f32_16x16x32_bf16 v[84:87], v[172:175], v[204:207], v[84:87]
	v_mfma_f32_16x16x32_bf16 v[72:75], v[164:167], v[208:211], v[72:75]
	v_mfma_f32_16x16x32_bf16 v[68:71], v[172:175], v[208:211], v[68:71]
	s_setprio 0
	s_barrier
	s_add_i32 s25, s25, s28
	s_mov_b32 m0, s25
	ds_read_b128 v[176:179], v161 offset:16384
	ds_read_b128 v[184:187], v161 offset:18432
	ds_read_b128 v[188:191], v162 offset:16384
	ds_read_b128 v[192:195], v162 offset:18432
	ds_read_b128 v[196:199], v161 offset:20480
	ds_read_b128 v[200:203], v161 offset:22528
	ds_read_b128 v[204:207], v162 offset:20480
	ds_read_b128 v[208:211], v162 offset:22528
	global_load_lds_dwordx4 v34, s[18:19]
	s_add_i32 m0, s25, 0x2000
	s_add_u32 s30, s18, 0x160000
	s_addc_u32 s31, s19, 0
	s_add_i32 s25, s34, s28
	global_load_lds_dwordx4 v132, s[18:19]
	s_mov_b32 m0, s25
	s_nop 0
	global_load_lds_dwordx4 v34, s[30:31]
	s_add_i32 m0, s25, 0x2000
	s_nop 0
	global_load_lds_dwordx4 v132, s[30:31]
	s_mov_b32 m0, s29
	s_nop 0
	global_load_lds_dwordx4 v136, s[22:23]
	s_mov_b32 m0, s33
	s_nop 0
	global_load_lds_dwordx4 v134, s[22:23]
	s_waitcnt vmcnt(8)
	s_waitcnt lgkmcnt(0)
	s_barrier
	s_setprio 1
	s_waitcnt lgkmcnt(0)
	v_mfma_f32_16x16x32_bf16 v[64:67], v[138:141], v[176:179], v[64:67]
	v_mfma_f32_16x16x32_bf16 v[60:63], v[146:149], v[176:179], v[60:63]
	v_mfma_f32_16x16x32_bf16 v[48:51], v[138:141], v[184:187], v[48:51]
	v_mfma_f32_16x16x32_bf16 v[44:47], v[146:149], v[184:187], v[44:47]
	v_mfma_f32_16x16x32_bf16 v[30:33], v[138:141], v[196:199], v[30:33]
	v_mfma_f32_16x16x32_bf16 v[26:29], v[146:149], v[196:199], v[26:29]
	v_mfma_f32_16x16x32_bf16 v[14:17], v[138:141], v[200:203], v[14:17]
	v_mfma_f32_16x16x32_bf16 v[10:13], v[146:149], v[200:203], v[10:13]
	v_mfma_f32_16x16x32_bf16 v[64:67], v[142:145], v[188:191], v[64:67]
	v_mfma_f32_16x16x32_bf16 v[60:63], v[150:153], v[188:191], v[60:63]
	v_mfma_f32_16x16x32_bf16 v[48:51], v[142:145], v[192:195], v[48:51]
	v_mfma_f32_16x16x32_bf16 v[44:47], v[150:153], v[192:195], v[44:47]
	v_mfma_f32_16x16x32_bf16 v[30:33], v[142:145], v[204:207], v[30:33]
	v_mfma_f32_16x16x32_bf16 v[26:29], v[150:153], v[204:207], v[26:29]
	v_mfma_f32_16x16x32_bf16 v[14:17], v[142:145], v[208:211], v[14:17]
	v_mfma_f32_16x16x32_bf16 v[10:13], v[150:153], v[208:211], v[10:13]
	s_setprio 0
	s_setprio 1
	v_mfma_f32_16x16x32_bf16 v[56:59], v[154:157], v[176:179], v[56:59]
	v_mfma_f32_16x16x32_bf16 v[52:55], v[168:171], v[176:179], v[52:55]
	v_mfma_f32_16x16x32_bf16 v[40:43], v[154:157], v[184:187], v[40:43]
	v_mfma_f32_16x16x32_bf16 v[36:39], v[168:171], v[184:187], v[36:39]
	v_mfma_f32_16x16x32_bf16 v[22:25], v[154:157], v[196:199], v[22:25]
	v_mfma_f32_16x16x32_bf16 v[18:21], v[168:171], v[196:199], v[18:21]
	v_mfma_f32_16x16x32_bf16 v[6:9], v[154:157], v[200:203], v[6:9]
	v_mfma_f32_16x16x32_bf16 v[2:5], v[168:171], v[200:203], v[2:5]
	v_mfma_f32_16x16x32_bf16 v[56:59], v[164:167], v[188:191], v[56:59]
	v_mfma_f32_16x16x32_bf16 v[52:55], v[172:175], v[188:191], v[52:55]
	v_mfma_f32_16x16x32_bf16 v[40:43], v[164:167], v[192:195], v[40:43]
	v_mfma_f32_16x16x32_bf16 v[36:39], v[172:175], v[192:195], v[36:39]
	v_mfma_f32_16x16x32_bf16 v[22:25], v[164:167], v[204:207], v[22:25]
	v_mfma_f32_16x16x32_bf16 v[18:21], v[172:175], v[204:207], v[18:21]
	v_mfma_f32_16x16x32_bf16 v[6:9], v[164:167], v[208:211], v[6:9]
	v_mfma_f32_16x16x32_bf16 v[2:5], v[172:175], v[208:211], v[2:5]
	s_setprio 0
	s_barrier
	s_add_i32 s25, 0, 0x18000
	s_add_i32 s30, 0, 0x1c000
	ds_read_b128 v[138:141], v1 offset:32768
	ds_read_b128 v[142:145], v160 offset:32768
	ds_read_b128 v[146:149], v1 offset:34816
	ds_read_b128 v[150:153], v160 offset:34816
	ds_read_b128 v[154:157], v1 offset:49152
	ds_read_b128 v[164:167], v160 offset:49152
	ds_read_b128 v[168:171], v1 offset:51200
	ds_read_b128 v[172:175], v160 offset:51200
	s_mov_b64 s[100:101], s[22:23]
	s_add_u32 s22, s22, 0x160000
	s_addc_u32 s23, s23, 0
	s_mov_b32 m0, s48
	ds_read_b128 v[176:179], v161 offset:32768
	ds_read_b128 v[184:187], v161 offset:34816
	ds_read_b128 v[188:191], v162 offset:32768
	ds_read_b128 v[192:195], v162 offset:34816
	ds_read_b128 v[196:199], v161 offset:36864
	ds_read_b128 v[200:203], v161 offset:38912
	ds_read_b128 v[204:207], v162 offset:36864
	ds_read_b128 v[208:211], v162 offset:38912
	global_load_lds_dwordx4 v136, s[22:23]
	s_mov_b32 m0, s49
	s_nop 0
	global_load_lds_dwordx4 v134, s[22:23]
	s_waitcnt vmcnt(8)
	s_waitcnt lgkmcnt(0)
	s_barrier
	s_setprio 1
	s_waitcnt lgkmcnt(0)
	v_mfma_f32_16x16x32_bf16 v[128:131], v[138:141], v[176:179], v[128:131]
	v_mfma_f32_16x16x32_bf16 v[124:127], v[146:149], v[176:179], v[124:127]
	v_mfma_f32_16x16x32_bf16 v[112:115], v[138:141], v[184:187], v[112:115]
	v_mfma_f32_16x16x32_bf16 v[108:111], v[146:149], v[184:187], v[108:111]
	v_mfma_f32_16x16x32_bf16 v[96:99], v[138:141], v[196:199], v[96:99]
	v_mfma_f32_16x16x32_bf16 v[92:95], v[146:149], v[196:199], v[92:95]
	v_mfma_f32_16x16x32_bf16 v[80:83], v[138:141], v[200:203], v[80:83]
	v_mfma_f32_16x16x32_bf16 v[76:79], v[146:149], v[200:203], v[76:79]
	v_mfma_f32_16x16x32_bf16 v[128:131], v[142:145], v[188:191], v[128:131]
	v_mfma_f32_16x16x32_bf16 v[124:127], v[150:153], v[188:191], v[124:127]
	v_mfma_f32_16x16x32_bf16 v[112:115], v[142:145], v[192:195], v[112:115]
	v_mfma_f32_16x16x32_bf16 v[108:111], v[150:153], v[192:195], v[108:111]
	v_mfma_f32_16x16x32_bf16 v[96:99], v[142:145], v[204:207], v[96:99]
	v_mfma_f32_16x16x32_bf16 v[92:95], v[150:153], v[204:207], v[92:95]
	v_mfma_f32_16x16x32_bf16 v[80:83], v[142:145], v[208:211], v[80:83]
	v_mfma_f32_16x16x32_bf16 v[76:79], v[150:153], v[208:211], v[76:79]
	s_setprio 0
	s_setprio 1
	v_mfma_f32_16x16x32_bf16 v[120:123], v[154:157], v[176:179], v[120:123]
	v_mfma_f32_16x16x32_bf16 v[116:119], v[168:171], v[176:179], v[116:119]
	v_mfma_f32_16x16x32_bf16 v[104:107], v[154:157], v[184:187], v[104:107]
	v_mfma_f32_16x16x32_bf16 v[100:103], v[168:171], v[184:187], v[100:103]
	v_mfma_f32_16x16x32_bf16 v[88:91], v[154:157], v[196:199], v[88:91]
	v_mfma_f32_16x16x32_bf16 v[84:87], v[168:171], v[196:199], v[84:87]
	v_mfma_f32_16x16x32_bf16 v[72:75], v[154:157], v[200:203], v[72:75]
	v_mfma_f32_16x16x32_bf16 v[68:71], v[168:171], v[200:203], v[68:71]
	v_mfma_f32_16x16x32_bf16 v[120:123], v[164:167], v[188:191], v[120:123]
	v_mfma_f32_16x16x32_bf16 v[116:119], v[172:175], v[188:191], v[116:119]
	v_mfma_f32_16x16x32_bf16 v[104:107], v[164:167], v[192:195], v[104:107]
	v_mfma_f32_16x16x32_bf16 v[100:103], v[172:175], v[192:195], v[100:103]
	v_mfma_f32_16x16x32_bf16 v[88:91], v[164:167], v[204:207], v[88:91]
	v_mfma_f32_16x16x32_bf16 v[84:87], v[172:175], v[204:207], v[84:87]
	v_mfma_f32_16x16x32_bf16 v[72:75], v[164:167], v[208:211], v[72:75]
	v_mfma_f32_16x16x32_bf16 v[68:71], v[172:175], v[208:211], v[68:71]
	s_setprio 0
	s_barrier
	s_add_i32 s22, s25, s28
	s_add_i32 m0, s22, 0xffffff80
	ds_read_b128 v[176:179], v161 offset:49152
	ds_read_b128 v[184:187], v161 offset:51200
	ds_read_b128 v[188:191], v162 offset:49152
	ds_read_b128 v[192:195], v162 offset:51200
	ds_read_b128 v[196:199], v161 offset:53248
	ds_read_b128 v[200:203], v161 offset:55296
	ds_read_b128 v[204:207], v162 offset:53248
	ds_read_b128 v[208:211], v162 offset:55296
	global_load_lds_dwordx4 v34, s[18:19] offset:128
	s_add_i32 m0, s22, 0x1f80
	s_mov_b64 s[98:99], s[18:19]
	s_add_u32 s18, s18, 0x160080
	s_addc_u32 s19, s19, 0
	s_add_i32 s22, s30, s28
	global_load_lds_dwordx4 v132, s[98:99] offset:128
	s_mov_b32 m0, s22
	s_nop 0
	global_load_lds_dwordx4 v34, s[18:19]
	s_add_i32 m0, s22, 0x2000
	s_nop 0
	global_load_lds_dwordx4 v132, s[18:19]
	s_add_i32 m0, s53, 0xffffff80
	s_nop 0
	global_load_lds_dwordx4 v136, s[100:101] offset:128
	s_add_i32 m0, s54, 0xffffff80
	s_nop 0
	global_load_lds_dwordx4 v134, s[100:101] offset:128
	s_waitcnt vmcnt(8)
	s_waitcnt lgkmcnt(0)
	s_barrier
	s_setprio 1
	s_waitcnt lgkmcnt(0)
	v_mfma_f32_16x16x32_bf16 v[64:67], v[138:141], v[176:179], v[64:67]
	v_mfma_f32_16x16x32_bf16 v[60:63], v[146:149], v[176:179], v[60:63]
	v_mfma_f32_16x16x32_bf16 v[48:51], v[138:141], v[184:187], v[48:51]
	v_mfma_f32_16x16x32_bf16 v[44:47], v[146:149], v[184:187], v[44:47]
	v_mfma_f32_16x16x32_bf16 v[30:33], v[138:141], v[196:199], v[30:33]
	v_mfma_f32_16x16x32_bf16 v[26:29], v[146:149], v[196:199], v[26:29]
	v_mfma_f32_16x16x32_bf16 v[14:17], v[138:141], v[200:203], v[14:17]
	v_mfma_f32_16x16x32_bf16 v[10:13], v[146:149], v[200:203], v[10:13]
	v_mfma_f32_16x16x32_bf16 v[64:67], v[142:145], v[188:191], v[64:67]
	v_mfma_f32_16x16x32_bf16 v[60:63], v[150:153], v[188:191], v[60:63]
	v_mfma_f32_16x16x32_bf16 v[48:51], v[142:145], v[192:195], v[48:51]
	v_mfma_f32_16x16x32_bf16 v[44:47], v[150:153], v[192:195], v[44:47]
	v_mfma_f32_16x16x32_bf16 v[30:33], v[142:145], v[204:207], v[30:33]
	v_mfma_f32_16x16x32_bf16 v[26:29], v[150:153], v[204:207], v[26:29]
	v_mfma_f32_16x16x32_bf16 v[14:17], v[142:145], v[208:211], v[14:17]
	v_mfma_f32_16x16x32_bf16 v[10:13], v[150:153], v[208:211], v[10:13]
	s_setprio 0
	s_setprio 1
	v_mfma_f32_16x16x32_bf16 v[56:59], v[154:157], v[176:179], v[56:59]
	v_mfma_f32_16x16x32_bf16 v[52:55], v[168:171], v[176:179], v[52:55]
	v_mfma_f32_16x16x32_bf16 v[40:43], v[154:157], v[184:187], v[40:43]
	v_mfma_f32_16x16x32_bf16 v[36:39], v[168:171], v[184:187], v[36:39]
	v_mfma_f32_16x16x32_bf16 v[22:25], v[154:157], v[196:199], v[22:25]
	v_mfma_f32_16x16x32_bf16 v[18:21], v[168:171], v[196:199], v[18:21]
	v_mfma_f32_16x16x32_bf16 v[6:9], v[154:157], v[200:203], v[6:9]
	v_mfma_f32_16x16x32_bf16 v[2:5], v[168:171], v[200:203], v[2:5]
	v_mfma_f32_16x16x32_bf16 v[56:59], v[164:167], v[188:191], v[56:59]
	v_mfma_f32_16x16x32_bf16 v[52:55], v[172:175], v[188:191], v[52:55]
	v_mfma_f32_16x16x32_bf16 v[40:43], v[164:167], v[192:195], v[40:43]
	v_mfma_f32_16x16x32_bf16 v[36:39], v[172:175], v[192:195], v[36:39]
	v_mfma_f32_16x16x32_bf16 v[22:25], v[164:167], v[204:207], v[22:25]
	v_mfma_f32_16x16x32_bf16 v[18:21], v[172:175], v[204:207], v[18:21]
	v_mfma_f32_16x16x32_bf16 v[6:9], v[164:167], v[208:211], v[6:9]
	v_mfma_f32_16x16x32_bf16 v[2:5], v[172:175], v[208:211], v[2:5]
	s_setprio 0
	s_barrier
	s_add_i32 s24, s24, 2
	s_add_u32 s8, s8, 0x100
	s_addc_u32 s9, s9, 0
	s_add_u32 s20, s20, 0x100
	s_addc_u32 s21, s21, 0
	s_cmpk_gt_u32 s24, 0x55
	s_cbranch_scc0 .LBB0_1195

	.amdhsa_kernel _Z8mega_fwd4Args
		.amdhsa_group_segment_fixed_size 0
		.amdhsa_private_segment_fixed_size 0
		.amdhsa_kernarg_size 464
		.amdhsa_user_sgpr_count 2
		.amdhsa_user_sgpr_dispatch_ptr 0
		.amdhsa_user_sgpr_queue_ptr 0
		.amdhsa_user_sgpr_kernarg_segment_ptr 1
		.amdhsa_user_sgpr_dispatch_id 0
		.amdhsa_user_sgpr_kernarg_preload_length 0
		.amdhsa_user_sgpr_kernarg_preload_offset 0
		.amdhsa_user_sgpr_private_segment_size 0
		.amdhsa_uses_dynamic_stack 0
		.amdhsa_enable_private_segment 0
		.amdhsa_system_sgpr_workgroup_id_x 1
		.amdhsa_system_sgpr_workgroup_id_y 0
		.amdhsa_system_sgpr_workgroup_id_z 0
		.amdhsa_system_sgpr_workgroup_info 0
		.amdhsa_system_vgpr_workitem_id 0
		.amdhsa_next_free_vgpr 256
		.amdhsa_next_free_sgpr 102
		.amdhsa_accum_offset 256
		.amdhsa_reserve_vcc 1
		.amdhsa_float_round_mode_32 0
		.amdhsa_float_round_mode_16_64 0
		.amdhsa_float_denorm_mode_32 3
		.amdhsa_float_denorm_mode_16_64 3
		.amdhsa_dx10_clamp 1
		.amdhsa_ieee_mode 1
		.amdhsa_fp16_overflow 0
		.amdhsa_tg_split 0
		.amdhsa_exception_fp_ieee_invalid_op 0
		.amdhsa_exception_fp_denorm_src 0
		.amdhsa_exception_fp_ieee_div_zero 0
		.amdhsa_exception_fp_ieee_overflow 0
		.amdhsa_exception_fp_ieee_underflow 0
		.amdhsa_exception_fp_ieee_inexact 0
		.amdhsa_exception_int_div_zero 0
	.end_amdhsa_kernel

amdhsa.kernels:
  - .agpr_count:     0
    .args:
      - .offset:         0
        .size:           208
        .value_kind:     by_value
      - .offset:         208
        .size:           4
        .value_kind:     hidden_block_count_x
      - .offset:         212
        .size:           4
        .value_kind:     hidden_block_count_y
      - .offset:         216
        .size:           4
        .value_kind:     hidden_block_count_z
      - .offset:         220
        .size:           2
        .value_kind:     hidden_group_size_x
      - .offset:         222
        .size:           2
        .value_kind:     hidden_group_size_y
      - .offset:         224
        .size:           2
        .value_kind:     hidden_group_size_z
      - .offset:         226
        .size:           2
        .value_kind:     hidden_remainder_x
      - .offset:         228
        .size:           2
        .value_kind:     hidden_remainder_y
      - .offset:         230
        .size:           2
        .value_kind:     hidden_remainder_z
      - .offset:         248
        .size:           8
        .value_kind:     hidden_global_offset_x
      - .offset:         256
        .size:           8
        .value_kind:     hidden_global_offset_y
      - .offset:         264
        .size:           8
        .value_kind:     hidden_global_offset_z
      - .offset:         272
        .size:           2
        .value_kind:     hidden_grid_dims
      - .offset:         328
        .size:           4
        .value_kind:     hidden_dynamic_lds_size
    .group_segment_fixed_size: 0
    .kernarg_segment_align: 8
    .kernarg_segment_size: 464
    .language:       OpenCL C
    .language_version:
      - 2
      - 0
    .max_flat_workgroup_size: 512
    .name:           _Z8mega_fwd4Args
    .private_segment_fixed_size: 0
    .sgpr_count:     108
    .sgpr_spill_count: 253
    .symbol:         _Z8mega_fwd4Args.kd
    .uniform_work_group_size: 1
    .uses_dynamic_stack: false
    .vgpr_count:     256
    .vgpr_spill_count: 0
    .wavefront_size: 64
